# comb6 variant: GEMM load segment starts with the LDS-DMA issue (no leading ds_reads), reads distributed after each DMA
# baseline (speedup 1.0000x reference)
; #define PG8_STAGE(bufoff, gbase, voff) do { _Pragma("unroll") for (int _i = 0; _i < 2; ++_i) \
;         __builtin_amdgcn_global_load_lds((const unsigned*)((const char*)(gbase) + (voff)[_i]), (LAS unsigned*)(lds + (bufoff) + ldsw + _i * 8192), 16, 0, 0); } while (0)
; #define PG8_LDA(dst, b, h) do { _Pragma("unroll") for (int m = 0; m < 4; ++m) _Pragma("unroll") for (int k = 0; k < 2; ++k) dst[m][k] = *(const LAS bf16x8*)(lds + PG8_SA(b, h) + aoff + m * 2048 + k * 1024); } while (0)
; #define PG8_LDB(dst, b, h) do { _Pragma("unroll") for (int n = 0; n < 2; ++n) _Pragma("unroll") for (int k = 0; k < 2; ++k) dst[n][k] = *(const LAS bf16x8*)(lds + PG8_SB(b, h) + boff + n * 2048 + k * 1024); } while (0)
; #define PG8_MMA(ai, bj, At, Bt) do { __builtin_amdgcn_s_setprio(1); _Pragma("unroll") for (int m = 0; m < 4; ++m) _Pragma("unroll") for (int n = 0; n < 2; ++n) _Pragma("unroll") for (int k = 0; k < 2; ++k) \
;         acc[ai][bj][m][n] = __builtin_amdgcn_mfma_f32_16x16x32_bf16(Bt[n][k], At[m][k], acc[ai][bj][m][n], 0, 0, 0); __builtin_amdgcn_s_setprio(0); } while (0)
; #define PG8_WAIT_V(n) asm volatile("s_waitcnt vmcnt(" #n ")" ::: "memory")
; #define PG8_WAIT_L(n) asm volatile("s_waitcnt lgkmcnt(" #n ")" ::: "memory")
; #define PG8_BAR __builtin_amdgcn_s_barrier()
; template <class Epi, class Sched, bool ALIGN_EPI, class Hook = NoHook>
; __device__ __forceinline__ void gemm_phase(LAS unsigned char* lds, const Gemm g, const Sched& S, const Epi& E, const Hook& H = Hook()) {
;     ...
;             const bool last = (t == nt - 2);
;             const char* a1 = cA + (size_t)(t + 1) * kstep;
;             const char* a2 = last ? nA : cA + (size_t)(t + 2) * kstep; const char* b2 = last ? nB : cB + (size_t)(t + 2) * kstep;
;             const char* a3 = a2 + kstep; const char* b3 = b2 + kstep;
;             if (last && has_next) S.a_ready(nxt);
;             PG8_LDB(B0, 0, 0); PG8_LDB(B1, 0, 1); PG8_SCHED; PG8_LDA(At, 0, 0); PG8_STAGE(PG8_SA(1, 1), a1 + hA, voffA);
;             PG8_WAIT_V(8); PG8_WAIT_L(0); PG8_BAR; PG8_MMA(0, 0, At, B0); PG8_MMA(0, 1, At, B1); PG8_BAR; PG8_SCHED;
;             PG8_LDA(At, 0, 1); PG8_STAGE(PG8_SB(0, 0), b2, voffB); PG8_STAGE(PG8_SB(0, 1), b2 + hB, voffB); PG8_STAGE(PG8_SA(0, 0), a2, voffA);
;             PG8_WAIT_V(8); PG8_WAIT_L(0); PG8_BAR; PG8_MMA(1, 0, At, B0); PG8_MMA(1, 1, At, B1); PG8_BAR; PG8_SCHED;
.LBB0_199:
	s_add_u32 s34, s4, 0x100
	s_addc_u32 s35, s5, 0
	s_cmp_eq_u32 s64, 60
	s_cselect_b32 s39, s7, s35
	s_cselect_b32 s38, s8, s34
	s_cselect_b32 s37, s23, s63
	s_cselect_b32 s36, s25, s31
	s_add_i32 m0, s40, 0xc000
	s_nop 0
	global_load_lds_dwordx4 v172, s[4:5]
	ds_read_b128 v[130:133], v217
	ds_read_b128 v[134:137], v217 offset:1024
	ds_read_b128 v[138:141], v217 offset:2048
	ds_read_b128 v[142:145], v217 offset:3072
	ds_read_b128 v[146:149], v218
	ds_read_b128 v[150:153], v218 offset:1024
	ds_read_b128 v[154:157], v218 offset:2048
	ds_read_b128 v[158:161], v218 offset:3072
	s_add_i32 m0, s40, 0xe000
	s_nop 0
	global_load_lds_dwordx4 v174, s[4:5]
	ds_read_b128 v[180:183], v219
	ds_read_b128 v[184:187], v219 offset:1024
	ds_read_b128 v[188:191], v219 offset:2048
	ds_read_b128 v[192:195], v219 offset:3072
	ds_read_b128 v[196:199], v219 offset:4096
	ds_read_b128 v[200:203], v219 offset:5120
	ds_read_b128 v[204:207], v219 offset:6144
	ds_read_b128 v[208:211], v219 offset:7168
	s_waitcnt vmcnt(8)
	s_waitcnt lgkmcnt(0)
	s_barrier
	s_setprio 1
	s_waitcnt lgkmcnt(0)
	v_mfma_f32_16x16x32_bf16 v[126:129], v[130:133], v[180:183], v[126:129]
	v_mfma_f32_16x16x32_bf16 v[94:97], v[138:141], v[180:183], v[94:97]
	v_mfma_f32_16x16x32_bf16 v[122:125], v[130:133], v[188:191], v[122:125]
	v_mfma_f32_16x16x32_bf16 v[90:93], v[138:141], v[188:191], v[90:93]
	v_mfma_f32_16x16x32_bf16 v[118:121], v[130:133], v[196:199], v[118:121]
	v_mfma_f32_16x16x32_bf16 v[86:89], v[138:141], v[196:199], v[86:89]
	v_mfma_f32_16x16x32_bf16 v[114:117], v[130:133], v[204:207], v[114:117]
	v_mfma_f32_16x16x32_bf16 v[82:85], v[138:141], v[204:207], v[82:85]
	v_mfma_f32_16x16x32_bf16 v[126:129], v[134:137], v[184:187], v[126:129]
	v_mfma_f32_16x16x32_bf16 v[94:97], v[142:145], v[184:187], v[94:97]
	v_mfma_f32_16x16x32_bf16 v[122:125], v[134:137], v[192:195], v[122:125]
	v_mfma_f32_16x16x32_bf16 v[90:93], v[142:145], v[192:195], v[90:93]
	v_mfma_f32_16x16x32_bf16 v[118:121], v[134:137], v[200:203], v[118:121]
	v_mfma_f32_16x16x32_bf16 v[86:89], v[142:145], v[200:203], v[86:89]
	v_mfma_f32_16x16x32_bf16 v[114:117], v[134:137], v[208:211], v[114:117]
	v_mfma_f32_16x16x32_bf16 v[82:85], v[142:145], v[208:211], v[82:85]
	s_setprio 0
	s_setprio 1
	v_mfma_f32_16x16x32_bf16 v[62:65], v[146:149], v[180:183], v[62:65]
	v_mfma_f32_16x16x32_bf16 v[30:33], v[154:157], v[180:183], v[30:33]
	v_mfma_f32_16x16x32_bf16 v[58:61], v[146:149], v[188:191], v[58:61]
	v_mfma_f32_16x16x32_bf16 v[26:29], v[154:157], v[188:191], v[26:29]
	v_mfma_f32_16x16x32_bf16 v[54:57], v[146:149], v[196:199], v[54:57]
	v_mfma_f32_16x16x32_bf16 v[22:25], v[154:157], v[196:199], v[22:25]
	v_mfma_f32_16x16x32_bf16 v[50:53], v[146:149], v[204:207], v[50:53]
	v_mfma_f32_16x16x32_bf16 v[18:21], v[154:157], v[204:207], v[18:21]
	v_mfma_f32_16x16x32_bf16 v[62:65], v[150:153], v[184:187], v[62:65]
	v_mfma_f32_16x16x32_bf16 v[30:33], v[158:161], v[184:187], v[30:33]
	v_mfma_f32_16x16x32_bf16 v[58:61], v[150:153], v[192:195], v[58:61]
	v_mfma_f32_16x16x32_bf16 v[26:29], v[158:161], v[192:195], v[26:29]
	v_mfma_f32_16x16x32_bf16 v[54:57], v[150:153], v[200:203], v[54:57]
	v_mfma_f32_16x16x32_bf16 v[22:25], v[158:161], v[200:203], v[22:25]
	v_mfma_f32_16x16x32_bf16 v[50:53], v[150:153], v[208:211], v[50:53]
	v_mfma_f32_16x16x32_bf16 v[18:21], v[158:161], v[208:211], v[18:21]
	s_setprio 0
	s_barrier
	s_add_i32 s4, s59, s21
	s_mov_b32 m0, s4
	s_nop 0
	global_load_lds_dwordx4 v164, s[36:37]
	ds_read_b128 v[180:183], v219 offset:16384
	ds_read_b128 v[184:187], v219 offset:17408
	s_add_i32 m0, s4, 0x2000
	s_add_u32 s4, s36, 0x100000
	s_addc_u32 s5, s37, 0
	s_add_i32 s65, s60, s21
	global_load_lds_dwordx4 v168, s[36:37]
	ds_read_b128 v[188:191], v219 offset:18432
	ds_read_b128 v[192:195], v219 offset:19456
	s_mov_b32 m0, s65
	s_nop 0
	global_load_lds_dwordx4 v164, s[4:5]
	ds_read_b128 v[196:199], v219 offset:20480
	s_add_i32 m0, s65, 0x2000
	s_nop 0
	global_load_lds_dwordx4 v168, s[4:5]
	ds_read_b128 v[200:203], v219 offset:21504
	s_mov_b32 m0, s40
	s_nop 0
	global_load_lds_dwordx4 v162, s[38:39]
	ds_read_b128 v[204:207], v219 offset:22528
	s_mov_b32 m0, s41
	s_nop 0
	global_load_lds_dwordx4 v166, s[38:39]
	ds_read_b128 v[208:211], v219 offset:23552
	s_waitcnt vmcnt(8)
	s_waitcnt lgkmcnt(0)
	s_barrier
	s_setprio 1
	s_waitcnt lgkmcnt(0)
	v_mfma_f32_16x16x32_bf16 v[110:113], v[130:133], v[180:183], v[110:113]
	v_mfma_f32_16x16x32_bf16 v[78:81], v[138:141], v[180:183], v[78:81]
	v_mfma_f32_16x16x32_bf16 v[106:109], v[130:133], v[188:191], v[106:109]
	v_mfma_f32_16x16x32_bf16 v[74:77], v[138:141], v[188:191], v[74:77]
	v_mfma_f32_16x16x32_bf16 v[102:105], v[130:133], v[196:199], v[102:105]
	v_mfma_f32_16x16x32_bf16 v[70:73], v[138:141], v[196:199], v[70:73]
	v_mfma_f32_16x16x32_bf16 v[98:101], v[130:133], v[204:207], v[98:101]
	v_mfma_f32_16x16x32_bf16 v[66:69], v[138:141], v[204:207], v[66:69]
	v_mfma_f32_16x16x32_bf16 v[110:113], v[134:137], v[184:187], v[110:113]
	v_mfma_f32_16x16x32_bf16 v[78:81], v[142:145], v[184:187], v[78:81]
	v_mfma_f32_16x16x32_bf16 v[106:109], v[134:137], v[192:195], v[106:109]
	v_mfma_f32_16x16x32_bf16 v[74:77], v[142:145], v[192:195], v[74:77]
	v_mfma_f32_16x16x32_bf16 v[102:105], v[134:137], v[200:203], v[102:105]
	v_mfma_f32_16x16x32_bf16 v[70:73], v[142:145], v[200:203], v[70:73]
	v_mfma_f32_16x16x32_bf16 v[98:101], v[134:137], v[208:211], v[98:101]
	v_mfma_f32_16x16x32_bf16 v[66:69], v[142:145], v[208:211], v[66:69]
	s_setprio 0
	s_setprio 1
	v_mfma_f32_16x16x32_bf16 v[46:49], v[146:149], v[180:183], v[46:49]
	v_mfma_f32_16x16x32_bf16 v[14:17], v[154:157], v[180:183], v[14:17]
	v_mfma_f32_16x16x32_bf16 v[42:45], v[146:149], v[188:191], v[42:45]
	v_mfma_f32_16x16x32_bf16 v[10:13], v[154:157], v[188:191], v[10:13]
	v_mfma_f32_16x16x32_bf16 v[38:41], v[146:149], v[196:199], v[38:41]
	v_mfma_f32_16x16x32_bf16 v[6:9], v[154:157], v[196:199], v[6:9]
	v_mfma_f32_16x16x32_bf16 v[34:37], v[146:149], v[204:207], v[34:37]
	v_mfma_f32_16x16x32_bf16 v[2:5], v[154:157], v[204:207], v[2:5]
	v_mfma_f32_16x16x32_bf16 v[46:49], v[150:153], v[184:187], v[46:49]
	v_mfma_f32_16x16x32_bf16 v[14:17], v[158:161], v[184:187], v[14:17]
	v_mfma_f32_16x16x32_bf16 v[42:45], v[150:153], v[192:195], v[42:45]
	v_mfma_f32_16x16x32_bf16 v[10:13], v[158:161], v[192:195], v[10:13]
	v_mfma_f32_16x16x32_bf16 v[38:41], v[150:153], v[200:203], v[38:41]
	v_mfma_f32_16x16x32_bf16 v[6:9], v[158:161], v[200:203], v[6:9]
	v_mfma_f32_16x16x32_bf16 v[34:37], v[150:153], v[208:211], v[34:37]
	v_mfma_f32_16x16x32_bf16 v[2:5], v[158:161], v[208:211], v[2:5]
	s_setprio 0
	s_barrier
; #define PG8_STAGE(bufoff, gbase, voff) do { _Pragma("unroll") for (int _i = 0; _i < 2; ++_i) \
;         __builtin_amdgcn_global_load_lds((const unsigned*)((const char*)(gbase) + (voff)[_i]), (LAS unsigned*)(lds + (bufoff) + ldsw + _i * 8192), 16, 0, 0); } while (0)
; #define PG8_LDA(dst, b, h) do { _Pragma("unroll") for (int m = 0; m < 4; ++m) _Pragma("unroll") for (int k = 0; k < 2; ++k) dst[m][k] = *(const LAS bf16x8*)(lds + PG8_SA(b, h) + aoff + m * 2048 + k * 1024); } while (0)
; #define PG8_LDB(dst, b, h) do { _Pragma("unroll") for (int n = 0; n < 2; ++n) _Pragma("unroll") for (int k = 0; k < 2; ++k) dst[n][k] = *(const LAS bf16x8*)(lds + PG8_SB(b, h) + boff + n * 2048 + k * 1024); } while (0)
; #define PG8_MMA(ai, bj, At, Bt) do { __builtin_amdgcn_s_setprio(1); _Pragma("unroll") for (int m = 0; m < 4; ++m) _Pragma("unroll") for (int n = 0; n < 2; ++n) _Pragma("unroll") for (int k = 0; k < 2; ++k) \
;         acc[ai][bj][m][n] = __builtin_amdgcn_mfma_f32_16x16x32_bf16(Bt[n][k], At[m][k], acc[ai][bj][m][n], 0, 0, 0); __builtin_amdgcn_s_setprio(0); } while (0)
; #define PG8_WAIT_V(n) asm volatile("s_waitcnt vmcnt(" #n ")" ::: "memory")
; #define PG8_WAIT_L(n) asm volatile("s_waitcnt lgkmcnt(" #n ")" ::: "memory")
; #define PG8_BAR __builtin_amdgcn_s_barrier()
;     __device__ __forceinline__ void operator()(const f32x4 (&acc)[2][2][4][2], const Unit& u, int wr, int wc, int fr, int fq) const {
;         if (u.pn >= TX0 && u.pn < TQ0) { conv_tile(acc, u, wr, wc, fr, fq); return; }
; template <class Epi, class Sched, bool ALIGN_EPI, class Hook = NoHook>
; __device__ __forceinline__ void gemm_phase(LAS unsigned char* lds, const Gemm g, const Sched& S, const Epi& E, const Hook& H = Hook()) {
;     ...
;             PG8_LDB(B0, 1, 0); PG8_LDB(B1, 1, 1); PG8_SCHED; PG8_LDA(At, 1, 0); PG8_STAGE(PG8_SA(0, 1), a2 + hA, voffA);
;             PG8_WAIT_V(8); PG8_WAIT_L(0); PG8_BAR; PG8_MMA(0, 0, At, B0); PG8_MMA(0, 1, At, B1); PG8_BAR; PG8_SCHED;
;             PG8_LDA(At, 1, 1); PG8_STAGE(PG8_SB(1, 0), b3, voffB); PG8_STAGE(PG8_SB(1, 1), b3 + hB, voffB); PG8_STAGE(PG8_SA(1, 0), a3, voffA);
;             PG8_WAIT_V(8); PG8_WAIT_L(0); PG8_BAR; PG8_MMA(1, 0, At, B0); PG8_MMA(1, 1, At, B1); PG8_BAR; PG8_SCHED;
;         }
;         if constexpr (Hook::ON) H.after(te, acc, cur, wr, wc, fr, fq);
;         }
;         if constexpr (ALIGN_EPI) { if (wr == 0) PG8_BAR; }
	s_add_i32 s65, 0, 0x18000
	s_add_i32 s66, 0, 0x1c000
	v_add_u32_e32 v142, s65, v213
	v_add_u32_e32 v158, s66, v213
	s_add_u32 s4, s38, 0x8000
	s_addc_u32 s5, s39, 0
	s_mov_b32 m0, s42
	s_nop 0
	global_load_lds_dwordx4 v162, s[4:5]
	ds_read_b128 v[130:133], v142
	ds_read_b128 v[134:137], v142 offset:1024
	ds_read_b128 v[138:141], v142 offset:2048
	ds_read_b128 v[142:145], v142 offset:3072
	ds_read_b128 v[146:149], v158
	ds_read_b128 v[150:153], v158 offset:1024
	ds_read_b128 v[154:157], v158 offset:2048
	ds_read_b128 v[158:161], v158 offset:3072
	s_mov_b32 m0, s43
	s_nop 0
	global_load_lds_dwordx4 v166, s[4:5]
	ds_read_b128 v[180:183], v219 offset:32768
	ds_read_b128 v[184:187], v219 offset:33792
	ds_read_b128 v[188:191], v219 offset:34816
	ds_read_b128 v[192:195], v219 offset:35840
	ds_read_b128 v[196:199], v219 offset:36864
	ds_read_b128 v[200:203], v219 offset:37888
	ds_read_b128 v[204:207], v219 offset:38912
	ds_read_b128 v[208:211], v219 offset:39936
	s_waitcnt vmcnt(8)
	s_waitcnt lgkmcnt(0)
	s_barrier
	s_setprio 1
	s_waitcnt lgkmcnt(0)
	v_mfma_f32_16x16x32_bf16 v[126:129], v[130:133], v[180:183], v[126:129]
	v_mfma_f32_16x16x32_bf16 v[94:97], v[138:141], v[180:183], v[94:97]
	v_mfma_f32_16x16x32_bf16 v[122:125], v[130:133], v[188:191], v[122:125]
	v_mfma_f32_16x16x32_bf16 v[90:93], v[138:141], v[188:191], v[90:93]
	v_mfma_f32_16x16x32_bf16 v[118:121], v[130:133], v[196:199], v[118:121]
	v_mfma_f32_16x16x32_bf16 v[86:89], v[138:141], v[196:199], v[86:89]
	v_mfma_f32_16x16x32_bf16 v[114:117], v[130:133], v[204:207], v[114:117]
	v_mfma_f32_16x16x32_bf16 v[82:85], v[138:141], v[204:207], v[82:85]
	v_mfma_f32_16x16x32_bf16 v[126:129], v[134:137], v[184:187], v[126:129]
	v_mfma_f32_16x16x32_bf16 v[94:97], v[142:145], v[184:187], v[94:97]
	v_mfma_f32_16x16x32_bf16 v[122:125], v[134:137], v[192:195], v[122:125]
	v_mfma_f32_16x16x32_bf16 v[90:93], v[142:145], v[192:195], v[90:93]
	v_mfma_f32_16x16x32_bf16 v[118:121], v[134:137], v[200:203], v[118:121]
	v_mfma_f32_16x16x32_bf16 v[86:89], v[142:145], v[200:203], v[86:89]
	v_mfma_f32_16x16x32_bf16 v[114:117], v[134:137], v[208:211], v[114:117]
	v_mfma_f32_16x16x32_bf16 v[82:85], v[142:145], v[208:211], v[82:85]
	s_setprio 0
	s_setprio 1
	v_mfma_f32_16x16x32_bf16 v[62:65], v[146:149], v[180:183], v[62:65]
	v_mfma_f32_16x16x32_bf16 v[30:33], v[154:157], v[180:183], v[30:33]
	v_mfma_f32_16x16x32_bf16 v[58:61], v[146:149], v[188:191], v[58:61]
	v_mfma_f32_16x16x32_bf16 v[26:29], v[154:157], v[188:191], v[26:29]
	v_mfma_f32_16x16x32_bf16 v[54:57], v[146:149], v[196:199], v[54:57]
	v_mfma_f32_16x16x32_bf16 v[22:25], v[154:157], v[196:199], v[22:25]
	v_mfma_f32_16x16x32_bf16 v[50:53], v[146:149], v[204:207], v[50:53]
	v_mfma_f32_16x16x32_bf16 v[18:21], v[154:157], v[204:207], v[18:21]
	v_mfma_f32_16x16x32_bf16 v[62:65], v[150:153], v[184:187], v[62:65]
	v_mfma_f32_16x16x32_bf16 v[30:33], v[158:161], v[184:187], v[30:33]
	v_mfma_f32_16x16x32_bf16 v[58:61], v[150:153], v[192:195], v[58:61]
	v_mfma_f32_16x16x32_bf16 v[26:29], v[158:161], v[192:195], v[26:29]
	v_mfma_f32_16x16x32_bf16 v[54:57], v[150:153], v[200:203], v[54:57]
	v_mfma_f32_16x16x32_bf16 v[22:25], v[158:161], v[200:203], v[22:25]
	v_mfma_f32_16x16x32_bf16 v[50:53], v[150:153], v[208:211], v[50:53]
	v_mfma_f32_16x16x32_bf16 v[18:21], v[158:161], v[208:211], v[18:21]
	s_setprio 0
	s_barrier
	s_add_i32 s4, s65, s21
	s_add_u32 s68, s36, s14
	s_addc_u32 s69, s37, s15
	s_mov_b32 m0, s4
	s_nop 0
	global_load_lds_dwordx4 v164, s[68:69]
	ds_read_b128 v[180:183], v219 offset:49152
	ds_read_b128 v[184:187], v219 offset:50176
	s_add_i32 m0, s4, 0x2000
	s_add_u32 s4, s36, 0x100080
	s_addc_u32 s5, s37, 0
	s_add_i32 s36, s66, s21
	global_load_lds_dwordx4 v168, s[68:69]
	ds_read_b128 v[188:191], v219 offset:51200
	ds_read_b128 v[192:195], v219 offset:52224
	s_mov_b32 m0, s36
	s_nop 0
	global_load_lds_dwordx4 v164, s[4:5]
	ds_read_b128 v[196:199], v219 offset:53248
	s_add_i32 m0, s36, 0x2000
	s_nop 0
	global_load_lds_dwordx4 v168, s[4:5]
	ds_read_b128 v[200:203], v219 offset:54272
	s_add_u32 s70, s38, s14
	s_addc_u32 s71, s39, s15
	s_mov_b32 m0, s51
	s_nop 0
	global_load_lds_dwordx4 v162, s[70:71]
	ds_read_b128 v[204:207], v219 offset:55296
	s_mov_b32 m0, s52
	s_nop 0
	global_load_lds_dwordx4 v166, s[70:71]
	ds_read_b128 v[208:211], v219 offset:56320
	s_waitcnt vmcnt(8)
	s_waitcnt lgkmcnt(0)
	s_barrier
	s_setprio 1
	s_waitcnt lgkmcnt(0)
	v_mfma_f32_16x16x32_bf16 v[110:113], v[130:133], v[180:183], v[110:113]
	v_mfma_f32_16x16x32_bf16 v[78:81], v[138:141], v[180:183], v[78:81]
	v_mfma_f32_16x16x32_bf16 v[106:109], v[130:133], v[188:191], v[106:109]
	v_mfma_f32_16x16x32_bf16 v[74:77], v[138:141], v[188:191], v[74:77]
	v_mfma_f32_16x16x32_bf16 v[102:105], v[130:133], v[196:199], v[102:105]
	v_mfma_f32_16x16x32_bf16 v[70:73], v[138:141], v[196:199], v[70:73]
	v_mfma_f32_16x16x32_bf16 v[98:101], v[130:133], v[204:207], v[98:101]
	v_mfma_f32_16x16x32_bf16 v[66:69], v[138:141], v[204:207], v[66:69]
	v_mfma_f32_16x16x32_bf16 v[110:113], v[134:137], v[184:187], v[110:113]
	v_mfma_f32_16x16x32_bf16 v[78:81], v[142:145], v[184:187], v[78:81]
	v_mfma_f32_16x16x32_bf16 v[106:109], v[134:137], v[192:195], v[106:109]
	v_mfma_f32_16x16x32_bf16 v[74:77], v[142:145], v[192:195], v[74:77]
	v_mfma_f32_16x16x32_bf16 v[102:105], v[134:137], v[200:203], v[102:105]
	v_mfma_f32_16x16x32_bf16 v[70:73], v[142:145], v[200:203], v[70:73]
	v_mfma_f32_16x16x32_bf16 v[98:101], v[134:137], v[208:211], v[98:101]
	v_mfma_f32_16x16x32_bf16 v[66:69], v[142:145], v[208:211], v[66:69]
	s_setprio 0
	s_setprio 1
	v_mfma_f32_16x16x32_bf16 v[46:49], v[146:149], v[180:183], v[46:49]
	v_mfma_f32_16x16x32_bf16 v[14:17], v[154:157], v[180:183], v[14:17]
	v_mfma_f32_16x16x32_bf16 v[42:45], v[146:149], v[188:191], v[42:45]
	v_mfma_f32_16x16x32_bf16 v[10:13], v[154:157], v[188:191], v[10:13]
	v_mfma_f32_16x16x32_bf16 v[38:41], v[146:149], v[196:199], v[38:41]
	v_mfma_f32_16x16x32_bf16 v[6:9], v[154:157], v[196:199], v[6:9]
	v_mfma_f32_16x16x32_bf16 v[34:37], v[146:149], v[204:207], v[34:37]
	v_mfma_f32_16x16x32_bf16 v[2:5], v[154:157], v[204:207], v[2:5]
	v_mfma_f32_16x16x32_bf16 v[46:49], v[150:153], v[184:187], v[46:49]
	v_mfma_f32_16x16x32_bf16 v[14:17], v[158:161], v[184:187], v[14:17]
	v_mfma_f32_16x16x32_bf16 v[42:45], v[150:153], v[192:195], v[42:45]
	v_mfma_f32_16x16x32_bf16 v[10:13], v[158:161], v[192:195], v[10:13]
	v_mfma_f32_16x16x32_bf16 v[38:41], v[150:153], v[200:203], v[38:41]
	v_mfma_f32_16x16x32_bf16 v[6:9], v[158:161], v[200:203], v[6:9]
	v_mfma_f32_16x16x32_bf16 v[34:37], v[150:153], v[208:211], v[34:37]
	v_mfma_f32_16x16x32_bf16 v[2:5], v[158:161], v[208:211], v[2:5]
	s_setprio 0
	s_barrier
	s_add_i32 s64, s64, 2
	s_add_u32 s31, s31, 0x100
	s_addc_u32 s63, s63, 0
	s_cmp_gt_u32 s64, 61
	s_mov_b64 s[4:5], s[34:35]
	s_cbranch_scc0 .LBB0_199
	s_and_b64 vcc, exec, s[18:19]
	s_cbranch_vccz .LBB0_203
	s_barrier
	s_sub_i32 s4, s6, 32
	s_cmp_gt_u32 s4, 39
	s_mov_b64 s[4:5], -1
	s_cbranch_scc1 .LBB0_204

; #define PG8_STAGE(bufoff, gbase, voff) do { _Pragma("unroll") for (int _i = 0; _i < 2; ++_i) \
;         __builtin_amdgcn_global_load_lds((const unsigned*)((const char*)(gbase) + (voff)[_i]), (LAS unsigned*)(lds + (bufoff) + ldsw + _i * 8192), 16, 0, 0); } while (0)
; #define PG8_LDA(dst, b, h) do { _Pragma("unroll") for (int m = 0; m < 4; ++m) _Pragma("unroll") for (int k = 0; k < 2; ++k) dst[m][k] = *(const LAS bf16x8*)(lds + PG8_SA(b, h) + aoff + m * 2048 + k * 1024); } while (0)
; #define PG8_LDB(dst, b, h) do { _Pragma("unroll") for (int n = 0; n < 2; ++n) _Pragma("unroll") for (int k = 0; k < 2; ++k) dst[n][k] = *(const LAS bf16x8*)(lds + PG8_SB(b, h) + boff + n * 2048 + k * 1024); } while (0)
; #define PG8_MMA(ai, bj, At, Bt) do { __builtin_amdgcn_s_setprio(1); _Pragma("unroll") for (int m = 0; m < 4; ++m) _Pragma("unroll") for (int n = 0; n < 2; ++n) _Pragma("unroll") for (int k = 0; k < 2; ++k) \
;         acc[ai][bj][m][n] = __builtin_amdgcn_mfma_f32_16x16x32_bf16(Bt[n][k], At[m][k], acc[ai][bj][m][n], 0, 0, 0); __builtin_amdgcn_s_setprio(0); } while (0)
; #define PG8_WAIT_V(n) asm volatile("s_waitcnt vmcnt(" #n ")" ::: "memory")
; #define PG8_WAIT_L(n) asm volatile("s_waitcnt lgkmcnt(" #n ")" ::: "memory")
; #define PG8_BAR __builtin_amdgcn_s_barrier()
; template <class Epi, class Sched, bool ALIGN_EPI, class Hook = NoHook>
; __device__ __forceinline__ void gemm_phase(LAS unsigned char* lds, const Gemm g, const Sched& S, const Epi& E, const Hook& H = Hook()) {
;     ...
;             const bool last = (t == nt - 2);
;             const char* a1 = cA + (size_t)(t + 1) * kstep;
;             const char* a2 = last ? nA : cA + (size_t)(t + 2) * kstep; const char* b2 = last ? nB : cB + (size_t)(t + 2) * kstep;
;             const char* a3 = a2 + kstep; const char* b3 = b2 + kstep;
;             if (last && has_next) S.a_ready(nxt);
;             PG8_LDB(B0, 0, 0); PG8_LDB(B1, 0, 1); PG8_SCHED; PG8_LDA(At, 0, 0); PG8_STAGE(PG8_SA(1, 1), a1 + hA, voffA);
;             PG8_WAIT_V(8); PG8_WAIT_L(0); PG8_BAR; PG8_MMA(0, 0, At, B0); PG8_MMA(0, 1, At, B1); PG8_BAR; PG8_SCHED;
;             PG8_LDA(At, 0, 1); PG8_STAGE(PG8_SB(0, 0), b2, voffB); PG8_STAGE(PG8_SB(0, 1), b2 + hB, voffB); PG8_STAGE(PG8_SA(0, 0), a2, voffA);
;             PG8_WAIT_V(8); PG8_WAIT_L(0); PG8_BAR; PG8_MMA(1, 0, At, B0); PG8_MMA(1, 1, At, B1); PG8_BAR; PG8_SCHED;
.LBB0_262:
	s_add_u32 s22, s20, 0xfff00080
	s_addc_u32 s23, s21, -1
	s_cmp_eq_u32 s50, 4
	s_cselect_b32 s25, s11, s23
	s_cselect_b32 s24, s13, s22
	s_cselect_b32 s23, s40, s43
	s_cselect_b32 s22, s41, s42
	s_add_i32 m0, s5, 0xc000
	s_nop 0
	global_load_lds_dwordx4 v136, s[20:21]
	ds_read_b128 v[148:151], v145
	ds_read_b128 v[152:155], v145 offset:1024
	ds_read_b128 v[156:159], v145 offset:2048
	ds_read_b128 v[160:163], v145 offset:3072
	ds_read_b128 v[164:167], v146
	ds_read_b128 v[168:171], v146 offset:1024
	ds_read_b128 v[172:175], v146 offset:2048
	ds_read_b128 v[176:179], v146 offset:3072
	s_add_i32 m0, s5, 0xe000
	s_nop 0
	global_load_lds_dwordx4 v138, s[20:21]
	ds_read_b128 v[180:183], v147
	ds_read_b128 v[184:187], v147 offset:1024
	ds_read_b128 v[188:191], v147 offset:2048
	ds_read_b128 v[192:195], v147 offset:3072
	ds_read_b128 v[196:199], v147 offset:4096
	ds_read_b128 v[200:203], v147 offset:5120
	ds_read_b128 v[204:207], v147 offset:6144
	ds_read_b128 v[208:211], v147 offset:7168
	s_waitcnt vmcnt(8)
	s_waitcnt lgkmcnt(0)
	s_barrier
	s_setprio 1
	s_waitcnt lgkmcnt(0)
	v_mfma_f32_16x16x32_bf16 v[126:129], v[148:151], v[180:183], v[126:129]
	v_mfma_f32_16x16x32_bf16 v[122:125], v[156:159], v[180:183], v[122:125]
	v_mfma_f32_16x16x32_bf16 v[118:121], v[148:151], v[188:191], v[118:121]
	v_mfma_f32_16x16x32_bf16 v[114:117], v[156:159], v[188:191], v[114:117]
	v_mfma_f32_16x16x32_bf16 v[106:109], v[148:151], v[196:199], v[106:109]
	v_mfma_f32_16x16x32_bf16 v[98:101], v[156:159], v[196:199], v[98:101]
	v_mfma_f32_16x16x32_bf16 v[90:93], v[148:151], v[204:207], v[90:93]
	v_mfma_f32_16x16x32_bf16 v[82:85], v[156:159], v[204:207], v[82:85]
	v_mfma_f32_16x16x32_bf16 v[126:129], v[152:155], v[184:187], v[126:129]
	v_mfma_f32_16x16x32_bf16 v[122:125], v[160:163], v[184:187], v[122:125]
	v_mfma_f32_16x16x32_bf16 v[118:121], v[152:155], v[192:195], v[118:121]
	v_mfma_f32_16x16x32_bf16 v[114:117], v[160:163], v[192:195], v[114:117]
	v_mfma_f32_16x16x32_bf16 v[106:109], v[152:155], v[200:203], v[106:109]
	v_mfma_f32_16x16x32_bf16 v[98:101], v[160:163], v[200:203], v[98:101]
	v_mfma_f32_16x16x32_bf16 v[90:93], v[152:155], v[208:211], v[90:93]
	v_mfma_f32_16x16x32_bf16 v[82:85], v[160:163], v[208:211], v[82:85]
	s_setprio 0
	s_setprio 1
	v_mfma_f32_16x16x32_bf16 v[110:113], v[164:167], v[180:183], v[110:113]
	v_mfma_f32_16x16x32_bf16 v[102:105], v[172:175], v[180:183], v[102:105]
	v_mfma_f32_16x16x32_bf16 v[94:97], v[164:167], v[188:191], v[94:97]
	v_mfma_f32_16x16x32_bf16 v[86:89], v[172:175], v[188:191], v[86:89]
	v_mfma_f32_16x16x32_bf16 v[78:81], v[164:167], v[196:199], v[78:81]
	v_mfma_f32_16x16x32_bf16 v[74:77], v[172:175], v[196:199], v[74:77]
	v_mfma_f32_16x16x32_bf16 v[70:73], v[164:167], v[204:207], v[70:73]
	v_mfma_f32_16x16x32_bf16 v[66:69], v[172:175], v[204:207], v[66:69]
	v_mfma_f32_16x16x32_bf16 v[110:113], v[168:171], v[184:187], v[110:113]
	v_mfma_f32_16x16x32_bf16 v[102:105], v[176:179], v[184:187], v[102:105]
	v_mfma_f32_16x16x32_bf16 v[94:97], v[168:171], v[192:195], v[94:97]
	v_mfma_f32_16x16x32_bf16 v[86:89], v[176:179], v[192:195], v[86:89]
	v_mfma_f32_16x16x32_bf16 v[78:81], v[168:171], v[200:203], v[78:81]
	v_mfma_f32_16x16x32_bf16 v[74:77], v[176:179], v[200:203], v[74:77]
	v_mfma_f32_16x16x32_bf16 v[70:73], v[168:171], v[208:211], v[70:73]
	v_mfma_f32_16x16x32_bf16 v[66:69], v[176:179], v[208:211], v[66:69]
	s_setprio 0
	s_barrier
	s_add_i32 s51, s38, s29
	s_mov_b32 m0, s51
	s_nop 0
	global_load_lds_dwordx4 v132, s[22:23]
	ds_read_b128 v[180:183], v147 offset:16384
	ds_read_b128 v[184:187], v147 offset:17408
	s_add_i32 m0, s51, 0x2000
	s_add_u32 s52, s22, 0x100000
	s_addc_u32 s53, s23, 0
	s_add_i32 s51, s39, s29
	global_load_lds_dwordx4 v130, s[22:23]
	ds_read_b128 v[188:191], v147 offset:18432
	ds_read_b128 v[192:195], v147 offset:19456
	s_mov_b32 m0, s51
	s_nop 0
	global_load_lds_dwordx4 v132, s[52:53]
	ds_read_b128 v[196:199], v147 offset:20480
	s_add_i32 m0, s51, 0x2000
	s_nop 0
	global_load_lds_dwordx4 v130, s[52:53]
	ds_read_b128 v[200:203], v147 offset:21504
	s_add_u32 s56, s24, s8
	s_addc_u32 s57, s25, s9
	s_mov_b32 m0, s5
	s_nop 0
	global_load_lds_dwordx4 v132, s[24:25]
	ds_read_b128 v[204:207], v147 offset:22528
	s_mov_b32 m0, s7
	s_nop 0
	global_load_lds_dwordx4 v130, s[24:25]
	ds_read_b128 v[208:211], v147 offset:23552
	s_waitcnt vmcnt(8)
	s_waitcnt lgkmcnt(0)
	s_barrier
	s_setprio 1
	s_waitcnt lgkmcnt(0)
	v_mfma_f32_16x16x32_bf16 v[62:65], v[148:151], v[180:183], v[62:65]
	v_mfma_f32_16x16x32_bf16 v[58:61], v[156:159], v[180:183], v[58:61]
	v_mfma_f32_16x16x32_bf16 v[54:57], v[148:151], v[188:191], v[54:57]
	v_mfma_f32_16x16x32_bf16 v[50:53], v[156:159], v[188:191], v[50:53]
	v_mfma_f32_16x16x32_bf16 v[38:41], v[148:151], v[196:199], v[38:41]
	v_mfma_f32_16x16x32_bf16 v[34:37], v[156:159], v[196:199], v[34:37]
	v_mfma_f32_16x16x32_bf16 v[22:25], v[148:151], v[204:207], v[22:25]
	v_mfma_f32_16x16x32_bf16 v[18:21], v[156:159], v[204:207], v[18:21]
	v_mfma_f32_16x16x32_bf16 v[62:65], v[152:155], v[184:187], v[62:65]
	v_mfma_f32_16x16x32_bf16 v[58:61], v[160:163], v[184:187], v[58:61]
	v_mfma_f32_16x16x32_bf16 v[54:57], v[152:155], v[192:195], v[54:57]
	v_mfma_f32_16x16x32_bf16 v[50:53], v[160:163], v[192:195], v[50:53]
	v_mfma_f32_16x16x32_bf16 v[38:41], v[152:155], v[200:203], v[38:41]
	v_mfma_f32_16x16x32_bf16 v[34:37], v[160:163], v[200:203], v[34:37]
	v_mfma_f32_16x16x32_bf16 v[22:25], v[152:155], v[208:211], v[22:25]
	v_mfma_f32_16x16x32_bf16 v[18:21], v[160:163], v[208:211], v[18:21]
	s_setprio 0
	s_setprio 1
	v_mfma_f32_16x16x32_bf16 v[46:49], v[164:167], v[180:183], v[46:49]
	v_mfma_f32_16x16x32_bf16 v[42:45], v[172:175], v[180:183], v[42:45]
	v_mfma_f32_16x16x32_bf16 v[30:33], v[164:167], v[188:191], v[30:33]
	v_mfma_f32_16x16x32_bf16 v[26:29], v[172:175], v[188:191], v[26:29]
	v_mfma_f32_16x16x32_bf16 v[14:17], v[164:167], v[196:199], v[14:17]
	v_mfma_f32_16x16x32_bf16 v[10:13], v[172:175], v[196:199], v[10:13]
	v_mfma_f32_16x16x32_bf16 v[6:9], v[164:167], v[204:207], v[6:9]
	v_mfma_f32_16x16x32_bf16 v[2:5], v[172:175], v[204:207], v[2:5]
	v_mfma_f32_16x16x32_bf16 v[46:49], v[168:171], v[184:187], v[46:49]
	v_mfma_f32_16x16x32_bf16 v[42:45], v[176:179], v[184:187], v[42:45]
	v_mfma_f32_16x16x32_bf16 v[30:33], v[168:171], v[192:195], v[30:33]
	v_mfma_f32_16x16x32_bf16 v[26:29], v[176:179], v[192:195], v[26:29]
	v_mfma_f32_16x16x32_bf16 v[14:17], v[168:171], v[200:203], v[14:17]
	v_mfma_f32_16x16x32_bf16 v[10:13], v[176:179], v[200:203], v[10:13]
	v_mfma_f32_16x16x32_bf16 v[6:9], v[168:171], v[208:211], v[6:9]
	v_mfma_f32_16x16x32_bf16 v[2:5], v[176:179], v[208:211], v[2:5]
	s_setprio 0
	s_barrier
; #define PG8_STAGE(bufoff, gbase, voff) do { _Pragma("unroll") for (int _i = 0; _i < 2; ++_i) \
;         __builtin_amdgcn_global_load_lds((const unsigned*)((const char*)(gbase) + (voff)[_i]), (LAS unsigned*)(lds + (bufoff) + ldsw + _i * 8192), 16, 0, 0); } while (0)
; #define PG8_LDA(dst, b, h) do { _Pragma("unroll") for (int m = 0; m < 4; ++m) _Pragma("unroll") for (int k = 0; k < 2; ++k) dst[m][k] = *(const LAS bf16x8*)(lds + PG8_SA(b, h) + aoff + m * 2048 + k * 1024); } while (0)
; #define PG8_LDB(dst, b, h) do { _Pragma("unroll") for (int n = 0; n < 2; ++n) _Pragma("unroll") for (int k = 0; k < 2; ++k) dst[n][k] = *(const LAS bf16x8*)(lds + PG8_SB(b, h) + boff + n * 2048 + k * 1024); } while (0)
; #define PG8_MMA(ai, bj, At, Bt) do { __builtin_amdgcn_s_setprio(1); _Pragma("unroll") for (int m = 0; m < 4; ++m) _Pragma("unroll") for (int n = 0; n < 2; ++n) _Pragma("unroll") for (int k = 0; k < 2; ++k) \
;         acc[ai][bj][m][n] = __builtin_amdgcn_mfma_f32_16x16x32_bf16(Bt[n][k], At[m][k], acc[ai][bj][m][n], 0, 0, 0); __builtin_amdgcn_s_setprio(0); } while (0)
; #define PG8_WAIT_V(n) asm volatile("s_waitcnt vmcnt(" #n ")" ::: "memory")
; #define PG8_WAIT_L(n) asm volatile("s_waitcnt lgkmcnt(" #n ")" ::: "memory")
; #define PG8_BAR __builtin_amdgcn_s_barrier()
; #define PG8_SCHED __builtin_amdgcn_sched_barrier(0)
; template <class Epi, class Sched, bool ALIGN_EPI, class Hook = NoHook>
; __device__ __forceinline__ void gemm_phase(LAS unsigned char* lds, const Gemm g, const Sched& S, const Epi& E, const Hook& H = Hook()) {
;     ...
;             PG8_LDB(B0, 1, 0); PG8_LDB(B1, 1, 1); PG8_SCHED; PG8_LDA(At, 1, 0); PG8_STAGE(PG8_SA(0, 1), a2 + hA, voffA);
;             PG8_WAIT_V(8); PG8_WAIT_L(0); PG8_BAR; PG8_MMA(0, 0, At, B0); PG8_MMA(0, 1, At, B1); PG8_BAR; PG8_SCHED;
;             PG8_LDA(At, 1, 1); PG8_STAGE(PG8_SB(1, 0), b3, voffB); PG8_STAGE(PG8_SB(1, 1), b3 + hB, voffB); PG8_STAGE(PG8_SA(1, 0), a3, voffA);
;             PG8_WAIT_V(8); PG8_WAIT_L(0); PG8_BAR; PG8_MMA(1, 0, At, B0); PG8_MMA(1, 1, At, B1); PG8_BAR; PG8_SCHED;
	s_add_i32 s51, 0, 0x18000
	s_add_i32 s52, 0, 0x1c000
	v_add_u32_e32 v160, s51, v144
	v_add_u32_e32 v176, s52, v144
	s_add_u32 s24, s24, 0x100000
	s_addc_u32 s25, s25, 0
	s_mov_b32 m0, s30
	s_nop 0
	global_load_lds_dwordx4 v132, s[24:25]
	ds_read_b128 v[148:151], v160
	ds_read_b128 v[152:155], v160 offset:1024
	ds_read_b128 v[156:159], v160 offset:2048
	ds_read_b128 v[160:163], v160 offset:3072
	ds_read_b128 v[164:167], v176
	ds_read_b128 v[168:171], v176 offset:1024
	ds_read_b128 v[172:175], v176 offset:2048
	ds_read_b128 v[176:179], v176 offset:3072
	s_mov_b32 m0, s31
	s_nop 0
	global_load_lds_dwordx4 v130, s[24:25]
	ds_read_b128 v[180:183], v147 offset:32768
	ds_read_b128 v[184:187], v147 offset:33792
	ds_read_b128 v[188:191], v147 offset:34816
	ds_read_b128 v[192:195], v147 offset:35840
	ds_read_b128 v[196:199], v147 offset:36864
	ds_read_b128 v[200:203], v147 offset:37888
	ds_read_b128 v[204:207], v147 offset:38912
	ds_read_b128 v[208:211], v147 offset:39936
	s_waitcnt vmcnt(8)
	s_waitcnt lgkmcnt(0)
	s_barrier
	s_setprio 1
	s_waitcnt lgkmcnt(0)
	v_mfma_f32_16x16x32_bf16 v[126:129], v[148:151], v[180:183], v[126:129]
	v_mfma_f32_16x16x32_bf16 v[122:125], v[156:159], v[180:183], v[122:125]
	v_mfma_f32_16x16x32_bf16 v[118:121], v[148:151], v[188:191], v[118:121]
	v_mfma_f32_16x16x32_bf16 v[114:117], v[156:159], v[188:191], v[114:117]
	v_mfma_f32_16x16x32_bf16 v[106:109], v[148:151], v[196:199], v[106:109]
	v_mfma_f32_16x16x32_bf16 v[98:101], v[156:159], v[196:199], v[98:101]
	v_mfma_f32_16x16x32_bf16 v[90:93], v[148:151], v[204:207], v[90:93]
	v_mfma_f32_16x16x32_bf16 v[82:85], v[156:159], v[204:207], v[82:85]
	v_mfma_f32_16x16x32_bf16 v[126:129], v[152:155], v[184:187], v[126:129]
	v_mfma_f32_16x16x32_bf16 v[122:125], v[160:163], v[184:187], v[122:125]
	v_mfma_f32_16x16x32_bf16 v[118:121], v[152:155], v[192:195], v[118:121]
	v_mfma_f32_16x16x32_bf16 v[114:117], v[160:163], v[192:195], v[114:117]
	v_mfma_f32_16x16x32_bf16 v[106:109], v[152:155], v[200:203], v[106:109]
	v_mfma_f32_16x16x32_bf16 v[98:101], v[160:163], v[200:203], v[98:101]
	v_mfma_f32_16x16x32_bf16 v[90:93], v[152:155], v[208:211], v[90:93]
	v_mfma_f32_16x16x32_bf16 v[82:85], v[160:163], v[208:211], v[82:85]
	s_setprio 0
	s_setprio 1
	v_mfma_f32_16x16x32_bf16 v[110:113], v[164:167], v[180:183], v[110:113]
	v_mfma_f32_16x16x32_bf16 v[102:105], v[172:175], v[180:183], v[102:105]
	v_mfma_f32_16x16x32_bf16 v[94:97], v[164:167], v[188:191], v[94:97]
	v_mfma_f32_16x16x32_bf16 v[86:89], v[172:175], v[188:191], v[86:89]
	v_mfma_f32_16x16x32_bf16 v[78:81], v[164:167], v[196:199], v[78:81]
	v_mfma_f32_16x16x32_bf16 v[74:77], v[172:175], v[196:199], v[74:77]
	v_mfma_f32_16x16x32_bf16 v[70:73], v[164:167], v[204:207], v[70:73]
	v_mfma_f32_16x16x32_bf16 v[66:69], v[172:175], v[204:207], v[66:69]
	v_mfma_f32_16x16x32_bf16 v[110:113], v[168:171], v[184:187], v[110:113]
	v_mfma_f32_16x16x32_bf16 v[102:105], v[176:179], v[184:187], v[102:105]
	v_mfma_f32_16x16x32_bf16 v[94:97], v[168:171], v[192:195], v[94:97]
	v_mfma_f32_16x16x32_bf16 v[86:89], v[176:179], v[192:195], v[86:89]
	v_mfma_f32_16x16x32_bf16 v[78:81], v[168:171], v[200:203], v[78:81]
	v_mfma_f32_16x16x32_bf16 v[74:77], v[176:179], v[200:203], v[74:77]
	v_mfma_f32_16x16x32_bf16 v[70:73], v[168:171], v[208:211], v[70:73]
	v_mfma_f32_16x16x32_bf16 v[66:69], v[176:179], v[208:211], v[66:69]
	s_setprio 0
	s_barrier
	s_add_i32 s24, s51, s29
	s_add_u32 s54, s22, s8
	s_addc_u32 s55, s23, s9
	s_mov_b32 m0, s24
	s_nop 0
	global_load_lds_dwordx4 v132, s[54:55]
	ds_read_b128 v[180:183], v147 offset:49152
	ds_read_b128 v[184:187], v147 offset:50176
	s_add_i32 m0, s24, 0x2000
	s_add_u32 s22, s22, 0x100080
	s_addc_u32 s23, s23, 0
	s_add_i32 s24, s52, s29
	global_load_lds_dwordx4 v130, s[54:55]
	ds_read_b128 v[188:191], v147 offset:51200
	ds_read_b128 v[192:195], v147 offset:52224
	s_mov_b32 m0, s24
	s_nop 0
	global_load_lds_dwordx4 v132, s[22:23]
	ds_read_b128 v[196:199], v147 offset:53248
	s_add_i32 m0, s24, 0x2000
	s_nop 0
	global_load_lds_dwordx4 v130, s[22:23]
	ds_read_b128 v[200:203], v147 offset:54272
	s_mov_b32 m0, s35
	s_nop 0
	global_load_lds_dwordx4 v132, s[56:57]
	ds_read_b128 v[204:207], v147 offset:55296
	s_mov_b32 m0, s36
	s_nop 0
	global_load_lds_dwordx4 v130, s[56:57]
	ds_read_b128 v[208:211], v147 offset:56320
	s_waitcnt vmcnt(8)
	s_waitcnt lgkmcnt(0)
	s_barrier
;     __device__ __forceinline__ void operator()(const f32x4 (&acc)[2][2][4][2], const Unit& u, int wr, int wc, int fr, int fq) const {
;         float* base = C + (size_t)(u.ka / kslab) * slab_stride;
;         const int row0 = u.pm * BM + wr * 64 + fr, col0 = wc * 32 + 4 * fq;
; #pragma unroll
;         for (int ai = 0; ai < 2; ++ai)
; #pragma unroll
;             for (int m = 0; m < 4; ++m) { float* rowp = base + (size_t)(row0 + ai * HALF + m * 16) * 256 + col0;
; #pragma unroll
;                 for (int bj = 0; bj < 2; ++bj)
; #pragma unroll
;                     for (int n = 0; n < 2; ++n) *(f32x4*)(rowp + bj * HALF + n * 16) = acc[ai][bj][m][n]; }
;     }
	s_setprio 1
	s_waitcnt lgkmcnt(0)
	v_mfma_f32_16x16x32_bf16 v[62:65], v[148:151], v[180:183], v[62:65]
	v_mfma_f32_16x16x32_bf16 v[58:61], v[156:159], v[180:183], v[58:61]
	v_mfma_f32_16x16x32_bf16 v[54:57], v[148:151], v[188:191], v[54:57]
	v_mfma_f32_16x16x32_bf16 v[50:53], v[156:159], v[188:191], v[50:53]
	v_mfma_f32_16x16x32_bf16 v[38:41], v[148:151], v[196:199], v[38:41]
	v_mfma_f32_16x16x32_bf16 v[34:37], v[156:159], v[196:199], v[34:37]
	v_mfma_f32_16x16x32_bf16 v[22:25], v[148:151], v[204:207], v[22:25]
	v_mfma_f32_16x16x32_bf16 v[18:21], v[156:159], v[204:207], v[18:21]
	v_mfma_f32_16x16x32_bf16 v[62:65], v[152:155], v[184:187], v[62:65]
	v_mfma_f32_16x16x32_bf16 v[58:61], v[160:163], v[184:187], v[58:61]
	v_mfma_f32_16x16x32_bf16 v[54:57], v[152:155], v[192:195], v[54:57]
	v_mfma_f32_16x16x32_bf16 v[50:53], v[160:163], v[192:195], v[50:53]
	v_mfma_f32_16x16x32_bf16 v[38:41], v[152:155], v[200:203], v[38:41]
	v_mfma_f32_16x16x32_bf16 v[34:37], v[160:163], v[200:203], v[34:37]
	v_mfma_f32_16x16x32_bf16 v[22:25], v[152:155], v[208:211], v[22:25]
	v_mfma_f32_16x16x32_bf16 v[18:21], v[160:163], v[208:211], v[18:21]
	s_setprio 0
	s_setprio 1
	v_mfma_f32_16x16x32_bf16 v[46:49], v[164:167], v[180:183], v[46:49]
	v_mfma_f32_16x16x32_bf16 v[42:45], v[172:175], v[180:183], v[42:45]
	v_mfma_f32_16x16x32_bf16 v[30:33], v[164:167], v[188:191], v[30:33]
	v_mfma_f32_16x16x32_bf16 v[26:29], v[172:175], v[188:191], v[26:29]
	v_mfma_f32_16x16x32_bf16 v[14:17], v[164:167], v[196:199], v[14:17]
	v_mfma_f32_16x16x32_bf16 v[10:13], v[172:175], v[196:199], v[10:13]
	v_mfma_f32_16x16x32_bf16 v[6:9], v[164:167], v[204:207], v[6:9]
	v_mfma_f32_16x16x32_bf16 v[2:5], v[172:175], v[204:207], v[2:5]
	v_mfma_f32_16x16x32_bf16 v[46:49], v[168:171], v[184:187], v[46:49]
	v_mfma_f32_16x16x32_bf16 v[42:45], v[176:179], v[184:187], v[42:45]
	v_mfma_f32_16x16x32_bf16 v[30:33], v[168:171], v[192:195], v[30:33]
	v_mfma_f32_16x16x32_bf16 v[26:29], v[176:179], v[192:195], v[26:29]
	v_mfma_f32_16x16x32_bf16 v[14:17], v[168:171], v[200:203], v[14:17]
	v_mfma_f32_16x16x32_bf16 v[10:13], v[176:179], v[200:203], v[10:13]
	v_mfma_f32_16x16x32_bf16 v[6:9], v[168:171], v[208:211], v[6:9]
	v_mfma_f32_16x16x32_bf16 v[2:5], v[176:179], v[208:211], v[2:5]
	s_setprio 0
	s_barrier
	s_add_i32 s50, s50, 2
	s_add_u32 s20, s20, 0x100
	s_addc_u32 s21, s21, 0
	s_add_u32 s42, s42, 0x100
	s_addc_u32 s43, s43, 0
	s_cmp_gt_u32 s50, 5
	s_cbranch_scc0 .LBB0_262
	s_ashr_i32 s11, s6, 31
	s_lshr_b32 s11, s11, 23
	s_add_i32 s6, s6, s11
	s_ashr_i32 s20, s6, 9
	s_ashr_i32 s21, s20, 31
	v_lshl_add_u32 v148, s4, 8, v1
	s_lshl_b64 s[20:21], s[20:21], 23
	v_ashrrev_i32_e32 v149, 31, v148
	v_lshl_add_u64 v[150:151], v[134:135], 0, s[20:21]
	v_lshlrev_b64 v[152:153], 10, v[148:149]
	v_lshl_add_u64 v[152:153], v[150:151], 0, v[152:153]
	global_store_dwordx4 v[152:153], v[126:129], off
	global_store_dwordx4 v[152:153], v[122:125], off offset:64
	global_store_dwordx4 v[152:153], v[110:113], off offset:512
	global_store_dwordx4 v[152:153], v[102:105], off offset:576
	s_mov_b32 s4, 0x20000
	s_mov_b64 s[20:21], 0x20000
	v_or_b32_e32 v102, 16, v148
	v_ashrrev_i32_e32 v103, 31, v102
	v_lshlrev_b64 v[102:103], 10, v[102:103]
	v_lshl_add_u64 v[102:103], v[150:151], 0, v[102:103]
	global_store_dwordx4 v[102:103], v[118:121], off
	global_store_dwordx4 v[102:103], v[114:117], off offset:64
	global_store_dwordx4 v[102:103], v[94:97], off offset:512
	global_store_dwordx4 v[102:103], v[86:89], off offset:576
	s_mov_b32 s6, s12
	s_mov_b64 s[22:23], s[18:19]
	v_or_b32_e32 v86, 32, v148
	v_ashrrev_i32_e32 v87, 31, v86
	v_lshlrev_b64 v[86:87], 10, v[86:87]
	v_lshl_add_u64 v[86:87], v[150:151], 0, v[86:87]
	global_store_dwordx4 v[86:87], v[106:109], off
	global_store_dwordx4 v[86:87], v[98:101], off offset:64
	global_store_dwordx4 v[86:87], v[78:81], off offset:512
	global_store_dwordx4 v[86:87], v[74:77], off offset:576
	s_nop 1
	v_or_b32_e32 v74, 48, v148
	v_ashrrev_i32_e32 v75, 31, v74
	v_lshlrev_b64 v[74:75], 10, v[74:75]
	v_lshl_add_u64 v[74:75], v[150:151], 0, v[74:75]
	global_store_dwordx4 v[74:75], v[90:93], off
	global_store_dwordx4 v[74:75], v[82:85], off offset:64
	global_store_dwordx4 v[74:75], v[70:73], off offset:512
	global_store_dwordx4 v[74:75], v[66:69], off offset:576
	s_nop 1
	v_add_co_u32_e32 v68, vcc, s4, v152
	s_mov_b32 s4, 0x24000
	s_nop 0
	v_addc_co_u32_e32 v69, vcc, 0, v153, vcc
	v_lshl_add_u64 v[66:67], v[152:153], 0, s[20:21]
	global_store_dwordx4 v[68:69], v[62:65], off
	global_store_dwordx4 v[66:67], v[58:61], off offset:64
	global_store_dwordx4 v[66:67], v[46:49], off offset:512
	global_store_dwordx4 v[66:67], v[42:45], off offset:576
	s_mov_b64 s[20:21], 0x24000
	s_nop 0
	v_add_co_u32_e32 v44, vcc, s4, v152
	s_mov_b32 s4, 0x28000
	s_nop 0
	v_addc_co_u32_e32 v45, vcc, 0, v153, vcc
	v_lshl_add_u64 v[42:43], v[152:153], 0, s[20:21]
	global_store_dwordx4 v[44:45], v[54:57], off
	global_store_dwordx4 v[42:43], v[50:53], off offset:64
	global_store_dwordx4 v[42:43], v[30:33], off offset:512
	global_store_dwordx4 v[42:43], v[26:29], off offset:576
	s_mov_b64 s[20:21], 0x28000
	s_nop 0
	v_add_co_u32_e32 v28, vcc, s4, v152
	v_lshl_add_u64 v[26:27], v[152:153], 0, s[20:21]
	s_nop 0
	v_addc_co_u32_e32 v29, vcc, 0, v153, vcc
	global_store_dwordx4 v[28:29], v[38:41], off
	global_store_dwordx4 v[26:27], v[34:37], off offset:64
	global_store_dwordx4 v[26:27], v[14:17], off offset:512
	global_store_dwordx4 v[26:27], v[10:13], off offset:576
	s_mov_b64 s[20:21], 0x2c000
	s_mov_b32 s4, s10
	v_add_co_u32_e32 v12, vcc, 0x2c000, v152
	v_lshl_add_u64 v[10:11], v[152:153], 0, s[20:21]
	s_nop 0
	v_addc_co_u32_e32 v13, vcc, 0, v153, vcc
	s_and_b64 vcc, exec, s[2:3]
	s_mov_b64 s[20:21], s[14:15]
	global_store_dwordx4 v[12:13], v[22:25], off
	global_store_dwordx4 v[10:11], v[18:21], off offset:64
	global_store_dwordx4 v[10:11], v[6:9], off offset:512
	global_store_dwordx4 v[10:11], v[2:5], off offset:576
	s_cbranch_vccz .LBB0_259
	s_waitcnt vmcnt(0)
	s_cmpk_gt_u32 s26, 0xff
	s_cbranch_scc1 .LBB0_266
	s_barrier

; #define PG8_STAGE(bufoff, gbase, voff) do { _Pragma("unroll") for (int _i = 0; _i < 2; ++_i) \
;         __builtin_amdgcn_global_load_lds((const unsigned*)((const char*)(gbase) + (voff)[_i]), (LAS unsigned*)(lds + (bufoff) + ldsw + _i * 8192), 16, 0, 0); } while (0)
; #define PG8_LDA(dst, b, h) do { _Pragma("unroll") for (int m = 0; m < 4; ++m) _Pragma("unroll") for (int k = 0; k < 2; ++k) dst[m][k] = *(const LAS bf16x8*)(lds + PG8_SA(b, h) + aoff + m * 2048 + k * 1024); } while (0)
; #define PG8_LDB(dst, b, h) do { _Pragma("unroll") for (int n = 0; n < 2; ++n) _Pragma("unroll") for (int k = 0; k < 2; ++k) dst[n][k] = *(const LAS bf16x8*)(lds + PG8_SB(b, h) + boff + n * 2048 + k * 1024); } while (0)
; #define PG8_MMA(ai, bj, At, Bt) do { __builtin_amdgcn_s_setprio(1); _Pragma("unroll") for (int m = 0; m < 4; ++m) _Pragma("unroll") for (int n = 0; n < 2; ++n) _Pragma("unroll") for (int k = 0; k < 2; ++k) \
;         acc[ai][bj][m][n] = __builtin_amdgcn_mfma_f32_16x16x32_bf16(Bt[n][k], At[m][k], acc[ai][bj][m][n], 0, 0, 0); __builtin_amdgcn_s_setprio(0); } while (0)
; #define PG8_WAIT_V(n) asm volatile("s_waitcnt vmcnt(" #n ")" ::: "memory")
; #define PG8_WAIT_L(n) asm volatile("s_waitcnt lgkmcnt(" #n ")" ::: "memory")
; #define PG8_BAR __builtin_amdgcn_s_barrier()
; template <class Epi, class Sched, bool ALIGN_EPI, class Hook = NoHook>
; __device__ __forceinline__ void gemm_phase(LAS unsigned char* lds, const Gemm g, const Sched& S, const Epi& E, const Hook& H = Hook()) {
;     ...
;             const bool last = (t == nt - 2);
;             const char* a1 = cA + (size_t)(t + 1) * kstep;
;             const char* a2 = last ? nA : cA + (size_t)(t + 2) * kstep; const char* b2 = last ? nB : cB + (size_t)(t + 2) * kstep;
;             const char* a3 = a2 + kstep; const char* b3 = b2 + kstep;
;             if (last && has_next) S.a_ready(nxt);
;             PG8_LDB(B0, 0, 0); PG8_LDB(B1, 0, 1); PG8_SCHED; PG8_LDA(At, 0, 0); PG8_STAGE(PG8_SA(1, 1), a1 + hA, voffA);
;             PG8_WAIT_V(8); PG8_WAIT_L(0); PG8_BAR; PG8_MMA(0, 0, At, B0); PG8_MMA(0, 1, At, B1); PG8_BAR; PG8_SCHED;
;             PG8_LDA(At, 0, 1); PG8_STAGE(PG8_SB(0, 0), b2, voffB); PG8_STAGE(PG8_SB(0, 1), b2 + hB, voffB); PG8_STAGE(PG8_SA(0, 0), a2, voffA);
;             PG8_WAIT_V(8); PG8_WAIT_L(0); PG8_BAR; PG8_MMA(1, 0, At, B0); PG8_MMA(1, 1, At, B1); PG8_BAR; PG8_SCHED;
.LBB0_783:
	v_add_u32_e32 v3, s56, v222
	s_add_i32 s67, s67, 2
	ds_read_b128 v[126:129], v3
	ds_read_b128 v[130:133], v3 offset:1024
	ds_read_b128 v[142:145], v3 offset:2048
	ds_read_b128 v[146:149], v3 offset:3072
	v_add_u32_e32 v3, s57, v222
	s_add_u32 s28, s22, s26
	s_addc_u32 s29, s23, s27
	s_add_u32 s28, s28, 0x100
	s_addc_u32 s29, s29, 0
	s_add_u32 s68, s63, s26
	s_addc_u32 s69, s64, s27
	s_cmpk_eq_i32 s26, 0x5f00
	s_cselect_b32 s31, s5, s29
	s_cselect_b32 s30, s4, s28
	s_cselect_b32 s29, s21, s69
	s_cselect_b32 s28, s20, s68
	ds_read_b128 v[150:153], v3
	ds_read_b128 v[154:157], v3 offset:1024
	ds_read_b128 v[158:161], v3 offset:2048
	ds_read_b128 v[162:165], v3 offset:3072
	v_lshl_add_u64 v[4:5], v[182:183], 0, s[26:27]
	s_add_i32 m0, s37, 0xc000
	s_nop 0
	global_load_lds_dwordx4 v[4:5], off
	ds_read_b128 v[186:189], v224
	ds_read_b128 v[190:193], v224 offset:1024
	ds_read_b128 v[194:197], v224 offset:2048
	ds_read_b128 v[198:201], v224 offset:3072
	ds_read_b128 v[202:205], v224 offset:4096
	ds_read_b128 v[206:209], v224 offset:5120
	ds_read_b128 v[210:213], v224 offset:6144
	ds_read_b128 v[214:217], v224 offset:7168
	v_lshl_add_u64 v[4:5], v[184:185], 0, s[26:27]
	s_add_i32 m0, s37, 0xe000
	s_nop 0
	global_load_lds_dwordx4 v[4:5], off
	s_waitcnt vmcnt(8)
	s_waitcnt lgkmcnt(0)
	s_barrier
	s_setprio 1
	s_waitcnt lgkmcnt(0)
	v_mfma_f32_16x16x32_bf16 v[138:141], v[126:129], v[186:189], v[138:141]
	v_mfma_f32_16x16x32_bf16 v[134:137], v[142:145], v[186:189], v[134:137]
	v_mfma_f32_16x16x32_bf16 v[122:125], v[126:129], v[194:197], v[122:125]
	v_mfma_f32_16x16x32_bf16 v[118:121], v[142:145], v[194:197], v[118:121]
	v_mfma_f32_16x16x32_bf16 v[114:117], v[126:129], v[202:205], v[114:117]
	v_mfma_f32_16x16x32_bf16 v[110:113], v[142:145], v[202:205], v[110:113]
	v_mfma_f32_16x16x32_bf16 v[106:109], v[126:129], v[210:213], v[106:109]
	v_mfma_f32_16x16x32_bf16 v[102:105], v[142:145], v[210:213], v[102:105]
	v_mfma_f32_16x16x32_bf16 v[138:141], v[130:133], v[190:193], v[138:141]
	v_mfma_f32_16x16x32_bf16 v[134:137], v[146:149], v[190:193], v[134:137]
	v_mfma_f32_16x16x32_bf16 v[122:125], v[130:133], v[198:201], v[122:125]
	v_mfma_f32_16x16x32_bf16 v[118:121], v[146:149], v[198:201], v[118:121]
	v_mfma_f32_16x16x32_bf16 v[114:117], v[130:133], v[206:209], v[114:117]
	v_mfma_f32_16x16x32_bf16 v[110:113], v[146:149], v[206:209], v[110:113]
	v_mfma_f32_16x16x32_bf16 v[106:109], v[130:133], v[214:217], v[106:109]
	v_mfma_f32_16x16x32_bf16 v[102:105], v[146:149], v[214:217], v[102:105]
	s_setprio 0
	s_setprio 1
	v_mfma_f32_16x16x32_bf16 v[66:69], v[150:153], v[186:189], v[66:69]
	v_mfma_f32_16x16x32_bf16 v[62:65], v[158:161], v[186:189], v[62:65]
	v_mfma_f32_16x16x32_bf16 v[58:61], v[150:153], v[194:197], v[58:61]
	v_mfma_f32_16x16x32_bf16 v[54:57], v[158:161], v[194:197], v[54:57]
	v_mfma_f32_16x16x32_bf16 v[50:53], v[150:153], v[202:205], v[50:53]
	v_mfma_f32_16x16x32_bf16 v[46:49], v[158:161], v[202:205], v[46:49]
	v_mfma_f32_16x16x32_bf16 v[42:45], v[150:153], v[210:213], v[42:45]
	v_mfma_f32_16x16x32_bf16 v[38:41], v[158:161], v[210:213], v[38:41]
	v_mfma_f32_16x16x32_bf16 v[66:69], v[154:157], v[190:193], v[66:69]
	v_mfma_f32_16x16x32_bf16 v[62:65], v[162:165], v[190:193], v[62:65]
	v_mfma_f32_16x16x32_bf16 v[58:61], v[154:157], v[198:201], v[58:61]
	v_mfma_f32_16x16x32_bf16 v[54:57], v[162:165], v[198:201], v[54:57]
	v_mfma_f32_16x16x32_bf16 v[50:53], v[154:157], v[206:209], v[50:53]
	v_mfma_f32_16x16x32_bf16 v[46:49], v[162:165], v[206:209], v[46:49]
	v_mfma_f32_16x16x32_bf16 v[42:45], v[154:157], v[214:217], v[42:45]
	v_mfma_f32_16x16x32_bf16 v[38:41], v[162:165], v[214:217], v[38:41]
	s_setprio 0
	s_barrier
	s_add_i32 s68, s56, s35
	s_mov_b32 m0, s68
	s_nop 0
	global_load_lds_dwordx4 v168, s[28:29]
	ds_read_b128 v[186:189], v224 offset:16384
	ds_read_b128 v[190:193], v224 offset:17408
	s_add_i32 m0, s68, 0x2000
	s_add_u32 s68, s28, 0x300000
	s_addc_u32 s69, s29, 0
	s_add_i32 s70, s57, s35
	global_load_lds_dwordx4 v172, s[28:29]
	ds_read_b128 v[194:197], v224 offset:18432
	ds_read_b128 v[198:201], v224 offset:19456
	s_mov_b32 m0, s70
	s_add_u32 s74, s30, s14
	s_addc_u32 s75, s31, s15
	global_load_lds_dwordx4 v168, s[68:69]
	ds_read_b128 v[202:205], v224 offset:20480
	s_add_i32 m0, s70, 0x2000
	s_nop 0
	global_load_lds_dwordx4 v172, s[68:69]
	ds_read_b128 v[206:209], v224 offset:21504
	s_mov_b32 m0, s37
	s_nop 0
	global_load_lds_dwordx4 v166, s[30:31]
	ds_read_b128 v[210:213], v224 offset:22528
	s_mov_b32 m0, s38
	s_nop 0
	global_load_lds_dwordx4 v170, s[30:31]
	ds_read_b128 v[214:217], v224 offset:23552
	s_waitcnt vmcnt(8)
	s_waitcnt lgkmcnt(0)
	s_barrier
; #define PG8_STAGE(bufoff, gbase, voff) do { _Pragma("unroll") for (int _i = 0; _i < 2; ++_i) \
;         __builtin_amdgcn_global_load_lds((const unsigned*)((const char*)(gbase) + (voff)[_i]), (LAS unsigned*)(lds + (bufoff) + ldsw + _i * 8192), 16, 0, 0); } while (0)
; #define PG8_LDA(dst, b, h) do { _Pragma("unroll") for (int m = 0; m < 4; ++m) _Pragma("unroll") for (int k = 0; k < 2; ++k) dst[m][k] = *(const LAS bf16x8*)(lds + PG8_SA(b, h) + aoff + m * 2048 + k * 1024); } while (0)
; #define PG8_LDB(dst, b, h) do { _Pragma("unroll") for (int n = 0; n < 2; ++n) _Pragma("unroll") for (int k = 0; k < 2; ++k) dst[n][k] = *(const LAS bf16x8*)(lds + PG8_SB(b, h) + boff + n * 2048 + k * 1024); } while (0)
; #define PG8_MMA(ai, bj, At, Bt) do { __builtin_amdgcn_s_setprio(1); _Pragma("unroll") for (int m = 0; m < 4; ++m) _Pragma("unroll") for (int n = 0; n < 2; ++n) _Pragma("unroll") for (int k = 0; k < 2; ++k) \
;         acc[ai][bj][m][n] = __builtin_amdgcn_mfma_f32_16x16x32_bf16(Bt[n][k], At[m][k], acc[ai][bj][m][n], 0, 0, 0); __builtin_amdgcn_s_setprio(0); } while (0)
; #define PG8_WAIT_V(n) asm volatile("s_waitcnt vmcnt(" #n ")" ::: "memory")
; #define PG8_WAIT_L(n) asm volatile("s_waitcnt lgkmcnt(" #n ")" ::: "memory")
; #define PG8_BAR __builtin_amdgcn_s_barrier()
; #define PG8_SCHED __builtin_amdgcn_sched_barrier(0)
; template <class Epi, class Sched, bool ALIGN_EPI, class Hook = NoHook>
; __device__ __forceinline__ void gemm_phase(LAS unsigned char* lds, const Gemm g, const Sched& S, const Epi& E, const Hook& H = Hook()) {
;     ...
;             PG8_WAIT_V(8); PG8_WAIT_L(0); PG8_BAR; PG8_MMA(1, 0, At, B0); PG8_MMA(1, 1, At, B1); PG8_BAR; PG8_SCHED;
;             PG8_LDB(B0, 1, 0); PG8_LDB(B1, 1, 1); PG8_SCHED; PG8_LDA(At, 1, 0); PG8_STAGE(PG8_SA(0, 1), a2 + hA, voffA);
;             PG8_WAIT_V(8); PG8_WAIT_L(0); PG8_BAR; PG8_MMA(0, 0, At, B0); PG8_MMA(0, 1, At, B1); PG8_BAR; PG8_SCHED;
	s_setprio 1
	s_waitcnt lgkmcnt(0)
	v_mfma_f32_16x16x32_bf16 v[98:101], v[126:129], v[186:189], v[98:101]
	v_mfma_f32_16x16x32_bf16 v[94:97], v[142:145], v[186:189], v[94:97]
	v_mfma_f32_16x16x32_bf16 v[90:93], v[126:129], v[194:197], v[90:93]
	v_mfma_f32_16x16x32_bf16 v[86:89], v[142:145], v[194:197], v[86:89]
	v_mfma_f32_16x16x32_bf16 v[82:85], v[126:129], v[202:205], v[82:85]
	v_mfma_f32_16x16x32_bf16 v[78:81], v[142:145], v[202:205], v[78:81]
	v_mfma_f32_16x16x32_bf16 v[74:77], v[126:129], v[210:213], v[74:77]
	v_mfma_f32_16x16x32_bf16 v[70:73], v[142:145], v[210:213], v[70:73]
	v_mfma_f32_16x16x32_bf16 v[98:101], v[130:133], v[190:193], v[98:101]
	v_mfma_f32_16x16x32_bf16 v[94:97], v[146:149], v[190:193], v[94:97]
	v_mfma_f32_16x16x32_bf16 v[90:93], v[130:133], v[198:201], v[90:93]
	v_mfma_f32_16x16x32_bf16 v[86:89], v[146:149], v[198:201], v[86:89]
	v_mfma_f32_16x16x32_bf16 v[82:85], v[130:133], v[206:209], v[82:85]
	v_mfma_f32_16x16x32_bf16 v[78:81], v[146:149], v[206:209], v[78:81]
	v_mfma_f32_16x16x32_bf16 v[74:77], v[130:133], v[214:217], v[74:77]
	v_mfma_f32_16x16x32_bf16 v[70:73], v[146:149], v[214:217], v[70:73]
	s_setprio 0
	s_setprio 1
	v_mfma_f32_16x16x32_bf16 v[34:37], v[150:153], v[186:189], v[34:37]
	v_mfma_f32_16x16x32_bf16 v[30:33], v[158:161], v[186:189], v[30:33]
	v_mfma_f32_16x16x32_bf16 v[26:29], v[150:153], v[194:197], v[26:29]
	v_mfma_f32_16x16x32_bf16 v[22:25], v[158:161], v[194:197], v[22:25]
	v_mfma_f32_16x16x32_bf16 v[18:21], v[150:153], v[202:205], v[18:21]
	v_mfma_f32_16x16x32_bf16 v[14:17], v[158:161], v[202:205], v[14:17]
	v_mfma_f32_16x16x32_bf16 v[10:13], v[150:153], v[210:213], v[10:13]
	v_mfma_f32_16x16x32_bf16 v[4:7], v[158:161], v[210:213], v[6:9]
	v_mfma_f32_16x16x32_bf16 v[34:37], v[154:157], v[190:193], v[34:37]
	v_mfma_f32_16x16x32_bf16 v[30:33], v[162:165], v[190:193], v[30:33]
	v_mfma_f32_16x16x32_bf16 v[26:29], v[154:157], v[198:201], v[26:29]
	v_mfma_f32_16x16x32_bf16 v[22:25], v[162:165], v[198:201], v[22:25]
	v_mfma_f32_16x16x32_bf16 v[18:21], v[154:157], v[206:209], v[18:21]
	v_mfma_f32_16x16x32_bf16 v[14:17], v[162:165], v[206:209], v[14:17]
	v_mfma_f32_16x16x32_bf16 v[10:13], v[154:157], v[214:217], v[10:13]
	v_mfma_f32_16x16x32_bf16 v[4:7], v[162:165], v[214:217], v[4:7]
	s_setprio 0
	s_barrier
	s_add_i32 s68, 0, 0x18000
	v_add_u32_e32 v3, s68, v222
	s_add_i32 s69, 0, 0x1c000
	ds_read_b128 v[126:129], v3
	ds_read_b128 v[130:133], v3 offset:1024
	ds_read_b128 v[142:145], v3 offset:2048
	ds_read_b128 v[146:149], v3 offset:3072
	v_add_u32_e32 v3, s69, v222
	s_add_u32 s30, s30, 0x300000
	s_addc_u32 s31, s31, 0
	s_mov_b32 m0, s39
	s_nop 0
	global_load_lds_dwordx4 v166, s[30:31]
	ds_read_b128 v[150:153], v3
	ds_read_b128 v[154:157], v3 offset:1024
	ds_read_b128 v[158:161], v3 offset:2048
	ds_read_b128 v[162:165], v3 offset:3072
	ds_read_b128 v[186:189], v224 offset:32768
	ds_read_b128 v[190:193], v224 offset:33792
	ds_read_b128 v[194:197], v224 offset:34816
	ds_read_b128 v[198:201], v224 offset:35840
	s_mov_b32 m0, s40
	s_nop 0
	global_load_lds_dwordx4 v170, s[30:31]
	ds_read_b128 v[202:205], v224 offset:36864
	ds_read_b128 v[206:209], v224 offset:37888
	ds_read_b128 v[210:213], v224 offset:38912
	ds_read_b128 v[214:217], v224 offset:39936
	s_waitcnt vmcnt(8)
	s_waitcnt lgkmcnt(0)
	s_barrier
	s_setprio 1
	s_waitcnt lgkmcnt(0)
	v_mfma_f32_16x16x32_bf16 v[138:141], v[126:129], v[186:189], v[138:141]
	v_mfma_f32_16x16x32_bf16 v[134:137], v[142:145], v[186:189], v[134:137]
	v_mfma_f32_16x16x32_bf16 v[122:125], v[126:129], v[194:197], v[122:125]
	v_mfma_f32_16x16x32_bf16 v[118:121], v[142:145], v[194:197], v[118:121]
	v_mfma_f32_16x16x32_bf16 v[114:117], v[126:129], v[202:205], v[114:117]
	v_mfma_f32_16x16x32_bf16 v[110:113], v[142:145], v[202:205], v[110:113]
	v_mfma_f32_16x16x32_bf16 v[106:109], v[126:129], v[210:213], v[106:109]
	v_mfma_f32_16x16x32_bf16 v[102:105], v[142:145], v[210:213], v[102:105]
	v_mfma_f32_16x16x32_bf16 v[138:141], v[130:133], v[190:193], v[138:141]
	v_mfma_f32_16x16x32_bf16 v[134:137], v[146:149], v[190:193], v[134:137]
	v_mfma_f32_16x16x32_bf16 v[122:125], v[130:133], v[198:201], v[122:125]
	v_mfma_f32_16x16x32_bf16 v[118:121], v[146:149], v[198:201], v[118:121]
	v_mfma_f32_16x16x32_bf16 v[114:117], v[130:133], v[206:209], v[114:117]
	v_mfma_f32_16x16x32_bf16 v[110:113], v[146:149], v[206:209], v[110:113]
	v_mfma_f32_16x16x32_bf16 v[106:109], v[130:133], v[214:217], v[106:109]
	v_mfma_f32_16x16x32_bf16 v[102:105], v[146:149], v[214:217], v[102:105]
	s_setprio 0
	s_setprio 1
	v_mfma_f32_16x16x32_bf16 v[66:69], v[150:153], v[186:189], v[66:69]
	v_mfma_f32_16x16x32_bf16 v[62:65], v[158:161], v[186:189], v[62:65]
	v_mfma_f32_16x16x32_bf16 v[58:61], v[150:153], v[194:197], v[58:61]
	v_mfma_f32_16x16x32_bf16 v[54:57], v[158:161], v[194:197], v[54:57]
	v_mfma_f32_16x16x32_bf16 v[50:53], v[150:153], v[202:205], v[50:53]
	v_mfma_f32_16x16x32_bf16 v[46:49], v[158:161], v[202:205], v[46:49]
	v_mfma_f32_16x16x32_bf16 v[42:45], v[150:153], v[210:213], v[42:45]
	v_mfma_f32_16x16x32_bf16 v[38:41], v[158:161], v[210:213], v[38:41]
	v_mfma_f32_16x16x32_bf16 v[66:69], v[154:157], v[190:193], v[66:69]
	v_mfma_f32_16x16x32_bf16 v[62:65], v[162:165], v[190:193], v[62:65]
	v_mfma_f32_16x16x32_bf16 v[58:61], v[154:157], v[198:201], v[58:61]
	v_mfma_f32_16x16x32_bf16 v[54:57], v[162:165], v[198:201], v[54:57]
	v_mfma_f32_16x16x32_bf16 v[50:53], v[154:157], v[206:209], v[50:53]
	v_mfma_f32_16x16x32_bf16 v[46:49], v[162:165], v[206:209], v[46:49]
	v_mfma_f32_16x16x32_bf16 v[42:45], v[154:157], v[214:217], v[42:45]
	v_mfma_f32_16x16x32_bf16 v[38:41], v[162:165], v[214:217], v[38:41]
	s_setprio 0
	s_barrier
; #define PG8_STAGE(bufoff, gbase, voff) do { _Pragma("unroll") for (int _i = 0; _i < 2; ++_i) \
;         __builtin_amdgcn_global_load_lds((const unsigned*)((const char*)(gbase) + (voff)[_i]), (LAS unsigned*)(lds + (bufoff) + ldsw + _i * 8192), 16, 0, 0); } while (0)
; #define PG8_LDA(dst, b, h) do { _Pragma("unroll") for (int m = 0; m < 4; ++m) _Pragma("unroll") for (int k = 0; k < 2; ++k) dst[m][k] = *(const LAS bf16x8*)(lds + PG8_SA(b, h) + aoff + m * 2048 + k * 1024); } while (0)
; #define PG8_MMA(ai, bj, At, Bt) do { __builtin_amdgcn_s_setprio(1); _Pragma("unroll") for (int m = 0; m < 4; ++m) _Pragma("unroll") for (int n = 0; n < 2; ++n) _Pragma("unroll") for (int k = 0; k < 2; ++k) \
;         acc[ai][bj][m][n] = __builtin_amdgcn_mfma_f32_16x16x32_bf16(Bt[n][k], At[m][k], acc[ai][bj][m][n], 0, 0, 0); __builtin_amdgcn_s_setprio(0); } while (0)
; #define PG8_WAIT_V(n) asm volatile("s_waitcnt vmcnt(" #n ")" ::: "memory")
; #define PG8_WAIT_L(n) asm volatile("s_waitcnt lgkmcnt(" #n ")" ::: "memory")
; #define PG8_BAR __builtin_amdgcn_s_barrier()
; #define PG8_SCHED __builtin_amdgcn_sched_barrier(0)
;     __device__ __forceinline__ void after(int te, f32x4 (&acc)[2][2][4][2], const Unit& u, int wr, int wc, int fr, int fq) const {
;         if (te > D_INNER / BK) return;
;         const int g = (te >> 4) - 1;
;         asm volatile("" : "+v"(fr), "+v"(fq));
; #pragma unroll
;         for (int ai = 0; ai < 2; ++ai)
; #pragma unroll
;             for (int m = 0; m < 4; ++m) { const float f = tab[(ai * HALF + wr * 64 + m * 16 + fr) * 8 + g];
; #pragma unroll
;                 for (int bj = 0; bj < 2; ++bj)
; #pragma unroll
;                     for (int n = 0; n < 2; ++n) acc[ai][bj][m][n] *= f; }
; template <class Epi, class Sched, bool ALIGN_EPI, class Hook = NoHook>
; __device__ __forceinline__ void gemm_phase(LAS unsigned char* lds, const Gemm g, const Sched& S, const Epi& E, const Hook& H = Hook()) {
;     ...
;             PG8_LDA(At, 1, 1); PG8_STAGE(PG8_SB(1, 0), b3, voffB); PG8_STAGE(PG8_SB(1, 1), b3 + hB, voffB); PG8_STAGE(PG8_SA(1, 0), a3, voffA);
;             PG8_WAIT_V(8); PG8_WAIT_L(0); PG8_BAR; PG8_MMA(1, 0, At, B0); PG8_MMA(1, 1, At, B1); PG8_BAR; PG8_SCHED;
	s_add_i32 s30, s68, s35
	s_add_u32 s72, s28, s14
	s_addc_u32 s73, s29, s15
	s_mov_b32 m0, s30
	s_nop 0
	global_load_lds_dwordx4 v168, s[72:73]
	ds_read_b128 v[186:189], v224 offset:49152
	ds_read_b128 v[190:193], v224 offset:50176
	s_add_i32 m0, s30, 0x2000
	s_add_u32 s28, s28, 0x300080
	s_addc_u32 s29, s29, 0
	s_add_i32 s30, s69, s35
	global_load_lds_dwordx4 v172, s[72:73]
	ds_read_b128 v[194:197], v224 offset:51200
	ds_read_b128 v[198:201], v224 offset:52224
	s_mov_b32 m0, s30
	s_nop 0
	global_load_lds_dwordx4 v168, s[28:29]
	ds_read_b128 v[202:205], v224 offset:53248
	s_add_i32 m0, s30, 0x2000
	s_nop 0
	global_load_lds_dwordx4 v172, s[28:29]
	ds_read_b128 v[206:209], v224 offset:54272
	s_mov_b32 m0, s45
	s_nop 0
	global_load_lds_dwordx4 v166, s[74:75]
	ds_read_b128 v[210:213], v224 offset:55296
	s_mov_b32 m0, s46
	s_nop 0
	global_load_lds_dwordx4 v170, s[74:75]
	ds_read_b128 v[214:217], v224 offset:56320
	s_waitcnt vmcnt(8)
	s_waitcnt lgkmcnt(0)
	s_barrier
	s_setprio 1
	s_waitcnt lgkmcnt(0)
	v_mfma_f32_16x16x32_bf16 v[98:101], v[126:129], v[186:189], v[98:101]
	v_mfma_f32_16x16x32_bf16 v[94:97], v[142:145], v[186:189], v[94:97]
	v_mfma_f32_16x16x32_bf16 v[90:93], v[126:129], v[194:197], v[90:93]
	v_mfma_f32_16x16x32_bf16 v[86:89], v[142:145], v[194:197], v[86:89]
	v_mfma_f32_16x16x32_bf16 v[82:85], v[126:129], v[202:205], v[82:85]
	v_mfma_f32_16x16x32_bf16 v[78:81], v[142:145], v[202:205], v[78:81]
	v_mfma_f32_16x16x32_bf16 v[74:77], v[126:129], v[210:213], v[74:77]
	v_mfma_f32_16x16x32_bf16 v[70:73], v[142:145], v[210:213], v[70:73]
	v_mfma_f32_16x16x32_bf16 v[98:101], v[130:133], v[190:193], v[98:101]
	v_mfma_f32_16x16x32_bf16 v[94:97], v[146:149], v[190:193], v[94:97]
	v_mfma_f32_16x16x32_bf16 v[90:93], v[130:133], v[198:201], v[90:93]
	v_mfma_f32_16x16x32_bf16 v[86:89], v[146:149], v[198:201], v[86:89]
	v_mfma_f32_16x16x32_bf16 v[82:85], v[130:133], v[206:209], v[82:85]
	v_mfma_f32_16x16x32_bf16 v[78:81], v[146:149], v[206:209], v[78:81]
	v_mfma_f32_16x16x32_bf16 v[74:77], v[130:133], v[214:217], v[74:77]
	v_mfma_f32_16x16x32_bf16 v[70:73], v[146:149], v[214:217], v[70:73]
	s_setprio 0
	s_setprio 1
	v_mfma_f32_16x16x32_bf16 v[34:37], v[150:153], v[186:189], v[34:37]
	v_mfma_f32_16x16x32_bf16 v[30:33], v[158:161], v[186:189], v[30:33]
	v_mfma_f32_16x16x32_bf16 v[26:29], v[150:153], v[194:197], v[26:29]
	v_mfma_f32_16x16x32_bf16 v[22:25], v[158:161], v[194:197], v[22:25]
	v_mfma_f32_16x16x32_bf16 v[18:21], v[150:153], v[202:205], v[18:21]
	v_mfma_f32_16x16x32_bf16 v[14:17], v[158:161], v[202:205], v[14:17]
	v_mfma_f32_16x16x32_bf16 v[8:11], v[150:153], v[210:213], v[10:13]
	v_mfma_f32_16x16x32_bf16 v[4:7], v[158:161], v[210:213], v[4:7]
	v_mfma_f32_16x16x32_bf16 v[34:37], v[154:157], v[190:193], v[34:37]
	v_mfma_f32_16x16x32_bf16 v[30:33], v[162:165], v[190:193], v[30:33]
	v_mfma_f32_16x16x32_bf16 v[26:29], v[154:157], v[198:201], v[26:29]
	v_mfma_f32_16x16x32_bf16 v[22:25], v[162:165], v[198:201], v[22:25]
	v_mfma_f32_16x16x32_bf16 v[18:21], v[154:157], v[206:209], v[18:21]
	v_mfma_f32_16x16x32_bf16 v[14:17], v[162:165], v[206:209], v[14:17]
	v_mfma_f32_16x16x32_bf16 v[10:13], v[154:157], v[214:217], v[8:11]
	v_mfma_f32_16x16x32_bf16 v[6:9], v[162:165], v[214:217], v[4:7]
	s_setprio 0
	s_barrier
	s_add_u32 s26, s26, 0x100
	s_addc_u32 s27, s27, 0
	s_cmp_ge_u32 s67, s66
	s_cbranch_scc0 .LBB0_783
	s_cmpk_gt_u32 s65, 0x7f
	s_cbranch_scc1 .LBB0_787
	s_lshr_b32 s26, s66, 4
	s_add_i32 s26, s26, -1
	v_mov_b32_e32 v3, v1
	v_mov_b32_e32 v4, v220
	s_lshl_b32 s27, s26, 2
	s_add_i32 s28, s27, s48
	v_lshlrev_b32_e32 v5, 5, v3
	v_add_u32_e32 v126, s28, v5
	ds_read_b32 v126, v126
	s_add_i32 s28, s27, s49
	s_waitcnt lgkmcnt(0)
	v_pk_mul_f32 v[140:141], v[140:141], v[126:127] op_sel_hi:[1,0]
	v_pk_mul_f32 v[138:139], v[138:139], v[126:127] op_sel_hi:[1,0]
	v_pk_mul_f32 v[136:137], v[136:137], v[126:127] op_sel_hi:[1,0]
	v_pk_mul_f32 v[134:135], v[134:135], v[126:127] op_sel_hi:[1,0]
	v_pk_mul_f32 v[68:69], v[68:69], v[126:127] op_sel_hi:[1,0]
	v_pk_mul_f32 v[66:67], v[66:67], v[126:127] op_sel_hi:[1,0]
	v_pk_mul_f32 v[64:65], v[64:65], v[126:127] op_sel_hi:[1,0]
	v_pk_mul_f32 v[62:63], v[62:63], v[126:127] op_sel_hi:[1,0]
	v_add_u32_e32 v126, s28, v5
	ds_read_b32 v126, v126
	s_add_i32 s28, s27, s50
	s_waitcnt lgkmcnt(0)
	v_pk_mul_f32 v[124:125], v[124:125], v[126:127] op_sel_hi:[1,0]
	v_pk_mul_f32 v[122:123], v[122:123], v[126:127] op_sel_hi:[1,0]
	v_pk_mul_f32 v[120:121], v[120:121], v[126:127] op_sel_hi:[1,0]
	v_pk_mul_f32 v[118:119], v[118:119], v[126:127] op_sel_hi:[1,0]
	v_pk_mul_f32 v[60:61], v[60:61], v[126:127] op_sel_hi:[1,0]
	v_pk_mul_f32 v[58:59], v[58:59], v[126:127] op_sel_hi:[1,0]
	v_pk_mul_f32 v[56:57], v[56:57], v[126:127] op_sel_hi:[1,0]
	v_pk_mul_f32 v[54:55], v[54:55], v[126:127] op_sel_hi:[1,0]
	v_add_u32_e32 v126, s28, v5
	ds_read_b32 v126, v126
	s_add_i32 s28, s27, s51
	s_waitcnt lgkmcnt(0)
	v_pk_mul_f32 v[116:117], v[116:117], v[126:127] op_sel_hi:[1,0]
	v_pk_mul_f32 v[114:115], v[114:115], v[126:127] op_sel_hi:[1,0]
	v_pk_mul_f32 v[112:113], v[112:113], v[126:127] op_sel_hi:[1,0]
	v_pk_mul_f32 v[110:111], v[110:111], v[126:127] op_sel_hi:[1,0]
	v_pk_mul_f32 v[52:53], v[52:53], v[126:127] op_sel_hi:[1,0]
	v_pk_mul_f32 v[50:51], v[50:51], v[126:127] op_sel_hi:[1,0]
	v_pk_mul_f32 v[48:49], v[48:49], v[126:127] op_sel_hi:[1,0]
	v_pk_mul_f32 v[46:47], v[46:47], v[126:127] op_sel_hi:[1,0]
	v_add_u32_e32 v126, s28, v5
	ds_read_b32 v126, v126
	s_add_i32 s28, s27, s52
	s_waitcnt lgkmcnt(0)
;     __device__ __forceinline__ void after(int te, f32x4 (&acc)[2][2][4][2], const Unit& u, int wr, int wc, int fr, int fq) const {
;     ...
; #pragma unroll
;         for (int ai = 0; ai < 2; ++ai)
; #pragma unroll
;             for (int m = 0; m < 4; ++m) { const float f = tab[(ai * HALF + wr * 64 + m * 16 + fr) * 8 + g];
; #pragma unroll
;                 for (int bj = 0; bj < 2; ++bj)
; #pragma unroll
;                     for (int n = 0; n < 2; ++n) acc[ai][bj][m][n] *= f; }
;         if (g == 7) {
;             const int row0 = u.pm * BM + wr * 64 + fr, col0 = u.pn * BM + wc * 32 + 8 * fq;
; #pragma unroll
;             for (int bj = 0; bj < 2; ++bj) { const int c = col0 + bj * HALF;
;                 const f32x4 s0 = *(const f32x4*)(gb + c), s1 = *(const f32x4*)(gb + c + 4), a0 = *(const f32x4*)(gb + D_MODEL + c), a1 = *(const f32x4*)(gb + D_MODEL + c + 4);
; #pragma unroll
;                 for (int ai = 0; ai < 2; ++ai) {
;                     u32x4 gs[4], ga[4];
; #pragma unroll
;                     for (int m = 0; m < 4; ++m) { const size_t r = (size_t)(row0 + ai * HALF + m * 16); gs[m] = *(const u32x4*)(proj + r * LDP + PGS + c); ga[m] = *(const u32x4*)(proj + r * LDP + PGA + c); }
	v_pk_mul_f32 v[108:109], v[108:109], v[126:127] op_sel_hi:[1,0]
	v_pk_mul_f32 v[106:107], v[106:107], v[126:127] op_sel_hi:[1,0]
	v_pk_mul_f32 v[104:105], v[104:105], v[126:127] op_sel_hi:[1,0]
	v_pk_mul_f32 v[102:103], v[102:103], v[126:127] op_sel_hi:[1,0]
	v_pk_mul_f32 v[44:45], v[44:45], v[126:127] op_sel_hi:[1,0]
	v_pk_mul_f32 v[42:43], v[42:43], v[126:127] op_sel_hi:[1,0]
	v_pk_mul_f32 v[40:41], v[40:41], v[126:127] op_sel_hi:[1,0]
	v_pk_mul_f32 v[38:39], v[38:39], v[126:127] op_sel_hi:[1,0]
	v_add_u32_e32 v126, s28, v5
	ds_read_b32 v126, v126
	s_add_i32 s28, s27, s53
	s_waitcnt lgkmcnt(0)
	v_pk_mul_f32 v[100:101], v[100:101], v[126:127] op_sel_hi:[1,0]
	v_pk_mul_f32 v[98:99], v[98:99], v[126:127] op_sel_hi:[1,0]
	v_pk_mul_f32 v[96:97], v[96:97], v[126:127] op_sel_hi:[1,0]
	v_pk_mul_f32 v[94:95], v[94:95], v[126:127] op_sel_hi:[1,0]
	v_pk_mul_f32 v[36:37], v[36:37], v[126:127] op_sel_hi:[1,0]
	v_pk_mul_f32 v[34:35], v[34:35], v[126:127] op_sel_hi:[1,0]
	v_pk_mul_f32 v[32:33], v[32:33], v[126:127] op_sel_hi:[1,0]
	v_pk_mul_f32 v[30:31], v[30:31], v[126:127] op_sel_hi:[1,0]
	v_add_u32_e32 v126, s28, v5
	ds_read_b32 v126, v126
	s_add_i32 s28, s27, s54
	s_add_i32 s27, s27, s55
	s_cmp_lg_u32 s26, 7
	s_waitcnt lgkmcnt(0)
	v_pk_mul_f32 v[92:93], v[92:93], v[126:127] op_sel_hi:[1,0]
	v_pk_mul_f32 v[90:91], v[90:91], v[126:127] op_sel_hi:[1,0]
	v_pk_mul_f32 v[88:89], v[88:89], v[126:127] op_sel_hi:[1,0]
	v_pk_mul_f32 v[86:87], v[86:87], v[126:127] op_sel_hi:[1,0]
	v_pk_mul_f32 v[28:29], v[28:29], v[126:127] op_sel_hi:[1,0]
	v_pk_mul_f32 v[26:27], v[26:27], v[126:127] op_sel_hi:[1,0]
	v_pk_mul_f32 v[24:25], v[24:25], v[126:127] op_sel_hi:[1,0]
	v_pk_mul_f32 v[22:23], v[22:23], v[126:127] op_sel_hi:[1,0]
	v_add_u32_e32 v126, s28, v5
	ds_read_b32 v126, v126
	v_add_u32_e32 v5, s27, v5
	s_waitcnt lgkmcnt(0)
	v_pk_mul_f32 v[84:85], v[84:85], v[126:127] op_sel_hi:[1,0]
	v_pk_mul_f32 v[82:83], v[82:83], v[126:127] op_sel_hi:[1,0]
	v_pk_mul_f32 v[80:81], v[80:81], v[126:127] op_sel_hi:[1,0]
	v_pk_mul_f32 v[78:79], v[78:79], v[126:127] op_sel_hi:[1,0]
	v_pk_mul_f32 v[20:21], v[20:21], v[126:127] op_sel_hi:[1,0]
	v_pk_mul_f32 v[18:19], v[18:19], v[126:127] op_sel_hi:[1,0]
	v_pk_mul_f32 v[16:17], v[16:17], v[126:127] op_sel_hi:[1,0]
	v_pk_mul_f32 v[14:15], v[14:15], v[126:127] op_sel_hi:[1,0]
	ds_read_b32 v126, v5
	s_waitcnt lgkmcnt(0)
	v_pk_mul_f32 v[76:77], v[76:77], v[126:127] op_sel_hi:[1,0]
	v_pk_mul_f32 v[74:75], v[74:75], v[126:127] op_sel_hi:[1,0]
	v_pk_mul_f32 v[72:73], v[72:73], v[126:127] op_sel_hi:[1,0]
	v_pk_mul_f32 v[70:71], v[70:71], v[126:127] op_sel_hi:[1,0]
	v_pk_mul_f32 v[12:13], v[12:13], v[126:127] op_sel_hi:[1,0]
	v_pk_mul_f32 v[10:11], v[10:11], v[126:127] op_sel_hi:[1,0]
	v_pk_mul_f32 v[8:9], v[8:9], v[126:127] op_sel_hi:[1,0]
	v_pk_mul_f32 v[6:7], v[6:7], v[126:127] op_sel_hi:[1,0]
	s_cbranch_scc1 .LBB0_787
	v_add_u32_e32 v126, s62, v3
	v_ashrrev_i32_e32 v127, 31, v126
	v_lshl_add_u32 v4, v4, 3, s61
	v_lshlrev_b64 v[126:127], 14, v[126:127]
	v_ashrrev_i32_e32 v5, 31, v4
	v_lshl_add_u64 v[126:127], s[76:77], 0, v[126:127]
	v_lshl_add_u64 v[192:193], v[4:5], 1, v[126:127]
	v_readlane_b32 s68, v254, 20
	global_load_dwordx4 v[204:207], v[192:193], off
	v_add_co_u32_e32 v126, vcc, s41, v192
	v_lshlrev_b64 v[4:5], 2, v[4:5]
	v_readlane_b32 s70, v254, 22
	v_readlane_b32 s71, v254, 23
	v_addc_co_u32_e32 v127, vcc, 0, v193, vcc
	s_nop 0
	v_lshl_add_u64 v[196:197], s[70:71], 0, v[4:5]
	global_load_dwordx4 v[208:211], v[126:127], off
	global_load_dwordx4 v[142:145], v[196:197], off
	s_nop 0
	global_load_dwordx4 v[126:129], v[196:197], off offset:16
	v_lshl_add_u64 v[198:199], s[12:13], 0, v[4:5]
	global_load_dwordx4 v[146:149], v[198:199], off
	global_load_dwordx4 v[130:133], v[198:199], off offset:16
	s_mov_b64 s[26:27], 0x40000
	v_lshl_add_u64 v[4:5], v[192:193], 0, s[26:27]
	s_mov_b32 s26, 0x40000
	v_add_co_u32_e32 v150, vcc, s26, v192
	s_mov_b64 s[26:27], 0x42000
	s_nop 0
	v_addc_co_u32_e32 v151, vcc, 0, v193, vcc
	v_lshl_add_u64 v[186:187], v[192:193], 0, s[26:27]
	s_mov_b32 s26, 0x42000
	v_add_co_u32_e32 v152, vcc, s26, v192
	s_mov_b64 s[26:27], 0x80000
	s_nop 0
	v_addc_co_u32_e32 v153, vcc, 0, v193, vcc
	v_lshl_add_u64 v[188:189], v[192:193], 0, s[26:27]
	s_mov_b32 s26, 0x80000
	v_add_co_u32_e32 v154, vcc, s26, v192
	s_mov_b64 s[26:27], 0x82000
	s_nop 0
	v_addc_co_u32_e32 v155, vcc, 0, v193, vcc
	v_lshl_add_u64 v[190:191], v[192:193], 0, s[26:27]
	s_mov_b32 s26, 0x82000
	v_add_co_u32_e32 v156, vcc, s26, v192
	s_mov_b64 s[26:27], 0xc0000
	s_nop 0
	v_addc_co_u32_e32 v157, vcc, 0, v193, vcc
	v_lshl_add_u64 v[194:195], v[192:193], 0, s[26:27]
	s_mov_b32 s26, 0xc0000
	v_add_co_u32_e32 v228, vcc, s26, v192
	s_mov_b64 s[26:27], 0xc2000
	s_nop 0
	v_addc_co_u32_e32 v229, vcc, 0, v193, vcc
	v_lshl_add_u64 v[200:201], v[192:193], 0, s[26:27]
	s_mov_b32 s26, 0xc2000
	v_add_co_u32_e32 v230, vcc, s26, v192
	s_mov_b32 s26, 0x200000
	s_nop 0
	v_addc_co_u32_e32 v231, vcc, 0, v193, vcc
	global_load_dwordx4 v[212:215], v[150:151], off
	global_load_dwordx4 v[216:219], v[152:153], off
	global_load_dwordx4 v[162:165], v[154:155], off
	global_load_dwordx4 v[158:161], v[156:157], off
	s_nop 0
	global_load_dwordx4 v[154:157], v[228:229], off
	global_load_dwordx4 v[150:153], v[230:231], off
	v_lshl_add_u64 v[202:203], v[192:193], 0, s[18:19]
	v_readlane_b32 s76, v254, 28
	v_readlane_b32 s77, v254, 29
	v_readlane_b32 s76, v255, 8
	v_readlane_b32 s77, v255, 9
	v_readlane_b32 s69, v254, 21
	v_readlane_b32 s72, v254, 24
	v_readlane_b32 s73, v254, 25
	v_readlane_b32 s74, v254, 26
	v_readlane_b32 s75, v254, 27
	v_readlane_b32 s78, v254, 30
	v_readlane_b32 s79, v254, 31
	v_readlane_b32 s80, v254, 32
	v_readlane_b32 s81, v254, 33
	v_readlane_b32 s82, v254, 34
	v_readlane_b32 s83, v254, 35
	s_waitcnt vmcnt(0)
; __device__ __forceinline__ void unpack8(const u32x4 w, float (&v)[8]) { v[0] = bf_lo(w.x); v[1] = bf_hi(w.x); v[2] = bf_lo(w.y); v[3] = bf_hi(w.y); v[4] = bf_lo(w.z); v[5] = bf_hi(w.z); v[6] = bf_lo(w.w); v[7] = bf_hi(w.w); }
;     __device__ __forceinline__ void after(int te, f32x4 (&acc)[2][2][4][2], const Unit& u, int wr, int wc, int fr, int fq) const {
;     ...
;             for (int bj = 0; bj < 2; ++bj) { const int c = col0 + bj * HALF;
;                 const f32x4 s0 = *(const f32x4*)(gb + c), s1 = *(const f32x4*)(gb + c + 4), a0 = *(const f32x4*)(gb + D_MODEL + c), a1 = *(const f32x4*)(gb + D_MODEL + c + 4);
; #pragma unroll
;                 for (int ai = 0; ai < 2; ++ai) {
;                     u32x4 gs[4], ga[4];
; #pragma unroll
;                     for (int m = 0; m < 4; ++m) { const size_t r = (size_t)(row0 + ai * HALF + m * 16); gs[m] = *(const u32x4*)(proj + r * LDP + PGS + c); ga[m] = *(const u32x4*)(proj + r * LDP + PGA + c); }
; #pragma unroll
;                     for (int m = 0; m < 4; ++m) { float vs[8], va[8]; unpack8(gs[m], vs); unpack8(ga[m], va);
; #pragma unroll
;                         for (int e = 0; e < 4; ++e) {
;                             acc[ai][bj][m][0][e] *= (1.f + __expf(-(va[e] + a0[e]))) * __builtin_amdgcn_rcpf(1.f + __expf(-(vs[e] + s0[e])));
;                             acc[ai][bj][m][1][e] *= (1.f + __expf(-(va[4 + e] + a1[e]))) * __builtin_amdgcn_rcpf(1.f + __expf(-(vs[4 + e] + s1[e]))); } }
	v_lshlrev_b32_e32 v3, 16, v204
	v_and_b32_e32 v204, 0xffff0000, v204
	v_lshlrev_b32_e32 v225, 16, v205
	v_and_b32_e32 v227, 0xffff0000, v205
	v_lshlrev_b32_e32 v205, 16, v206
	v_and_b32_e32 v228, 0xffff0000, v206
	v_lshlrev_b32_e32 v229, 16, v207
	v_and_b32_e32 v233, 0xffff0000, v207
	v_add_f32_e32 v3, v142, v3
	v_add_f32_e32 v204, v143, v204
	v_mul_f32_e32 v3, 0xbfb8aa3b, v3
	v_mul_f32_e32 v204, 0xbfb8aa3b, v204
	v_exp_f32_e32 v3, v3
	v_lshlrev_b32_e32 v230, 16, v209
	v_and_b32_e32 v231, 0xffff0000, v209
	v_exp_f32_e32 v209, v204
	v_lshlrev_b32_e32 v206, 16, v208
	v_and_b32_e32 v207, 0xffff0000, v208
	v_lshlrev_b32_e32 v208, 16, v210
	v_add_f32_e32 v206, v146, v206
	v_add_f32_e32 v208, v130, v208
	v_mul_f32_e32 v206, 0xbfb8aa3b, v206
	v_mul_f32_e32 v208, 0xbfb8aa3b, v208
	v_add_f32_e32 v3, 1.0, v3
	v_exp_f32_e32 v204, v206
	v_exp_f32_e32 v206, v208
	v_rcp_f32_e32 v208, v3
	v_add_f32_e32 v3, 1.0, v209
	v_rcp_f32_e32 v209, v3
	v_add_f32_e32 v3, v127, v228
	v_mul_f32_e32 v3, 0xbfb8aa3b, v3
	v_exp_f32_e32 v3, v3
	v_lshlrev_b32_e32 v234, 16, v211
	v_and_b32_e32 v235, 0xffff0000, v211
	v_add_f32_e32 v205, v126, v205
	v_add_f32_e32 v3, 1.0, v3
	v_rcp_f32_e32 v211, v3
	v_add_f32_e32 v3, v144, v225
	v_mul_f32_e32 v3, 0xbfb8aa3b, v3
	v_exp_f32_e32 v3, v3
	v_mul_f32_e32 v205, 0xbfb8aa3b, v205
	v_exp_f32_e32 v205, v205
	v_add_f32_e32 v225, v148, v230
	v_add_f32_e32 v3, 1.0, v3
	v_rcp_f32_e32 v230, v3
	v_add_f32_e32 v3, v128, v229
	v_mul_f32_e32 v3, 0xbfb8aa3b, v3
	v_add_f32_e32 v227, v145, v227
	v_mul_f32_e32 v225, 0xbfb8aa3b, v225
	v_exp_f32_e32 v3, v3
	v_mul_f32_e32 v227, 0xbfb8aa3b, v227
	v_add_f32_e32 v207, v147, v207
	v_exp_f32_e32 v228, v225
	v_add_f32_e32 v225, v132, v234
	v_exp_f32_e32 v227, v227
	v_and_b32_e32 v232, 0xffff0000, v210
	v_mul_f32_e32 v207, 0xbfb8aa3b, v207
	v_add_f32_e32 v205, 1.0, v205
	v_mul_f32_e32 v225, 0xbfb8aa3b, v225
	v_rcp_f32_e32 v210, v205
	v_exp_f32_e32 v205, v207
	v_add_f32_e32 v207, v131, v232
	v_exp_f32_e32 v232, v225
	v_add_f32_e32 v225, v149, v231
	v_add_f32_e32 v3, 1.0, v3
	v_mul_f32_e32 v225, 0xbfb8aa3b, v225
	v_exp_f32_e32 v229, v225
	v_rcp_f32_e32 v234, v3
	v_add_f32_e32 v3, 1.0, v227
	v_rcp_f32_e32 v231, v3
	v_pk_add_f32 v[228:229], v[228:229], 1.0 op_sel_hi:[1,0]
	v_pk_add_f32 v[204:205], v[204:205], 1.0 op_sel_hi:[1,0]
	v_add_f32_e32 v3, v133, v235
	v_pk_mul_f32 v[204:205], v[204:205], v[208:209]
	v_pk_mul_f32 v[208:209], v[228:229], v[230:231]
	v_mul_f32_e32 v3, 0xbfb8aa3b, v3
	v_pk_mul_f32 v[140:141], v[140:141], v[208:209]
	v_add_f32_e32 v208, v129, v233
	v_mul_f32_e32 v208, 0xbfb8aa3b, v208
	v_exp_f32_e32 v208, v208
	v_exp_f32_e32 v233, v3
	v_mul_f32_e32 v207, 0xbfb8aa3b, v207
	v_exp_f32_e32 v207, v207
	v_add_f32_e32 v3, 1.0, v208
	v_rcp_f32_e32 v235, v3
	v_lshlrev_b32_e32 v3, 16, v212
	v_add_f32_e32 v3, v142, v3
	v_mul_f32_e32 v3, 0xbfb8aa3b, v3
	v_exp_f32_e32 v3, v3
	v_pk_add_f32 v[206:207], v[206:207], 1.0 op_sel_hi:[1,0]
	v_pk_mul_f32 v[138:139], v[138:139], v[204:205]
	v_pk_mul_f32 v[206:207], v[206:207], v[210:211]
	v_add_f32_e32 v3, 1.0, v3
	v_pk_mul_f32 v[134:135], v[134:135], v[206:207]
	v_lshlrev_b32_e32 v207, 16, v214
	v_rcp_f32_e32 v206, v3
	v_add_f32_e32 v3, v126, v207
	v_mul_f32_e32 v3, 0xbfb8aa3b, v3
	v_exp_f32_e32 v3, v3
	v_pk_add_f32 v[204:205], v[232:233], 1.0 op_sel_hi:[1,0]
	v_lshlrev_b32_e32 v208, 16, v218
	v_pk_mul_f32 v[204:205], v[204:205], v[234:235]
	v_add_f32_e32 v3, 1.0, v3
	v_pk_mul_f32 v[136:137], v[136:137], v[204:205]
	v_and_b32_e32 v205, 0xffff0000, v212
	v_rcp_f32_e32 v210, v3
	v_add_f32_e32 v3, v143, v205
	v_mul_f32_e32 v3, 0xbfb8aa3b, v3
	v_exp_f32_e32 v3, v3
	v_add_f32_e32 v207, v130, v208
	v_and_b32_e32 v209, 0xffff0000, v214
	v_mul_f32_e32 v207, 0xbfb8aa3b, v207
	v_add_f32_e32 v3, 1.0, v3
	v_exp_f32_e32 v208, v207
	v_rcp_f32_e32 v207, v3
	v_add_f32_e32 v3, v127, v209
	v_mul_f32_e32 v3, 0xbfb8aa3b, v3
	v_exp_f32_e32 v3, v3
	v_lshlrev_b32_e32 v212, 16, v213
	v_and_b32_e32 v211, 0xffff0000, v216
	v_add_f32_e32 v205, v147, v211
	v_add_f32_e32 v3, 1.0, v3
	v_rcp_f32_e32 v211, v3
	v_add_f32_e32 v3, v144, v212
	v_mul_f32_e32 v3, 0xbfb8aa3b, v3
	v_exp_f32_e32 v3, v3
	v_lshlrev_b32_e32 v225, 16, v215
	v_lshlrev_b32_e32 v214, 16, v217
	v_and_b32_e32 v213, 0xffff0000, v213
	v_add_f32_e32 v3, 1.0, v3
	v_add_f32_e32 v212, v148, v214
	v_rcp_f32_e32 v214, v3
	v_add_f32_e32 v3, v128, v225
	v_mul_f32_e32 v3, 0xbfb8aa3b, v3
	v_add_f32_e32 v213, v145, v213
	v_and_b32_e32 v227, 0xffff0000, v215
	v_lshlrev_b32_e32 v204, 16, v216
	v_and_b32_e32 v215, 0xffff0000, v217
	v_and_b32_e32 v216, 0xffff0000, v218
	v_lshlrev_b32_e32 v217, 16, v219
	v_exp_f32_e32 v3, v3
	v_mul_f32_e32 v213, 0xbfb8aa3b, v213
	v_add_f32_e32 v209, v131, v216
	v_add_f32_e32 v216, v132, v217
	v_exp_f32_e32 v217, v213
	v_add_f32_e32 v204, v146, v204
	v_add_f32_e32 v215, v149, v215
	v_mul_f32_e32 v204, 0xbfb8aa3b, v204
	v_mul_f32_e32 v205, 0xbfb8aa3b, v205
	v_mul_f32_e32 v212, 0xbfb8aa3b, v212
	v_add_f32_e32 v3, 1.0, v3
	v_mul_f32_e32 v213, 0xbfb8aa3b, v215
	v_exp_f32_e32 v204, v204
	v_exp_f32_e32 v205, v205
	v_exp_f32_e32 v212, v212
	v_exp_f32_e32 v213, v213
	v_rcp_f32_e32 v218, v3
	v_add_f32_e32 v3, 1.0, v217
	v_rcp_f32_e32 v215, v3
	v_pk_add_f32 v[212:213], v[212:213], 1.0 op_sel_hi:[1,0]
	v_pk_add_f32 v[204:205], v[204:205], 1.0 op_sel_hi:[1,0]
	v_and_b32_e32 v219, 0xffff0000, v219
	v_pk_mul_f32 v[204:205], v[204:205], v[206:207]
	v_pk_mul_f32 v[206:207], v[212:213], v[214:215]
	v_add_f32_e32 v3, v133, v219
	v_pk_mul_f32 v[124:125], v[124:125], v[206:207]
	v_add_f32_e32 v206, v129, v227
	v_mul_f32_e32 v206, 0xbfb8aa3b, v206
	v_exp_f32_e32 v206, v206
	v_mul_f32_e32 v3, 0xbfb8aa3b, v3
	v_exp_f32_e32 v217, v3
; __device__ __forceinline__ void unpack8(const u32x4 w, float (&v)[8]) { v[0] = bf_lo(w.x); v[1] = bf_hi(w.x); v[2] = bf_lo(w.y); v[3] = bf_hi(w.y); v[4] = bf_lo(w.z); v[5] = bf_hi(w.z); v[6] = bf_lo(w.w); v[7] = bf_hi(w.w); }
;     __device__ __forceinline__ void after(int te, f32x4 (&acc)[2][2][4][2], const Unit& u, int wr, int wc, int fr, int fq) const {
;     ...
;             for (int bj = 0; bj < 2; ++bj) { const int c = col0 + bj * HALF;
;                 const f32x4 s0 = *(const f32x4*)(gb + c), s1 = *(const f32x4*)(gb + c + 4), a0 = *(const f32x4*)(gb + D_MODEL + c), a1 = *(const f32x4*)(gb + D_MODEL + c + 4);
; #pragma unroll
;                 for (int ai = 0; ai < 2; ++ai) {
;                     u32x4 gs[4], ga[4];
; #pragma unroll
;                     for (int m = 0; m < 4; ++m) { const size_t r = (size_t)(row0 + ai * HALF + m * 16); gs[m] = *(const u32x4*)(proj + r * LDP + PGS + c); ga[m] = *(const u32x4*)(proj + r * LDP + PGA + c); }
; #pragma unroll
;                     for (int m = 0; m < 4; ++m) { float vs[8], va[8]; unpack8(gs[m], vs); unpack8(ga[m], va);
; #pragma unroll
;                         for (int e = 0; e < 4; ++e) {
;                             acc[ai][bj][m][0][e] *= (1.f + __expf(-(va[e] + a0[e]))) * __builtin_amdgcn_rcpf(1.f + __expf(-(vs[e] + s0[e])));
;                             acc[ai][bj][m][1][e] *= (1.f + __expf(-(va[4 + e] + a1[e]))) * __builtin_amdgcn_rcpf(1.f + __expf(-(vs[4 + e] + s1[e]))); } }
	v_mul_f32_e32 v216, 0xbfb8aa3b, v216
	v_add_f32_e32 v3, 1.0, v206
	v_rcp_f32_e32 v219, v3
	v_lshlrev_b32_e32 v3, 16, v162
	v_mul_f32_e32 v209, 0xbfb8aa3b, v209
	v_exp_f32_e32 v216, v216
	v_add_f32_e32 v3, v142, v3
	v_exp_f32_e32 v209, v209
	v_mul_f32_e32 v3, 0xbfb8aa3b, v3
	v_exp_f32_e32 v3, v3
	v_pk_mul_f32 v[122:123], v[122:123], v[204:205]
	v_pk_add_f32 v[204:205], v[216:217], 1.0 op_sel_hi:[1,0]
	v_pk_add_f32 v[206:207], v[208:209], 1.0 op_sel_hi:[1,0]
	v_pk_mul_f32 v[204:205], v[204:205], v[218:219]
	v_pk_mul_f32 v[206:207], v[206:207], v[210:211]
	v_pk_mul_f32 v[120:121], v[120:121], v[204:205]
	v_and_b32_e32 v204, 0xffff0000, v162
	v_lshlrev_b32_e32 v162, 16, v164
	v_add_f32_e32 v3, 1.0, v3
	v_pk_mul_f32 v[118:119], v[118:119], v[206:207]
	v_lshlrev_b32_e32 v206, 16, v159
	v_and_b32_e32 v210, 0xffff0000, v159
	v_lshlrev_b32_e32 v159, 16, v160
	v_and_b32_e32 v211, 0xffff0000, v160
	v_rcp_f32_e32 v160, v3
	v_add_f32_e32 v3, v126, v162
	v_mul_f32_e32 v3, 0xbfb8aa3b, v3
	v_exp_f32_e32 v3, v3
	v_lshlrev_b32_e32 v205, 16, v163
	v_and_b32_e32 v207, 0xffff0000, v163
	v_and_b32_e32 v163, 0xffff0000, v164
	v_lshlrev_b32_e32 v164, 16, v158
	v_add_f32_e32 v3, 1.0, v3
	v_lshlrev_b32_e32 v208, 16, v165
	v_and_b32_e32 v209, 0xffff0000, v165
	v_and_b32_e32 v165, 0xffff0000, v158
	v_add_f32_e32 v158, v146, v164
	v_rcp_f32_e32 v164, v3
	v_add_f32_e32 v3, v143, v204
	v_mul_f32_e32 v3, 0xbfb8aa3b, v3
	v_exp_f32_e32 v3, v3
	v_lshlrev_b32_e32 v212, 16, v161
	v_and_b32_e32 v213, 0xffff0000, v161
	v_add_f32_e32 v159, v130, v159
	v_add_f32_e32 v3, 1.0, v3
	v_rcp_f32_e32 v161, v3
	v_add_f32_e32 v3, v127, v163
	v_mul_f32_e32 v3, 0xbfb8aa3b, v3
	v_exp_f32_e32 v3, v3
	v_mul_f32_e32 v159, 0xbfb8aa3b, v159
	v_exp_f32_e32 v162, v159
	v_add_f32_e32 v159, v147, v165
	v_add_f32_e32 v3, 1.0, v3
	v_rcp_f32_e32 v165, v3
	v_add_f32_e32 v3, v144, v205
	v_mul_f32_e32 v3, 0xbfb8aa3b, v3
	v_exp_f32_e32 v3, v3
	v_add_f32_e32 v204, v148, v206
	v_add_f32_e32 v207, v145, v207
	v_mul_f32_e32 v207, 0xbfb8aa3b, v207
	v_add_f32_e32 v3, 1.0, v3
	v_rcp_f32_e32 v206, v3
	v_add_f32_e32 v3, v128, v208
	v_mul_f32_e32 v3, 0xbfb8aa3b, v3
	v_exp_f32_e32 v3, v3
	v_add_f32_e32 v205, v132, v212
	v_exp_f32_e32 v207, v207
	v_mul_f32_e32 v205, 0xbfb8aa3b, v205
	v_exp_f32_e32 v208, v205
	v_add_f32_e32 v205, v149, v210
	v_mul_f32_e32 v158, 0xbfb8aa3b, v158
	v_mul_f32_e32 v159, 0xbfb8aa3b, v159
	v_mul_f32_e32 v204, 0xbfb8aa3b, v204
	v_add_f32_e32 v3, 1.0, v3
	v_mul_f32_e32 v205, 0xbfb8aa3b, v205
	v_exp_f32_e32 v158, v158
	v_exp_f32_e32 v159, v159
	v_exp_f32_e32 v204, v204
	v_exp_f32_e32 v205, v205
	v_rcp_f32_e32 v210, v3
	v_add_f32_e32 v3, 1.0, v207
	v_rcp_f32_e32 v207, v3
	v_pk_add_f32 v[204:205], v[204:205], 1.0 op_sel_hi:[1,0]
	v_pk_add_f32 v[158:159], v[158:159], 1.0 op_sel_hi:[1,0]
	v_add_f32_e32 v3, v133, v213
	v_pk_mul_f32 v[158:159], v[158:159], v[160:161]
	v_pk_mul_f32 v[160:161], v[204:205], v[206:207]
	v_mul_f32_e32 v3, 0xbfb8aa3b, v3
	v_pk_mul_f32 v[116:117], v[116:117], v[160:161]
	v_add_f32_e32 v160, v129, v209
	v_mul_f32_e32 v160, 0xbfb8aa3b, v160
	v_exp_f32_e32 v160, v160
	v_exp_f32_e32 v209, v3
	v_add_f32_e32 v163, v131, v211
	v_mul_f32_e32 v163, 0xbfb8aa3b, v163
	v_add_f32_e32 v3, 1.0, v160
	v_rcp_f32_e32 v211, v3
	v_lshlrev_b32_e32 v3, 16, v154
	v_add_f32_e32 v3, v142, v3
	v_exp_f32_e32 v163, v163
	v_mul_f32_e32 v3, 0xbfb8aa3b, v3
	v_exp_f32_e32 v3, v3
	v_pk_mul_f32 v[114:115], v[114:115], v[158:159]
	v_pk_add_f32 v[158:159], v[208:209], 1.0 op_sel_hi:[1,0]
	v_pk_add_f32 v[160:161], v[162:163], 1.0 op_sel_hi:[1,0]
	v_pk_mul_f32 v[158:159], v[158:159], v[210:211]
	v_pk_mul_f32 v[160:161], v[160:161], v[164:165]
	v_pk_mul_f32 v[112:113], v[112:113], v[158:159]
	v_and_b32_e32 v158, 0xffff0000, v154
	v_lshlrev_b32_e32 v154, 16, v156
	v_add_f32_e32 v3, 1.0, v3
	v_pk_mul_f32 v[110:111], v[110:111], v[160:161]
	v_lshlrev_b32_e32 v160, 16, v151
	v_and_b32_e32 v204, 0xffff0000, v151
	v_lshlrev_b32_e32 v151, 16, v152
	v_and_b32_e32 v162, 0xffff0000, v152
	v_rcp_f32_e32 v152, v3
	v_add_f32_e32 v3, v126, v154
	v_mul_f32_e32 v3, 0xbfb8aa3b, v3
	v_exp_f32_e32 v3, v3
	v_lshlrev_b32_e32 v159, 16, v155
	v_and_b32_e32 v161, 0xffff0000, v155
	v_and_b32_e32 v155, 0xffff0000, v156
	v_lshlrev_b32_e32 v156, 16, v150
	v_add_f32_e32 v3, 1.0, v3
	v_lshlrev_b32_e32 v164, 16, v157
	v_and_b32_e32 v165, 0xffff0000, v157
	v_and_b32_e32 v157, 0xffff0000, v150
	v_add_f32_e32 v150, v146, v156
	v_rcp_f32_e32 v156, v3
	v_add_f32_e32 v3, v143, v158
	v_mul_f32_e32 v3, 0xbfb8aa3b, v3
	v_exp_f32_e32 v3, v3
	v_lshlrev_b32_e32 v205, 16, v153
	v_and_b32_e32 v206, 0xffff0000, v153
	v_add_f32_e32 v151, v130, v151
	v_add_f32_e32 v3, 1.0, v3
	v_rcp_f32_e32 v153, v3
	v_add_f32_e32 v3, v127, v155
	v_add_f32_e32 v155, v131, v162
	v_add_co_u32_e32 v162, vcc, s26, v192
	v_mul_f32_e32 v3, 0xbfb8aa3b, v3
	s_nop 0
	v_addc_co_u32_e32 v163, vcc, 0, v193, vcc
	global_load_dwordx4 v[228:231], v[162:163], off
	v_exp_f32_e32 v3, v3
	v_mul_f32_e32 v151, 0xbfb8aa3b, v151
	s_mov_b32 s26, 0x202000
	v_exp_f32_e32 v154, v151
	v_add_f32_e32 v3, 1.0, v3
	v_add_f32_e32 v151, v147, v157
	v_rcp_f32_e32 v157, v3
	v_add_f32_e32 v3, v144, v159
	v_add_co_u32_e32 v162, vcc, s26, v192
	v_mul_f32_e32 v3, 0xbfb8aa3b, v3
	s_nop 0
	v_addc_co_u32_e32 v163, vcc, 0, v193, vcc
	v_exp_f32_e32 v3, v3
	global_load_dwordx4 v[232:235], v[162:163], off
	v_add_f32_e32 v158, v148, v160
	v_add_f32_e32 v161, v145, v161
	v_add_f32_e32 v3, 1.0, v3
	v_rcp_f32_e32 v160, v3
	v_add_f32_e32 v3, v128, v164
	v_mul_f32_e32 v3, 0xbfb8aa3b, v3
	v_exp_f32_e32 v3, v3
	v_mul_f32_e32 v161, 0xbfb8aa3b, v161
	v_add_f32_e32 v159, v132, v205
	v_exp_f32_e32 v161, v161
	v_mul_f32_e32 v159, 0xbfb8aa3b, v159
; __device__ __forceinline__ void unpack8(const u32x4 w, float (&v)[8]) { v[0] = bf_lo(w.x); v[1] = bf_hi(w.x); v[2] = bf_lo(w.y); v[3] = bf_hi(w.y); v[4] = bf_lo(w.z); v[5] = bf_hi(w.z); v[6] = bf_lo(w.w); v[7] = bf_hi(w.w); }
;     __device__ __forceinline__ void after(int te, f32x4 (&acc)[2][2][4][2], const Unit& u, int wr, int wc, int fr, int fq) const {
;     ...
;             for (int bj = 0; bj < 2; ++bj) { const int c = col0 + bj * HALF;
;                 const f32x4 s0 = *(const f32x4*)(gb + c), s1 = *(const f32x4*)(gb + c + 4), a0 = *(const f32x4*)(gb + D_MODEL + c), a1 = *(const f32x4*)(gb + D_MODEL + c + 4);
; #pragma unroll
;                 for (int ai = 0; ai < 2; ++ai) {
;                     u32x4 gs[4], ga[4];
; #pragma unroll
;                     for (int m = 0; m < 4; ++m) { const size_t r = (size_t)(row0 + ai * HALF + m * 16); gs[m] = *(const u32x4*)(proj + r * LDP + PGS + c); ga[m] = *(const u32x4*)(proj + r * LDP + PGA + c); }
; #pragma unroll
;                     for (int m = 0; m < 4; ++m) { float vs[8], va[8]; unpack8(gs[m], vs); unpack8(ga[m], va);
; #pragma unroll
;                         for (int e = 0; e < 4; ++e) {
;                             acc[ai][bj][m][0][e] *= (1.f + __expf(-(va[e] + a0[e]))) * __builtin_amdgcn_rcpf(1.f + __expf(-(vs[e] + s0[e])));
;                             acc[ai][bj][m][1][e] *= (1.f + __expf(-(va[4 + e] + a1[e]))) * __builtin_amdgcn_rcpf(1.f + __expf(-(vs[4 + e] + s1[e]))); } }
	v_exp_f32_e32 v162, v159
	v_add_f32_e32 v159, v149, v204
	v_mul_f32_e32 v150, 0xbfb8aa3b, v150
	v_mul_f32_e32 v151, 0xbfb8aa3b, v151
	v_mul_f32_e32 v158, 0xbfb8aa3b, v158
	v_add_f32_e32 v3, 1.0, v3
	v_mul_f32_e32 v159, 0xbfb8aa3b, v159
	v_exp_f32_e32 v150, v150
	v_exp_f32_e32 v151, v151
	v_exp_f32_e32 v158, v158
	v_exp_f32_e32 v159, v159
	v_rcp_f32_e32 v164, v3
	v_add_f32_e32 v3, 1.0, v161
	v_rcp_f32_e32 v161, v3
	v_pk_add_f32 v[158:159], v[158:159], 1.0 op_sel_hi:[1,0]
	v_pk_add_f32 v[150:151], v[150:151], 1.0 op_sel_hi:[1,0]
	v_add_f32_e32 v3, v133, v206
	v_pk_mul_f32 v[150:151], v[150:151], v[152:153]
	v_pk_mul_f32 v[152:153], v[158:159], v[160:161]
	v_mul_f32_e32 v3, 0xbfb8aa3b, v3
	v_pk_mul_f32 v[108:109], v[108:109], v[152:153]
	v_add_f32_e32 v152, v129, v165
	v_mul_f32_e32 v152, 0xbfb8aa3b, v152
	v_exp_f32_e32 v152, v152
	v_exp_f32_e32 v163, v3
	v_mul_f32_e32 v155, 0xbfb8aa3b, v155
	v_exp_f32_e32 v155, v155
	v_add_f32_e32 v3, 1.0, v152
	v_rcp_f32_e32 v165, v3
	s_mov_b64 s[26:27], 0x200000
	v_lshl_add_u64 v[218:219], v[192:193], 0, s[26:27]
	s_mov_b64 s[26:27], 0x202000
	v_pk_mul_f32 v[106:107], v[106:107], v[150:151]
	v_pk_add_f32 v[150:151], v[162:163], 1.0 op_sel_hi:[1,0]
	v_lshl_add_u64 v[216:217], v[192:193], 0, s[26:27]
	s_mov_b64 s[26:27], 0x240000
	v_pk_mul_f32 v[150:151], v[150:151], v[164:165]
	v_lshl_add_u64 v[204:205], v[192:193], 0, s[26:27]
	s_mov_b32 s26, 0x240000
	v_pk_add_f32 v[152:153], v[154:155], 1.0 op_sel_hi:[1,0]
	v_pk_mul_f32 v[104:105], v[104:105], v[150:151]
	v_add_co_u32_e32 v150, vcc, s26, v192
	s_mov_b64 s[26:27], 0x242000
	v_pk_mul_f32 v[152:153], v[152:153], v[156:157]
	v_addc_co_u32_e32 v151, vcc, 0, v193, vcc
	v_lshl_add_u64 v[206:207], v[192:193], 0, s[26:27]
	s_mov_b32 s26, 0x242000
	v_pk_mul_f32 v[102:103], v[102:103], v[152:153]
	v_add_co_u32_e32 v152, vcc, s26, v192
	s_mov_b64 s[26:27], 0x280000
	s_nop 0
	v_addc_co_u32_e32 v153, vcc, 0, v193, vcc
	global_load_dwordx4 v[236:239], v[150:151], off
	global_load_dwordx4 v[240:243], v[152:153], off
	s_waitcnt vmcnt(3)
	v_lshlrev_b32_e32 v3, 16, v228
	v_add_f32_e32 v3, v142, v3
	v_mul_f32_e32 v3, 0xbfb8aa3b, v3
	v_exp_f32_e32 v3, v3
	v_lshlrev_b32_e32 v227, 16, v229
	v_and_b32_e32 v245, 0xffff0000, v229
	v_lshlrev_b32_e32 v229, 16, v230
	v_add_f32_e32 v3, 1.0, v3
	v_and_b32_e32 v246, 0xffff0000, v230
	v_rcp_f32_e32 v230, v3
	v_add_f32_e32 v3, v126, v229
	v_mul_f32_e32 v3, 0xbfb8aa3b, v3
	v_exp_f32_e32 v3, v3
	v_lshl_add_u64 v[208:209], v[192:193], 0, s[26:27]
	s_mov_b32 s26, 0x280000
	v_add_co_u32_e32 v150, vcc, s26, v192
	s_mov_b64 s[26:27], 0x282000
	s_nop 0
	v_addc_co_u32_e32 v151, vcc, 0, v193, vcc
	v_lshl_add_u64 v[210:211], v[192:193], 0, s[26:27]
	s_mov_b32 s26, 0x282000
	v_add_co_u32_e32 v152, vcc, s26, v192
	v_and_b32_e32 v225, 0xffff0000, v228
	v_add_f32_e32 v3, 1.0, v3
	v_addc_co_u32_e32 v153, vcc, 0, v193, vcc
	global_load_dwordx4 v[162:165], v[150:151], off
	global_load_dwordx4 v[158:161], v[152:153], off
	v_lshlrev_b32_e32 v247, 16, v231
	v_and_b32_e32 v251, 0xffff0000, v231
	s_waitcnt vmcnt(4)
	v_lshlrev_b32_e32 v228, 16, v232
	v_and_b32_e32 v231, 0xffff0000, v232
	v_lshlrev_b32_e32 v248, 16, v233
	v_and_b32_e32 v249, 0xffff0000, v233
	v_lshlrev_b32_e32 v232, 16, v234
	v_and_b32_e32 v233, 0xffff0000, v234
	v_rcp_f32_e32 v234, v3
	v_add_f32_e32 v3, v143, v225
	v_mul_f32_e32 v3, 0xbfb8aa3b, v3
	v_exp_f32_e32 v3, v3
	v_add_f32_e32 v225, v147, v231
	v_lshlrev_b32_e32 v250, 16, v235
	v_and_b32_e32 v253, 0xffff0000, v235
	v_add_f32_e32 v3, 1.0, v3
	v_rcp_f32_e32 v231, v3
	v_add_f32_e32 v3, v127, v246
	v_mul_f32_e32 v3, 0xbfb8aa3b, v3
	v_exp_f32_e32 v3, v3
	v_add_f32_e32 v229, v130, v232
	v_mul_f32_e32 v229, 0xbfb8aa3b, v229
	v_mul_f32_e32 v225, 0xbfb8aa3b, v225
	v_add_f32_e32 v3, 1.0, v3
	v_rcp_f32_e32 v235, v3
	v_add_f32_e32 v3, v144, v227
	v_mul_f32_e32 v3, 0xbfb8aa3b, v3
	v_exp_f32_e32 v3, v3
	v_exp_f32_e32 v232, v229
	v_exp_f32_e32 v229, v225
	v_add_f32_e32 v225, v131, v233
	v_mul_f32_e32 v225, 0xbfb8aa3b, v225
	v_exp_f32_e32 v233, v225
	v_add_f32_e32 v225, v148, v248
	v_mul_f32_e32 v225, 0xbfb8aa3b, v225
	v_add_f32_e32 v3, 1.0, v3
	v_exp_f32_e32 v246, v225
	v_rcp_f32_e32 v248, v3
	v_add_f32_e32 v3, v128, v247
	v_add_f32_e32 v225, v132, v250
	v_mul_f32_e32 v3, 0xbfb8aa3b, v3
	v_mul_f32_e32 v225, 0xbfb8aa3b, v225
	v_add_f32_e32 v227, v145, v245
	v_exp_f32_e32 v3, v3
	v_exp_f32_e32 v250, v225
	v_add_f32_e32 v225, v149, v249
	v_mul_f32_e32 v227, 0xbfb8aa3b, v227
	v_exp_f32_e32 v227, v227
	v_mul_f32_e32 v225, 0xbfb8aa3b, v225
	v_exp_f32_e32 v247, v225
	v_add_f32_e32 v225, v129, v251
	v_mul_f32_e32 v225, 0xbfb8aa3b, v225
	v_add_f32_e32 v3, 1.0, v3
	v_exp_f32_e32 v225, v225
	v_rcp_f32_e32 v252, v3
	v_add_f32_e32 v3, 1.0, v227
	v_add_f32_e32 v228, v146, v228
	v_rcp_f32_e32 v249, v3
	v_add_f32_e32 v3, v133, v253
	v_mul_f32_e32 v228, 0xbfb8aa3b, v228
	v_mul_f32_e32 v3, 0xbfb8aa3b, v3
	v_exp_f32_e32 v228, v228
	v_exp_f32_e32 v251, v3
	v_add_f32_e32 v3, 1.0, v225
	v_rcp_f32_e32 v253, v3
	s_waitcnt vmcnt(3)
; __device__ __forceinline__ void unpack8(const u32x4 w, float (&v)[8]) { v[0] = bf_lo(w.x); v[1] = bf_hi(w.x); v[2] = bf_lo(w.y); v[3] = bf_hi(w.y); v[4] = bf_lo(w.z); v[5] = bf_hi(w.z); v[6] = bf_lo(w.w); v[7] = bf_hi(w.w); }
;     __device__ __forceinline__ void after(int te, f32x4 (&acc)[2][2][4][2], const Unit& u, int wr, int wc, int fr, int fq) const {
;     ...
;             for (int bj = 0; bj < 2; ++bj) { const int c = col0 + bj * HALF;
;                 const f32x4 s0 = *(const f32x4*)(gb + c), s1 = *(const f32x4*)(gb + c + 4), a0 = *(const f32x4*)(gb + D_MODEL + c), a1 = *(const f32x4*)(gb + D_MODEL + c + 4);
; #pragma unroll
;                 for (int ai = 0; ai < 2; ++ai) {
;                     u32x4 gs[4], ga[4];
; #pragma unroll
;                     for (int m = 0; m < 4; ++m) { const size_t r = (size_t)(row0 + ai * HALF + m * 16); gs[m] = *(const u32x4*)(proj + r * LDP + PGS + c); ga[m] = *(const u32x4*)(proj + r * LDP + PGA + c); }
; #pragma unroll
;                     for (int m = 0; m < 4; ++m) { float vs[8], va[8]; unpack8(gs[m], vs); unpack8(ga[m], va);
; #pragma unroll
;                         for (int e = 0; e < 4; ++e) {
;                             acc[ai][bj][m][0][e] *= (1.f + __expf(-(va[e] + a0[e]))) * __builtin_amdgcn_rcpf(1.f + __expf(-(vs[e] + s0[e])));
;                             acc[ai][bj][m][1][e] *= (1.f + __expf(-(va[4 + e] + a1[e]))) * __builtin_amdgcn_rcpf(1.f + __expf(-(vs[4 + e] + s1[e]))); } }
	v_lshlrev_b32_e32 v3, 16, v236
	v_add_f32_e32 v3, v142, v3
	v_mul_f32_e32 v3, 0xbfb8aa3b, v3
	v_pk_add_f32 v[228:229], v[228:229], 1.0 op_sel_hi:[1,0]
	v_exp_f32_e32 v3, v3
	v_pk_add_f32 v[246:247], v[246:247], 1.0 op_sel_hi:[1,0]
	v_pk_mul_f32 v[228:229], v[228:229], v[230:231]
	v_pk_mul_f32 v[230:231], v[246:247], v[248:249]
	v_pk_mul_f32 v[98:99], v[98:99], v[228:229]
	v_pk_add_f32 v[228:229], v[250:251], 1.0 op_sel_hi:[1,0]
	v_pk_mul_f32 v[100:101], v[100:101], v[230:231]
	v_pk_add_f32 v[230:231], v[232:233], 1.0 op_sel_hi:[1,0]
	v_pk_mul_f32 v[228:229], v[228:229], v[252:253]
	v_pk_mul_f32 v[230:231], v[230:231], v[234:235]
	v_pk_mul_f32 v[96:97], v[96:97], v[228:229]
	v_lshlrev_b32_e32 v229, 16, v238
	v_add_f32_e32 v3, 1.0, v3
	v_pk_mul_f32 v[94:95], v[94:95], v[230:231]
	v_rcp_f32_e32 v230, v3
	v_add_f32_e32 v3, v126, v229
	v_mul_f32_e32 v3, 0xbfb8aa3b, v3
	v_exp_f32_e32 v3, v3
	v_and_b32_e32 v225, 0xffff0000, v236
	s_mov_b64 s[26:27], 0x2c0000
	v_lshl_add_u64 v[212:213], v[192:193], 0, s[26:27]
	v_add_f32_e32 v3, 1.0, v3
	v_rcp_f32_e32 v234, v3
	v_add_f32_e32 v3, v143, v225
	v_mul_f32_e32 v3, 0xbfb8aa3b, v3
	v_exp_f32_e32 v3, v3
	s_mov_b32 s26, 0x2c0000
	v_add_co_u32_e32 v150, vcc, s26, v192
	s_mov_b64 s[26:27], 0x2c2000
	s_nop 0
	v_addc_co_u32_e32 v151, vcc, 0, v193, vcc
	v_lshl_add_u64 v[214:215], v[192:193], 0, s[26:27]
	s_mov_b32 s26, 0x2c2000
	v_and_b32_e32 v233, 0xffff0000, v238
	s_waitcnt vmcnt(2)
	v_and_b32_e32 v231, 0xffff0000, v240
	v_add_f32_e32 v3, 1.0, v3
	v_add_co_u32_e32 v152, vcc, s26, v192
	v_add_f32_e32 v225, v147, v231
	v_rcp_f32_e32 v231, v3
	v_add_f32_e32 v3, v127, v233
	v_addc_co_u32_e32 v153, vcc, 0, v193, vcc
	v_mul_f32_e32 v3, 0xbfb8aa3b, v3
	global_load_dwordx4 v[154:157], v[150:151], off
	s_nop 0
	global_load_dwordx4 v[150:153], v[152:153], off
	v_exp_f32_e32 v3, v3
	v_lshlrev_b32_e32 v232, 16, v242
	v_add_f32_e32 v229, v130, v232
	v_lshlrev_b32_e32 v227, 16, v237
	v_and_b32_e32 v235, 0xffff0000, v242
	v_mul_f32_e32 v229, 0xbfb8aa3b, v229
	v_mul_f32_e32 v225, 0xbfb8aa3b, v225
	v_add_f32_e32 v3, 1.0, v3
	v_exp_f32_e32 v232, v229
	v_exp_f32_e32 v229, v225
	v_add_f32_e32 v225, v131, v235
	v_rcp_f32_e32 v235, v3
	v_add_f32_e32 v3, v144, v227
	v_mul_f32_e32 v3, 0xbfb8aa3b, v3
	v_exp_f32_e32 v3, v3
	v_lshlrev_b32_e32 v236, 16, v241
	v_mul_f32_e32 v225, 0xbfb8aa3b, v225
	v_exp_f32_e32 v233, v225
	v_add_f32_e32 v225, v148, v236
	v_lshlrev_b32_e32 v245, 16, v239
	v_lshlrev_b32_e32 v228, 16, v240
	v_lshlrev_b32_e32 v240, 16, v243
	v_mul_f32_e32 v225, 0xbfb8aa3b, v225
	v_add_f32_e32 v3, 1.0, v3
	v_and_b32_e32 v237, 0xffff0000, v237
	v_exp_f32_e32 v236, v225
	v_rcp_f32_e32 v238, v3
	v_add_f32_e32 v3, v128, v245
	v_add_f32_e32 v225, v132, v240
	v_and_b32_e32 v246, 0xffff0000, v239
	v_and_b32_e32 v239, 0xffff0000, v241
	v_mul_f32_e32 v3, 0xbfb8aa3b, v3
	v_mul_f32_e32 v225, 0xbfb8aa3b, v225
	v_add_f32_e32 v227, v145, v237
	v_exp_f32_e32 v3, v3
	v_exp_f32_e32 v240, v225
	v_add_f32_e32 v225, v149, v239
	v_mul_f32_e32 v227, 0xbfb8aa3b, v227
	v_exp_f32_e32 v227, v227
	v_mul_f32_e32 v225, 0xbfb8aa3b, v225
	v_exp_f32_e32 v237, v225
	v_add_f32_e32 v225, v129, v246
	v_mul_f32_e32 v225, 0xbfb8aa3b, v225
	v_add_f32_e32 v3, 1.0, v3
	v_exp_f32_e32 v225, v225
	v_and_b32_e32 v241, 0xffff0000, v243
	v_rcp_f32_e32 v242, v3
	v_add_f32_e32 v3, 1.0, v227
	v_rcp_f32_e32 v239, v3
	v_add_f32_e32 v3, v133, v241
	v_add_f32_e32 v228, v146, v228
	v_mul_f32_e32 v3, 0xbfb8aa3b, v3
	v_mul_f32_e32 v228, 0xbfb8aa3b, v228
	v_exp_f32_e32 v241, v3
	v_add_f32_e32 v3, 1.0, v225
	v_exp_f32_e32 v228, v228
	v_rcp_f32_e32 v243, v3
	s_waitcnt vmcnt(3)
	v_lshlrev_b32_e32 v3, 16, v162
	v_add_f32_e32 v3, v142, v3
	v_mul_f32_e32 v3, 0xbfb8aa3b, v3
	v_exp_f32_e32 v3, v3
	v_pk_add_f32 v[236:237], v[236:237], 1.0 op_sel_hi:[1,0]
	v_pk_add_f32 v[228:229], v[228:229], 1.0 op_sel_hi:[1,0]
	v_and_b32_e32 v225, 0xffff0000, v162
	v_pk_mul_f32 v[228:229], v[228:229], v[230:231]
	v_pk_mul_f32 v[230:231], v[236:237], v[238:239]
	v_pk_mul_f32 v[90:91], v[90:91], v[228:229]
	v_pk_mul_f32 v[92:93], v[92:93], v[230:231]
	v_pk_add_f32 v[228:229], v[240:241], 1.0 op_sel_hi:[1,0]
	v_pk_add_f32 v[230:231], v[232:233], 1.0 op_sel_hi:[1,0]
	v_pk_mul_f32 v[228:229], v[228:229], v[242:243]
	v_pk_mul_f32 v[230:231], v[230:231], v[234:235]
	v_lshlrev_b32_e32 v162, 16, v164
	v_add_f32_e32 v3, 1.0, v3
	v_pk_mul_f32 v[88:89], v[88:89], v[228:229]
	v_pk_mul_f32 v[86:87], v[86:87], v[230:231]
	s_waitcnt vmcnt(2)
; __device__ __forceinline__ void unpack8(const u32x4 w, float (&v)[8]) { v[0] = bf_lo(w.x); v[1] = bf_hi(w.x); v[2] = bf_lo(w.y); v[3] = bf_hi(w.y); v[4] = bf_lo(w.z); v[5] = bf_hi(w.z); v[6] = bf_lo(w.w); v[7] = bf_hi(w.w); }
;     __device__ __forceinline__ void after(int te, f32x4 (&acc)[2][2][4][2], const Unit& u, int wr, int wc, int fr, int fq) const {
;     ...
;             for (int bj = 0; bj < 2; ++bj) { const int c = col0 + bj * HALF;
;                 const f32x4 s0 = *(const f32x4*)(gb + c), s1 = *(const f32x4*)(gb + c + 4), a0 = *(const f32x4*)(gb + D_MODEL + c), a1 = *(const f32x4*)(gb + D_MODEL + c + 4);
; #pragma unroll
;                 for (int ai = 0; ai < 2; ++ai) {
;                     u32x4 gs[4], ga[4];
; #pragma unroll
;                     for (int m = 0; m < 4; ++m) { const size_t r = (size_t)(row0 + ai * HALF + m * 16); gs[m] = *(const u32x4*)(proj + r * LDP + PGS + c); ga[m] = *(const u32x4*)(proj + r * LDP + PGA + c); }
; #pragma unroll
;                     for (int m = 0; m < 4; ++m) { float vs[8], va[8]; unpack8(gs[m], vs); unpack8(ga[m], va);
; #pragma unroll
;                         for (int e = 0; e < 4; ++e) {
;                             acc[ai][bj][m][0][e] *= (1.f + __expf(-(va[e] + a0[e]))) * __builtin_amdgcn_rcpf(1.f + __expf(-(vs[e] + s0[e])));
;                             acc[ai][bj][m][1][e] *= (1.f + __expf(-(va[4 + e] + a1[e]))) * __builtin_amdgcn_rcpf(1.f + __expf(-(vs[4 + e] + s1[e]))); } }
	v_lshlrev_b32_e32 v228, 16, v159
	v_and_b32_e32 v234, 0xffff0000, v159
	v_lshlrev_b32_e32 v159, 16, v160
	v_and_b32_e32 v230, 0xffff0000, v160
	v_rcp_f32_e32 v160, v3
	v_add_f32_e32 v3, v126, v162
	v_mul_f32_e32 v3, 0xbfb8aa3b, v3
	v_exp_f32_e32 v3, v3
	v_lshlrev_b32_e32 v227, 16, v163
	v_and_b32_e32 v229, 0xffff0000, v163
	v_and_b32_e32 v163, 0xffff0000, v164
	v_lshlrev_b32_e32 v164, 16, v158
	v_add_f32_e32 v3, 1.0, v3
	v_lshlrev_b32_e32 v231, 16, v165
	v_and_b32_e32 v233, 0xffff0000, v165
	v_and_b32_e32 v165, 0xffff0000, v158
	v_add_f32_e32 v158, v146, v164
	v_rcp_f32_e32 v164, v3
	v_add_f32_e32 v3, v143, v225
	v_mul_f32_e32 v3, 0xbfb8aa3b, v3
	v_exp_f32_e32 v3, v3
	v_lshlrev_b32_e32 v232, 16, v161
	v_and_b32_e32 v235, 0xffff0000, v161
	v_add_f32_e32 v159, v130, v159
	v_add_f32_e32 v3, 1.0, v3
	v_rcp_f32_e32 v161, v3
	v_add_f32_e32 v3, v127, v163
	v_mul_f32_e32 v3, 0xbfb8aa3b, v3
	v_exp_f32_e32 v3, v3
	v_mul_f32_e32 v159, 0xbfb8aa3b, v159
	v_exp_f32_e32 v162, v159
	v_add_f32_e32 v159, v147, v165
	v_add_f32_e32 v3, 1.0, v3
	v_rcp_f32_e32 v165, v3
	v_add_f32_e32 v3, v144, v227
	v_mul_f32_e32 v3, 0xbfb8aa3b, v3
	v_exp_f32_e32 v3, v3
	v_add_f32_e32 v163, v131, v230
	v_add_f32_e32 v225, v148, v228
	v_add_f32_e32 v227, v145, v229
	v_add_f32_e32 v3, 1.0, v3
	v_rcp_f32_e32 v230, v3
	v_add_f32_e32 v3, v128, v231
	v_mul_f32_e32 v3, 0xbfb8aa3b, v3
	v_mul_f32_e32 v225, 0xbfb8aa3b, v225
	v_exp_f32_e32 v3, v3
	v_mul_f32_e32 v227, 0xbfb8aa3b, v227
	v_exp_f32_e32 v228, v225
	v_add_f32_e32 v225, v132, v232
	v_exp_f32_e32 v227, v227
	v_mul_f32_e32 v225, 0xbfb8aa3b, v225
	v_exp_f32_e32 v232, v225
	v_add_f32_e32 v225, v149, v234
	v_mul_f32_e32 v158, 0xbfb8aa3b, v158
	v_mul_f32_e32 v159, 0xbfb8aa3b, v159
	v_add_f32_e32 v3, 1.0, v3
	v_mul_f32_e32 v225, 0xbfb8aa3b, v225
	v_exp_f32_e32 v158, v158
	v_exp_f32_e32 v159, v159
	v_exp_f32_e32 v229, v225
	v_rcp_f32_e32 v234, v3
	v_add_f32_e32 v3, 1.0, v227
	v_rcp_f32_e32 v231, v3
	v_pk_add_f32 v[228:229], v[228:229], 1.0 op_sel_hi:[1,0]
	v_pk_add_f32 v[158:159], v[158:159], 1.0 op_sel_hi:[1,0]
	v_add_f32_e32 v3, v133, v235
	v_pk_mul_f32 v[158:159], v[158:159], v[160:161]
	v_pk_mul_f32 v[160:161], v[228:229], v[230:231]
	v_mul_f32_e32 v3, 0xbfb8aa3b, v3
	v_pk_mul_f32 v[84:85], v[84:85], v[160:161]
	v_add_f32_e32 v160, v129, v233
	v_mul_f32_e32 v160, 0xbfb8aa3b, v160
	v_exp_f32_e32 v160, v160
	v_exp_f32_e32 v233, v3
	s_waitcnt vmcnt(1)
	v_lshlrev_b32_e32 v225, 16, v155
	v_and_b32_e32 v227, 0xffff0000, v155
	v_add_f32_e32 v3, 1.0, v160
	v_rcp_f32_e32 v235, v3
	v_lshlrev_b32_e32 v3, 16, v154
	v_add_f32_e32 v3, v142, v3
	v_mul_f32_e32 v3, 0xbfb8aa3b, v3
	v_exp_f32_e32 v3, v3
	v_lshlrev_b32_e32 v155, 16, v156
	v_and_b32_e32 v236, 0xffff0000, v156
	s_waitcnt vmcnt(0)
	v_lshlrev_b32_e32 v156, 16, v150
	v_add_f32_e32 v3, 1.0, v3
	v_mul_f32_e32 v163, 0xbfb8aa3b, v163
	v_add_f32_e32 v142, v146, v156
	v_rcp_f32_e32 v146, v3
	v_add_f32_e32 v3, v126, v155
	v_exp_f32_e32 v163, v163
	v_mul_f32_e32 v3, 0xbfb8aa3b, v3
	v_exp_f32_e32 v3, v3
	v_pk_mul_f32 v[82:83], v[82:83], v[158:159]
	v_pk_add_f32 v[158:159], v[232:233], 1.0 op_sel_hi:[1,0]
	v_pk_add_f32 v[160:161], v[162:163], 1.0 op_sel_hi:[1,0]
	v_pk_mul_f32 v[158:159], v[158:159], v[234:235]
	v_pk_mul_f32 v[160:161], v[160:161], v[164:165]
	v_and_b32_e32 v150, 0xffff0000, v150
	v_lshlrev_b32_e32 v239, 16, v151
	v_and_b32_e32 v240, 0xffff0000, v151
	v_lshlrev_b32_e32 v151, 16, v152
	global_load_dwordx4 v[228:231], v[192:193], off offset:256
	global_load_dwordx4 v[232:235], v[202:203], off offset:256
	v_add_f32_e32 v3, 1.0, v3
	v_pk_mul_f32 v[80:81], v[80:81], v[158:159]
	v_pk_mul_f32 v[78:79], v[78:79], v[160:161]
	v_and_b32_e32 v241, 0xffff0000, v152
	v_lshlrev_b32_e32 v242, 16, v153
	v_and_b32_e32 v243, 0xffff0000, v153
	v_add_f32_e32 v126, v130, v151
	v_rcp_f32_e32 v130, v3
	v_add_f32_e32 v3, v147, v150
	global_load_dwordx4 v[150:153], v[196:197], off offset:528
	global_load_dwordx4 v[158:161], v[196:197], off offset:512
	v_and_b32_e32 v154, 0xffff0000, v154
	v_lshlrev_b32_e32 v237, 16, v157
	v_and_b32_e32 v238, 0xffff0000, v157
	v_add_f32_e32 v143, v143, v154
	global_load_dwordx4 v[154:157], v[198:199], off offset:528
	global_load_dwordx4 v[162:165], v[198:199], off offset:512
	v_mul_f32_e32 v143, 0xbfb8aa3b, v143
	v_exp_f32_e32 v147, v143
	v_mul_f32_e32 v3, 0xbfb8aa3b, v3
	v_exp_f32_e32 v143, v3
	v_add_f32_e32 v145, v145, v227
	v_add_f32_e32 v3, 1.0, v147
	v_rcp_f32_e32 v147, v3
	v_add_f32_e32 v3, v127, v236
	v_mul_f32_e32 v3, 0xbfb8aa3b, v3
	v_exp_f32_e32 v3, v3
	v_add_f32_e32 v127, v131, v241
	v_mul_f32_e32 v145, 0xbfb8aa3b, v145
	v_add_f32_e32 v129, v129, v238
	v_add_f32_e32 v3, 1.0, v3
	v_rcp_f32_e32 v131, v3
	v_add_f32_e32 v3, v144, v225
	v_mul_f32_e32 v3, 0xbfb8aa3b, v3
	v_exp_f32_e32 v3, v3
	v_add_f32_e32 v144, v148, v239
	v_mul_f32_e32 v129, 0xbfb8aa3b, v129
	v_mul_f32_e32 v142, 0xbfb8aa3b, v142
	v_add_f32_e32 v3, 1.0, v3
	v_rcp_f32_e32 v148, v3
	v_add_f32_e32 v3, v128, v237
	v_mul_f32_e32 v3, 0xbfb8aa3b, v3
	v_exp_f32_e32 v3, v3
	v_add_f32_e32 v128, v132, v242
	v_add_f32_e32 v132, v149, v240
	v_exp_f32_e32 v149, v145
	v_add_f32_e32 v3, 1.0, v3
	v_mul_f32_e32 v132, 0xbfb8aa3b, v132
	v_exp_f32_e32 v145, v132
	v_rcp_f32_e32 v132, v3
	v_add_f32_e32 v3, 1.0, v149
	v_rcp_f32_e32 v149, v3
	v_add_f32_e32 v3, v133, v243
	v_exp_f32_e32 v133, v129
	v_mul_f32_e32 v126, 0xbfb8aa3b, v126
	v_mul_f32_e32 v127, 0xbfb8aa3b, v127
	v_mul_f32_e32 v144, 0xbfb8aa3b, v144
	v_mul_f32_e32 v128, 0xbfb8aa3b, v128
	v_mul_f32_e32 v3, 0xbfb8aa3b, v3
	v_exp_f32_e32 v142, v142
	v_exp_f32_e32 v126, v126
	v_exp_f32_e32 v127, v127
	v_exp_f32_e32 v144, v144
	v_exp_f32_e32 v128, v128
	v_exp_f32_e32 v129, v3
	v_add_f32_e32 v3, 1.0, v133
	v_rcp_f32_e32 v133, v3
	v_pk_add_f32 v[144:145], v[144:145], 1.0 op_sel_hi:[1,0]
	v_pk_add_f32 v[142:143], v[142:143], 1.0 op_sel_hi:[1,0]
	v_pk_add_f32 v[128:129], v[128:129], 1.0 op_sel_hi:[1,0]
	v_pk_add_f32 v[126:127], v[126:127], 1.0 op_sel_hi:[1,0]
	v_pk_mul_f32 v[142:143], v[142:143], v[146:147]
	v_pk_mul_f32 v[144:145], v[144:145], v[148:149]
	v_pk_mul_f32 v[126:127], v[126:127], v[130:131]
	v_pk_mul_f32 v[128:129], v[128:129], v[132:133]
	v_pk_mul_f32 v[76:77], v[76:77], v[144:145]
	v_pk_mul_f32 v[74:75], v[74:75], v[142:143]
	v_pk_mul_f32 v[72:73], v[72:73], v[128:129]
	v_pk_mul_f32 v[70:71], v[70:71], v[126:127]
	global_load_dwordx4 v[196:199], v[4:5], off offset:256
	global_load_dwordx4 v[236:239], v[186:187], off offset:256
	global_load_dwordx4 v[146:149], v[188:189], off offset:256
	global_load_dwordx4 v[142:145], v[190:191], off offset:256
	global_load_dwordx4 v[130:133], v[194:195], off offset:256
	global_load_dwordx4 v[126:129], v[200:201], off offset:256
	s_waitcnt vmcnt(11)
; __device__ __forceinline__ void unpack8(const u32x4 w, float (&v)[8]) { v[0] = bf_lo(w.x); v[1] = bf_hi(w.x); v[2] = bf_lo(w.y); v[3] = bf_hi(w.y); v[4] = bf_lo(w.z); v[5] = bf_hi(w.z); v[6] = bf_lo(w.w); v[7] = bf_hi(w.w); }
;     __device__ __forceinline__ void after(int te, f32x4 (&acc)[2][2][4][2], const Unit& u, int wr, int wc, int fr, int fq) const {
;     ...
;             for (int bj = 0; bj < 2; ++bj) { const int c = col0 + bj * HALF;
;                 const f32x4 s0 = *(const f32x4*)(gb + c), s1 = *(const f32x4*)(gb + c + 4), a0 = *(const f32x4*)(gb + D_MODEL + c), a1 = *(const f32x4*)(gb + D_MODEL + c + 4);
; #pragma unroll
;                 for (int ai = 0; ai < 2; ++ai) {
;                     u32x4 gs[4], ga[4];
; #pragma unroll
;                     for (int m = 0; m < 4; ++m) { const size_t r = (size_t)(row0 + ai * HALF + m * 16); gs[m] = *(const u32x4*)(proj + r * LDP + PGS + c); ga[m] = *(const u32x4*)(proj + r * LDP + PGA + c); }
; #pragma unroll
;                     for (int m = 0; m < 4; ++m) { float vs[8], va[8]; unpack8(gs[m], vs); unpack8(ga[m], va);
; #pragma unroll
;                         for (int e = 0; e < 4; ++e) {
;                             acc[ai][bj][m][0][e] *= (1.f + __expf(-(va[e] + a0[e]))) * __builtin_amdgcn_rcpf(1.f + __expf(-(vs[e] + s0[e])));
;                             acc[ai][bj][m][1][e] *= (1.f + __expf(-(va[4 + e] + a1[e]))) * __builtin_amdgcn_rcpf(1.f + __expf(-(vs[4 + e] + s1[e]))); } }
	v_lshlrev_b32_e32 v3, 16, v228
	v_lshlrev_b32_e32 v187, 16, v230
	v_and_b32_e32 v5, 0xffff0000, v228
	s_waitcnt vmcnt(10)
	v_lshlrev_b32_e32 v188, 16, v234
	v_and_b32_e32 v189, 0xffff0000, v230
	v_lshlrev_b32_e32 v192, 16, v229
	v_and_b32_e32 v191, 0xffff0000, v232
	v_lshlrev_b32_e32 v195, 16, v231
	v_lshlrev_b32_e32 v194, 16, v233
	v_and_b32_e32 v193, 0xffff0000, v229
	v_lshlrev_b32_e32 v203, 16, v235
	s_waitcnt vmcnt(8)
	v_add_f32_e32 v3, v158, v3
	v_mul_f32_e32 v3, 0xbfb8aa3b, v3
	v_exp_f32_e32 v3, v3
	v_add_f32_e32 v193, v161, v193
	v_mul_f32_e32 v193, 0xbfb8aa3b, v193
	v_lshlrev_b32_e32 v4, 16, v232
	v_add_f32_e32 v3, 1.0, v3
	v_rcp_f32_e32 v186, v3
	v_add_f32_e32 v3, v150, v187
	v_mul_f32_e32 v3, 0xbfb8aa3b, v3
	v_exp_f32_e32 v3, v3
	s_waitcnt vmcnt(7)
	v_add_f32_e32 v187, v154, v188
	v_mul_f32_e32 v187, 0xbfb8aa3b, v187
	v_exp_f32_e32 v188, v187
	v_add_f32_e32 v3, 1.0, v3
	v_rcp_f32_e32 v190, v3
	v_add_f32_e32 v3, v159, v5
	v_mul_f32_e32 v3, 0xbfb8aa3b, v3
	v_exp_f32_e32 v3, v3
	s_waitcnt vmcnt(6)
	v_add_f32_e32 v5, v163, v191
	v_and_b32_e32 v202, 0xffff0000, v233
	v_and_b32_e32 v200, 0xffff0000, v234
	v_add_f32_e32 v3, 1.0, v3
	v_rcp_f32_e32 v187, v3
	v_add_f32_e32 v3, v151, v189
	v_mul_f32_e32 v3, 0xbfb8aa3b, v3
	v_exp_f32_e32 v3, v3
	v_add_f32_e32 v4, v162, v4
	v_add_f32_e32 v189, v155, v200
	v_mul_f32_e32 v4, 0xbfb8aa3b, v4
	v_add_f32_e32 v3, 1.0, v3
	v_rcp_f32_e32 v191, v3
	v_add_f32_e32 v3, v160, v192
	v_mul_f32_e32 v3, 0xbfb8aa3b, v3
	v_exp_f32_e32 v3, v3
	v_add_f32_e32 v192, v164, v194
	v_mul_f32_e32 v5, 0xbfb8aa3b, v5
	v_mul_f32_e32 v192, 0xbfb8aa3b, v192
	v_add_f32_e32 v3, 1.0, v3
	v_rcp_f32_e32 v194, v3
	v_add_f32_e32 v3, v152, v195
	v_mul_f32_e32 v3, 0xbfb8aa3b, v3
	v_exp_f32_e32 v3, v3
	v_add_f32_e32 v195, v156, v203
	v_exp_f32_e32 v203, v193
	v_mul_f32_e32 v195, 0xbfb8aa3b, v195
	v_exp_f32_e32 v200, v195
	v_add_f32_e32 v195, v165, v202
	v_add_f32_e32 v3, 1.0, v3
	v_mul_f32_e32 v193, 0xbfb8aa3b, v195
	v_exp_f32_e32 v4, v4
	v_exp_f32_e32 v5, v5
	v_exp_f32_e32 v192, v192
	v_exp_f32_e32 v193, v193
	v_rcp_f32_e32 v202, v3
	v_add_f32_e32 v3, 1.0, v203
	v_rcp_f32_e32 v195, v3
	v_pk_add_f32 v[192:193], v[192:193], 1.0 op_sel_hi:[1,0]
	v_pk_add_f32 v[4:5], v[4:5], 1.0 op_sel_hi:[1,0]
	v_and_b32_e32 v201, 0xffff0000, v231
	v_pk_mul_f32 v[4:5], v[4:5], v[186:187]
	v_pk_mul_f32 v[186:187], v[192:193], v[194:195]
	v_and_b32_e32 v225, 0xffff0000, v235
	v_pk_mul_f32 v[68:69], v[68:69], v[186:187]
	v_add_f32_e32 v186, v153, v201
	v_mul_f32_e32 v186, 0xbfb8aa3b, v186
	v_exp_f32_e32 v186, v186
	v_add_f32_e32 v3, v157, v225
	v_mul_f32_e32 v3, 0xbfb8aa3b, v3
	v_exp_f32_e32 v201, v3
	v_add_f32_e32 v3, 1.0, v186
	v_mul_f32_e32 v189, 0xbfb8aa3b, v189
	v_rcp_f32_e32 v203, v3
	s_waitcnt vmcnt(5)
	v_lshlrev_b32_e32 v3, 16, v196
	v_exp_f32_e32 v189, v189
	v_add_f32_e32 v3, v158, v3
	v_mul_f32_e32 v3, 0xbfb8aa3b, v3
	v_exp_f32_e32 v3, v3
	v_pk_add_f32 v[186:187], v[188:189], 1.0 op_sel_hi:[1,0]
	v_pk_mul_f32 v[66:67], v[66:67], v[4:5]
	v_pk_mul_f32 v[186:187], v[186:187], v[190:191]
	v_add_f32_e32 v3, 1.0, v3
	v_pk_mul_f32 v[62:63], v[62:63], v[186:187]
	v_lshlrev_b32_e32 v187, 16, v198
	v_rcp_f32_e32 v186, v3
	v_add_f32_e32 v3, v150, v187
	v_mul_f32_e32 v3, 0xbfb8aa3b, v3
	v_exp_f32_e32 v3, v3
	v_pk_add_f32 v[4:5], v[200:201], 1.0 op_sel_hi:[1,0]
	s_waitcnt vmcnt(4)
	v_lshlrev_b32_e32 v188, 16, v238
	v_pk_mul_f32 v[4:5], v[4:5], v[202:203]
	v_add_f32_e32 v3, 1.0, v3
	v_pk_mul_f32 v[64:65], v[64:65], v[4:5]
	v_and_b32_e32 v5, 0xffff0000, v196
	v_rcp_f32_e32 v190, v3
	v_add_f32_e32 v3, v159, v5
	v_mul_f32_e32 v3, 0xbfb8aa3b, v3
	v_exp_f32_e32 v3, v3
	v_add_f32_e32 v187, v154, v188
	v_and_b32_e32 v189, 0xffff0000, v198
	v_mul_f32_e32 v187, 0xbfb8aa3b, v187
	v_add_f32_e32 v3, 1.0, v3
	v_exp_f32_e32 v188, v187
	v_rcp_f32_e32 v187, v3
	v_add_f32_e32 v3, v151, v189
	v_mul_f32_e32 v3, 0xbfb8aa3b, v3
	v_exp_f32_e32 v3, v3
	v_lshlrev_b32_e32 v192, 16, v197
	v_and_b32_e32 v191, 0xffff0000, v236
	v_add_f32_e32 v5, v163, v191
	v_add_f32_e32 v3, 1.0, v3
	v_rcp_f32_e32 v191, v3
	v_add_f32_e32 v3, v160, v192
	v_mul_f32_e32 v3, 0xbfb8aa3b, v3
	v_exp_f32_e32 v3, v3
	v_lshlrev_b32_e32 v195, 16, v199
	v_lshlrev_b32_e32 v194, 16, v237
	v_and_b32_e32 v193, 0xffff0000, v197
	v_add_f32_e32 v3, 1.0, v3
	v_add_f32_e32 v192, v164, v194
	v_rcp_f32_e32 v194, v3
	v_add_f32_e32 v3, v152, v195
	v_mul_f32_e32 v3, 0xbfb8aa3b, v3
	v_add_f32_e32 v193, v161, v193
	v_and_b32_e32 v197, 0xffff0000, v199
	v_lshlrev_b32_e32 v199, 16, v239
	v_exp_f32_e32 v3, v3
	v_mul_f32_e32 v193, 0xbfb8aa3b, v193
	v_add_f32_e32 v195, v156, v199
	v_exp_f32_e32 v199, v193
	v_lshlrev_b32_e32 v4, 16, v236
	v_and_b32_e32 v198, 0xffff0000, v237
	v_and_b32_e32 v196, 0xffff0000, v238
	v_mul_f32_e32 v195, 0xbfb8aa3b, v195
	v_add_f32_e32 v4, v162, v4
	v_add_f32_e32 v189, v155, v196
	v_exp_f32_e32 v196, v195
	v_add_f32_e32 v195, v165, v198
	v_mul_f32_e32 v4, 0xbfb8aa3b, v4
	v_mul_f32_e32 v5, 0xbfb8aa3b, v5
	v_mul_f32_e32 v192, 0xbfb8aa3b, v192
	v_add_f32_e32 v3, 1.0, v3
	v_mul_f32_e32 v193, 0xbfb8aa3b, v195
	v_exp_f32_e32 v4, v4
	v_exp_f32_e32 v5, v5
	v_exp_f32_e32 v192, v192
	v_exp_f32_e32 v193, v193
	v_rcp_f32_e32 v198, v3
	v_add_f32_e32 v3, 1.0, v199
	v_rcp_f32_e32 v195, v3
	v_pk_add_f32 v[192:193], v[192:193], 1.0 op_sel_hi:[1,0]
	v_pk_add_f32 v[4:5], v[4:5], 1.0 op_sel_hi:[1,0]
	v_and_b32_e32 v200, 0xffff0000, v239
	v_pk_mul_f32 v[4:5], v[4:5], v[186:187]
	v_pk_mul_f32 v[186:187], v[192:193], v[194:195]
	v_add_f32_e32 v3, v157, v200
	v_pk_mul_f32 v[60:61], v[60:61], v[186:187]
	v_add_f32_e32 v186, v153, v197
	v_mul_f32_e32 v186, 0xbfb8aa3b, v186
	v_exp_f32_e32 v186, v186
	v_mul_f32_e32 v3, 0xbfb8aa3b, v3
	v_exp_f32_e32 v197, v3
	v_mul_f32_e32 v189, 0xbfb8aa3b, v189
	v_add_f32_e32 v3, 1.0, v186
	v_rcp_f32_e32 v199, v3
	s_waitcnt vmcnt(3)
; __device__ __forceinline__ void unpack8(const u32x4 w, float (&v)[8]) { v[0] = bf_lo(w.x); v[1] = bf_hi(w.x); v[2] = bf_lo(w.y); v[3] = bf_hi(w.y); v[4] = bf_lo(w.z); v[5] = bf_hi(w.z); v[6] = bf_lo(w.w); v[7] = bf_hi(w.w); }
;     __device__ __forceinline__ void after(int te, f32x4 (&acc)[2][2][4][2], const Unit& u, int wr, int wc, int fr, int fq) const {
;     ...
;             for (int bj = 0; bj < 2; ++bj) { const int c = col0 + bj * HALF;
;                 const f32x4 s0 = *(const f32x4*)(gb + c), s1 = *(const f32x4*)(gb + c + 4), a0 = *(const f32x4*)(gb + D_MODEL + c), a1 = *(const f32x4*)(gb + D_MODEL + c + 4);
; #pragma unroll
;                 for (int ai = 0; ai < 2; ++ai) {
;                     u32x4 gs[4], ga[4];
; #pragma unroll
;                     for (int m = 0; m < 4; ++m) { const size_t r = (size_t)(row0 + ai * HALF + m * 16); gs[m] = *(const u32x4*)(proj + r * LDP + PGS + c); ga[m] = *(const u32x4*)(proj + r * LDP + PGA + c); }
; #pragma unroll
;                     for (int m = 0; m < 4; ++m) { float vs[8], va[8]; unpack8(gs[m], vs); unpack8(ga[m], va);
; #pragma unroll
;                         for (int e = 0; e < 4; ++e) {
;                             acc[ai][bj][m][0][e] *= (1.f + __expf(-(va[e] + a0[e]))) * __builtin_amdgcn_rcpf(1.f + __expf(-(vs[e] + s0[e])));
;                             acc[ai][bj][m][1][e] *= (1.f + __expf(-(va[4 + e] + a1[e]))) * __builtin_amdgcn_rcpf(1.f + __expf(-(vs[4 + e] + s1[e]))); } }
	v_lshlrev_b32_e32 v3, 16, v146
	v_add_f32_e32 v3, v158, v3
	v_exp_f32_e32 v189, v189
	v_mul_f32_e32 v3, 0xbfb8aa3b, v3
	v_exp_f32_e32 v3, v3
	v_pk_mul_f32 v[58:59], v[58:59], v[4:5]
	v_pk_add_f32 v[4:5], v[196:197], 1.0 op_sel_hi:[1,0]
	v_pk_add_f32 v[186:187], v[188:189], 1.0 op_sel_hi:[1,0]
	v_pk_mul_f32 v[4:5], v[4:5], v[198:199]
	v_pk_mul_f32 v[186:187], v[186:187], v[190:191]
	v_pk_mul_f32 v[56:57], v[56:57], v[4:5]
	v_and_b32_e32 v5, 0xffff0000, v146
	v_lshlrev_b32_e32 v146, 16, v148
	v_add_f32_e32 v3, 1.0, v3
	v_pk_mul_f32 v[54:55], v[54:55], v[186:187]
	v_lshlrev_b32_e32 v186, 16, v147
	v_and_b32_e32 v187, 0xffff0000, v147
	v_and_b32_e32 v147, 0xffff0000, v148
	s_waitcnt vmcnt(2)
	v_lshlrev_b32_e32 v4, 16, v142
	v_and_b32_e32 v148, 0xffff0000, v142
	v_rcp_f32_e32 v142, v3
	v_add_f32_e32 v3, v150, v146
	v_mul_f32_e32 v3, 0xbfb8aa3b, v3
	v_exp_f32_e32 v3, v3
	v_lshlrev_b32_e32 v188, 16, v149
	v_and_b32_e32 v189, 0xffff0000, v149
	v_lshlrev_b32_e32 v149, 16, v143
	v_add_f32_e32 v3, 1.0, v3
	v_rcp_f32_e32 v146, v3
	v_add_f32_e32 v3, v159, v5
	v_mul_f32_e32 v3, 0xbfb8aa3b, v3
	v_exp_f32_e32 v3, v3
	v_and_b32_e32 v190, 0xffff0000, v143
	v_lshlrev_b32_e32 v143, 16, v144
	v_add_f32_e32 v143, v154, v143
	v_mul_f32_e32 v143, 0xbfb8aa3b, v143
	v_add_f32_e32 v3, 1.0, v3
	v_and_b32_e32 v191, 0xffff0000, v144
	v_exp_f32_e32 v144, v143
	v_rcp_f32_e32 v143, v3
	v_add_f32_e32 v3, v151, v147
	v_mul_f32_e32 v3, 0xbfb8aa3b, v3
	v_exp_f32_e32 v3, v3
	v_add_f32_e32 v187, v161, v187
	v_lshlrev_b32_e32 v192, 16, v145
	v_mul_f32_e32 v187, 0xbfb8aa3b, v187
	v_add_f32_e32 v3, 1.0, v3
	v_rcp_f32_e32 v147, v3
	v_add_f32_e32 v3, v160, v186
	v_mul_f32_e32 v3, 0xbfb8aa3b, v3
	v_exp_f32_e32 v3, v3
	v_add_f32_e32 v5, v163, v148
	v_add_f32_e32 v148, v164, v149
	v_add_f32_e32 v149, v156, v192
	v_add_f32_e32 v3, 1.0, v3
	v_rcp_f32_e32 v186, v3
	v_add_f32_e32 v3, v152, v188
	v_mul_f32_e32 v3, 0xbfb8aa3b, v3
	v_exp_f32_e32 v3, v3
	v_exp_f32_e32 v187, v187
	v_mul_f32_e32 v149, 0xbfb8aa3b, v149
	v_add_f32_e32 v4, v162, v4
	v_exp_f32_e32 v188, v149
	v_add_f32_e32 v149, v165, v190
	v_mul_f32_e32 v4, 0xbfb8aa3b, v4
	v_mul_f32_e32 v5, 0xbfb8aa3b, v5
	v_mul_f32_e32 v148, 0xbfb8aa3b, v148
	v_add_f32_e32 v3, 1.0, v3
	v_mul_f32_e32 v149, 0xbfb8aa3b, v149
	v_exp_f32_e32 v4, v4
	v_exp_f32_e32 v5, v5
	v_exp_f32_e32 v148, v148
	v_exp_f32_e32 v149, v149
	v_rcp_f32_e32 v190, v3
	v_add_f32_e32 v3, 1.0, v187
	v_rcp_f32_e32 v187, v3
	v_pk_add_f32 v[148:149], v[148:149], 1.0 op_sel_hi:[1,0]
	v_pk_add_f32 v[4:5], v[4:5], 1.0 op_sel_hi:[1,0]
	v_and_b32_e32 v193, 0xffff0000, v145
	v_pk_mul_f32 v[4:5], v[4:5], v[142:143]
	v_pk_mul_f32 v[142:143], v[148:149], v[186:187]
	v_add_f32_e32 v3, v157, v193
	v_pk_mul_f32 v[52:53], v[52:53], v[142:143]
	v_add_f32_e32 v142, v153, v189
	v_mul_f32_e32 v142, 0xbfb8aa3b, v142
	v_mul_f32_e32 v3, 0xbfb8aa3b, v3
	v_exp_f32_e32 v142, v142
	v_exp_f32_e32 v189, v3
	v_pk_mul_f32 v[50:51], v[50:51], v[4:5]
	v_add_f32_e32 v3, 1.0, v142
	v_pk_add_f32 v[4:5], v[188:189], 1.0 op_sel_hi:[1,0]
	global_load_dwordx4 v[186:189], v[218:219], off offset:256
	v_add_f32_e32 v145, v155, v191
	v_rcp_f32_e32 v191, v3
	s_waitcnt vmcnt(2)
	v_lshlrev_b32_e32 v3, 16, v130
	v_mul_f32_e32 v145, 0xbfb8aa3b, v145
	v_add_f32_e32 v3, v158, v3
	v_exp_f32_e32 v145, v145
	v_mul_f32_e32 v3, 0xbfb8aa3b, v3
	v_exp_f32_e32 v3, v3
	v_pk_mul_f32 v[4:5], v[4:5], v[190:191]
	v_pk_add_f32 v[142:143], v[144:145], 1.0 op_sel_hi:[1,0]
	v_pk_mul_f32 v[48:49], v[48:49], v[4:5]
	v_pk_mul_f32 v[142:143], v[142:143], v[146:147]
	v_and_b32_e32 v5, 0xffff0000, v130
	v_lshlrev_b32_e32 v130, 16, v132
	v_add_f32_e32 v3, 1.0, v3
	v_pk_mul_f32 v[46:47], v[46:47], v[142:143]
	v_lshlrev_b32_e32 v142, 16, v131
	v_and_b32_e32 v143, 0xffff0000, v131
	v_and_b32_e32 v131, 0xffff0000, v132
	s_waitcnt vmcnt(1)
	v_lshlrev_b32_e32 v4, 16, v126
	v_and_b32_e32 v132, 0xffff0000, v126
	v_rcp_f32_e32 v126, v3
	v_add_f32_e32 v3, v150, v130
	v_mul_f32_e32 v3, 0xbfb8aa3b, v3
	v_exp_f32_e32 v3, v3
	global_load_dwordx4 v[190:193], v[216:217], off offset:256
	v_lshlrev_b32_e32 v144, 16, v133
	v_and_b32_e32 v145, 0xffff0000, v133
	v_add_f32_e32 v3, 1.0, v3
	v_rcp_f32_e32 v130, v3
	v_add_f32_e32 v3, v159, v5
	v_mul_f32_e32 v3, 0xbfb8aa3b, v3
	v_exp_f32_e32 v3, v3
	v_lshlrev_b32_e32 v133, 16, v127
	v_and_b32_e32 v146, 0xffff0000, v127
	v_lshlrev_b32_e32 v127, 16, v128
	v_add_f32_e32 v127, v154, v127
	v_mul_f32_e32 v127, 0xbfb8aa3b, v127
	v_add_f32_e32 v3, 1.0, v3
	v_and_b32_e32 v147, 0xffff0000, v128
	v_exp_f32_e32 v128, v127
	v_rcp_f32_e32 v127, v3
	v_add_f32_e32 v3, v151, v131
	v_mul_f32_e32 v3, 0xbfb8aa3b, v3
	v_exp_f32_e32 v3, v3
	v_add_f32_e32 v143, v161, v143
	v_lshlrev_b32_e32 v148, 16, v129
	v_mul_f32_e32 v143, 0xbfb8aa3b, v143
	v_add_f32_e32 v3, 1.0, v3
	v_rcp_f32_e32 v131, v3
	v_add_f32_e32 v3, v160, v142
	v_mul_f32_e32 v3, 0xbfb8aa3b, v3
	v_exp_f32_e32 v3, v3
	v_add_f32_e32 v5, v163, v132
	v_add_f32_e32 v132, v164, v133
	v_add_f32_e32 v133, v156, v148
	v_add_f32_e32 v3, 1.0, v3
	v_rcp_f32_e32 v142, v3
	v_add_f32_e32 v3, v152, v144
	v_mul_f32_e32 v3, 0xbfb8aa3b, v3
	v_exp_f32_e32 v3, v3
	v_exp_f32_e32 v143, v143
	v_mul_f32_e32 v133, 0xbfb8aa3b, v133
	v_add_f32_e32 v4, v162, v4
	v_exp_f32_e32 v144, v133
	v_add_f32_e32 v133, v165, v146
	v_mul_f32_e32 v4, 0xbfb8aa3b, v4
	v_mul_f32_e32 v5, 0xbfb8aa3b, v5
	v_mul_f32_e32 v132, 0xbfb8aa3b, v132
	v_add_f32_e32 v3, 1.0, v3
	v_mul_f32_e32 v133, 0xbfb8aa3b, v133
	v_exp_f32_e32 v4, v4
	v_exp_f32_e32 v5, v5
	v_exp_f32_e32 v132, v132
	v_exp_f32_e32 v133, v133
	v_rcp_f32_e32 v146, v3
	v_add_f32_e32 v3, 1.0, v143
	v_rcp_f32_e32 v143, v3
	v_pk_add_f32 v[132:133], v[132:133], 1.0 op_sel_hi:[1,0]
	v_pk_add_f32 v[4:5], v[4:5], 1.0 op_sel_hi:[1,0]
	v_and_b32_e32 v149, 0xffff0000, v129
	v_pk_mul_f32 v[4:5], v[4:5], v[126:127]
	v_pk_mul_f32 v[126:127], v[132:133], v[142:143]
	v_add_f32_e32 v129, v155, v147
	v_pk_mul_f32 v[44:45], v[44:45], v[126:127]
	v_add_f32_e32 v126, v153, v145
	v_mul_f32_e32 v126, 0xbfb8aa3b, v126
	v_exp_f32_e32 v126, v126
	v_mul_f32_e32 v129, 0xbfb8aa3b, v129
	v_add_f32_e32 v3, v157, v149
	v_exp_f32_e32 v129, v129
	v_mul_f32_e32 v3, 0xbfb8aa3b, v3
	v_exp_f32_e32 v145, v3
	v_add_f32_e32 v3, 1.0, v126
	v_rcp_f32_e32 v147, v3
	v_pk_add_f32 v[126:127], v[128:129], 1.0 op_sel_hi:[1,0]
	v_pk_mul_f32 v[42:43], v[42:43], v[4:5]
	v_pk_add_f32 v[4:5], v[144:145], 1.0 op_sel_hi:[1,0]
	v_pk_mul_f32 v[126:127], v[126:127], v[130:131]
	v_pk_mul_f32 v[4:5], v[4:5], v[146:147]
	v_pk_mul_f32 v[38:39], v[38:39], v[126:127]
	global_load_dwordx4 v[194:197], v[204:205], off offset:256
	global_load_dwordx4 v[198:201], v[206:207], off offset:256
	global_load_dwordx4 v[146:149], v[208:209], off offset:256
	global_load_dwordx4 v[142:145], v[210:211], off offset:256
	global_load_dwordx4 v[130:133], v[212:213], off offset:256
	global_load_dwordx4 v[126:129], v[214:215], off offset:256
	s_waitcnt vmcnt(7)
; __device__ __forceinline__ void unpack8(const u32x4 w, float (&v)[8]) { v[0] = bf_lo(w.x); v[1] = bf_hi(w.x); v[2] = bf_lo(w.y); v[3] = bf_hi(w.y); v[4] = bf_lo(w.z); v[5] = bf_hi(w.z); v[6] = bf_lo(w.w); v[7] = bf_hi(w.w); }
;     __device__ __forceinline__ void after(int te, f32x4 (&acc)[2][2][4][2], const Unit& u, int wr, int wc, int fr, int fq) const {
;     ...
;             for (int bj = 0; bj < 2; ++bj) { const int c = col0 + bj * HALF;
;                 const f32x4 s0 = *(const f32x4*)(gb + c), s1 = *(const f32x4*)(gb + c + 4), a0 = *(const f32x4*)(gb + D_MODEL + c), a1 = *(const f32x4*)(gb + D_MODEL + c + 4);
; #pragma unroll
;                 for (int ai = 0; ai < 2; ++ai) {
;                     u32x4 gs[4], ga[4];
; #pragma unroll
;                     for (int m = 0; m < 4; ++m) { const size_t r = (size_t)(row0 + ai * HALF + m * 16); gs[m] = *(const u32x4*)(proj + r * LDP + PGS + c); ga[m] = *(const u32x4*)(proj + r * LDP + PGA + c); }
; #pragma unroll
;                     for (int m = 0; m < 4; ++m) { float vs[8], va[8]; unpack8(gs[m], vs); unpack8(ga[m], va);
; #pragma unroll
;                         for (int e = 0; e < 4; ++e) {
;                             acc[ai][bj][m][0][e] *= (1.f + __expf(-(va[e] + a0[e]))) * __builtin_amdgcn_rcpf(1.f + __expf(-(vs[e] + s0[e])));
;                             acc[ai][bj][m][1][e] *= (1.f + __expf(-(va[4 + e] + a1[e]))) * __builtin_amdgcn_rcpf(1.f + __expf(-(vs[4 + e] + s1[e]))); } }
	v_lshlrev_b32_e32 v3, 16, v186
	v_add_f32_e32 v3, v158, v3
	v_mul_f32_e32 v3, 0xbfb8aa3b, v3
	v_exp_f32_e32 v3, v3
	v_lshlrev_b32_e32 v202, 16, v187
	v_and_b32_e32 v203, 0xffff0000, v187
	v_lshlrev_b32_e32 v187, 16, v188
	v_add_f32_e32 v3, 1.0, v3
	v_pk_mul_f32 v[40:41], v[40:41], v[4:5]
	v_and_b32_e32 v5, 0xffff0000, v186
	v_rcp_f32_e32 v186, v3
	v_add_f32_e32 v3, v150, v187
	v_mul_f32_e32 v3, 0xbfb8aa3b, v3
	v_exp_f32_e32 v3, v3
	v_lshlrev_b32_e32 v205, 16, v189
	v_and_b32_e32 v207, 0xffff0000, v189
	s_waitcnt vmcnt(6)
	v_lshlrev_b32_e32 v4, 16, v190
	v_add_f32_e32 v3, 1.0, v3
	v_and_b32_e32 v189, 0xffff0000, v190
	v_rcp_f32_e32 v190, v3
	v_add_f32_e32 v3, v159, v5
	v_mul_f32_e32 v3, 0xbfb8aa3b, v3
	v_exp_f32_e32 v3, v3
	v_and_b32_e32 v204, 0xffff0000, v188
	v_lshlrev_b32_e32 v188, 16, v192
	v_add_f32_e32 v187, v154, v188
	v_mul_f32_e32 v187, 0xbfb8aa3b, v187
	v_add_f32_e32 v3, 1.0, v3
	v_exp_f32_e32 v188, v187
	v_rcp_f32_e32 v187, v3
	v_add_f32_e32 v3, v151, v204
	v_mul_f32_e32 v3, 0xbfb8aa3b, v3
	v_exp_f32_e32 v3, v3
	v_lshlrev_b32_e32 v206, 16, v191
	v_and_b32_e32 v208, 0xffff0000, v191
	v_and_b32_e32 v191, 0xffff0000, v192
	v_add_f32_e32 v3, 1.0, v3
	v_add_f32_e32 v5, v163, v189
	v_add_f32_e32 v189, v155, v191
	v_rcp_f32_e32 v191, v3
	v_add_f32_e32 v3, v160, v202
	v_mul_f32_e32 v3, 0xbfb8aa3b, v3
	v_exp_f32_e32 v3, v3
	v_add_f32_e32 v203, v161, v203
	v_lshlrev_b32_e32 v209, 16, v193
	v_mul_f32_e32 v203, 0xbfb8aa3b, v203
	v_add_f32_e32 v3, 1.0, v3
	v_rcp_f32_e32 v202, v3
	v_add_f32_e32 v3, v152, v205
	v_mul_f32_e32 v3, 0xbfb8aa3b, v3
	v_exp_f32_e32 v3, v3
	v_and_b32_e32 v210, 0xffff0000, v193
	v_add_f32_e32 v193, v156, v209
	v_exp_f32_e32 v203, v203
	v_mul_f32_e32 v193, 0xbfb8aa3b, v193
	v_add_f32_e32 v4, v162, v4
	v_add_f32_e32 v192, v164, v206
	v_exp_f32_e32 v204, v193
	v_add_f32_e32 v193, v165, v208
	v_mul_f32_e32 v4, 0xbfb8aa3b, v4
	v_mul_f32_e32 v5, 0xbfb8aa3b, v5
	v_mul_f32_e32 v192, 0xbfb8aa3b, v192
	v_add_f32_e32 v3, 1.0, v3
	v_mul_f32_e32 v193, 0xbfb8aa3b, v193
	v_exp_f32_e32 v4, v4
	v_exp_f32_e32 v5, v5
	v_exp_f32_e32 v192, v192
	v_exp_f32_e32 v193, v193
	v_rcp_f32_e32 v206, v3
	v_add_f32_e32 v3, 1.0, v203
	v_rcp_f32_e32 v203, v3
	v_pk_add_f32 v[192:193], v[192:193], 1.0 op_sel_hi:[1,0]
	v_pk_add_f32 v[4:5], v[4:5], 1.0 op_sel_hi:[1,0]
	v_add_f32_e32 v3, v157, v210
	v_pk_mul_f32 v[4:5], v[4:5], v[186:187]
	v_pk_mul_f32 v[186:187], v[192:193], v[202:203]
	v_mul_f32_e32 v3, 0xbfb8aa3b, v3
	v_pk_mul_f32 v[36:37], v[36:37], v[186:187]
	v_add_f32_e32 v186, v153, v207
	v_mul_f32_e32 v186, 0xbfb8aa3b, v186
	v_exp_f32_e32 v186, v186
	v_exp_f32_e32 v205, v3
	v_mul_f32_e32 v189, 0xbfb8aa3b, v189
	v_exp_f32_e32 v189, v189
	v_add_f32_e32 v3, 1.0, v186
	v_rcp_f32_e32 v207, v3
	s_waitcnt vmcnt(5)
	v_lshlrev_b32_e32 v3, 16, v194
	v_add_f32_e32 v3, v158, v3
	v_mul_f32_e32 v3, 0xbfb8aa3b, v3
	v_exp_f32_e32 v3, v3
	v_pk_add_f32 v[186:187], v[188:189], 1.0 op_sel_hi:[1,0]
	v_pk_mul_f32 v[34:35], v[34:35], v[4:5]
	v_pk_mul_f32 v[186:187], v[186:187], v[190:191]
	v_add_f32_e32 v3, 1.0, v3
	v_pk_mul_f32 v[30:31], v[30:31], v[186:187]
	v_lshlrev_b32_e32 v187, 16, v196
	v_rcp_f32_e32 v186, v3
	v_add_f32_e32 v3, v150, v187
	v_mul_f32_e32 v3, 0xbfb8aa3b, v3
	v_exp_f32_e32 v3, v3
	v_pk_add_f32 v[4:5], v[204:205], 1.0 op_sel_hi:[1,0]
	s_waitcnt vmcnt(4)
	v_lshlrev_b32_e32 v188, 16, v200
	v_pk_mul_f32 v[4:5], v[4:5], v[206:207]
	v_add_f32_e32 v3, 1.0, v3
	v_pk_mul_f32 v[32:33], v[32:33], v[4:5]
	v_and_b32_e32 v5, 0xffff0000, v194
	v_rcp_f32_e32 v190, v3
	v_add_f32_e32 v3, v159, v5
	v_mul_f32_e32 v3, 0xbfb8aa3b, v3
	v_exp_f32_e32 v3, v3
	v_add_f32_e32 v187, v154, v188
	v_and_b32_e32 v189, 0xffff0000, v196
	v_mul_f32_e32 v187, 0xbfb8aa3b, v187
	v_add_f32_e32 v3, 1.0, v3
	v_exp_f32_e32 v188, v187
	v_rcp_f32_e32 v187, v3
	v_add_f32_e32 v3, v151, v189
	v_mul_f32_e32 v3, 0xbfb8aa3b, v3
	v_exp_f32_e32 v3, v3
	v_lshlrev_b32_e32 v192, 16, v195
	v_and_b32_e32 v191, 0xffff0000, v198
	v_add_f32_e32 v5, v163, v191
	v_add_f32_e32 v3, 1.0, v3
	v_rcp_f32_e32 v191, v3
	v_add_f32_e32 v3, v160, v192
	v_mul_f32_e32 v3, 0xbfb8aa3b, v3
	v_exp_f32_e32 v3, v3
	v_and_b32_e32 v193, 0xffff0000, v195
	v_lshlrev_b32_e32 v195, 16, v197
	v_lshlrev_b32_e32 v194, 16, v199
	v_add_f32_e32 v3, 1.0, v3
	v_add_f32_e32 v192, v164, v194
	v_rcp_f32_e32 v194, v3
	v_add_f32_e32 v3, v152, v195
	v_mul_f32_e32 v3, 0xbfb8aa3b, v3
	v_add_f32_e32 v193, v161, v193
	v_lshlrev_b32_e32 v4, 16, v198
	v_and_b32_e32 v198, 0xffff0000, v199
	v_lshlrev_b32_e32 v199, 16, v201
	v_exp_f32_e32 v3, v3
	v_mul_f32_e32 v193, 0xbfb8aa3b, v193
	v_add_f32_e32 v195, v156, v199
	v_exp_f32_e32 v199, v193
	v_and_b32_e32 v196, 0xffff0000, v200
	v_mul_f32_e32 v195, 0xbfb8aa3b, v195
	v_add_f32_e32 v4, v162, v4
	v_add_f32_e32 v189, v155, v196
	v_exp_f32_e32 v196, v195
	v_add_f32_e32 v195, v165, v198
	v_mul_f32_e32 v4, 0xbfb8aa3b, v4
	v_mul_f32_e32 v5, 0xbfb8aa3b, v5
	v_mul_f32_e32 v192, 0xbfb8aa3b, v192
	v_add_f32_e32 v3, 1.0, v3
	v_mul_f32_e32 v193, 0xbfb8aa3b, v195
	v_exp_f32_e32 v4, v4
	v_exp_f32_e32 v5, v5
	v_exp_f32_e32 v192, v192
	v_exp_f32_e32 v193, v193
	v_rcp_f32_e32 v198, v3
	v_add_f32_e32 v3, 1.0, v199
	v_rcp_f32_e32 v195, v3
	v_pk_add_f32 v[192:193], v[192:193], 1.0 op_sel_hi:[1,0]
	v_pk_add_f32 v[4:5], v[4:5], 1.0 op_sel_hi:[1,0]
	v_and_b32_e32 v197, 0xffff0000, v197
	v_pk_mul_f32 v[4:5], v[4:5], v[186:187]
	v_pk_mul_f32 v[186:187], v[192:193], v[194:195]
	v_and_b32_e32 v200, 0xffff0000, v201
	v_pk_mul_f32 v[28:29], v[28:29], v[186:187]
	v_add_f32_e32 v186, v153, v197
	v_mul_f32_e32 v186, 0xbfb8aa3b, v186
	v_exp_f32_e32 v186, v186
	v_add_f32_e32 v3, v157, v200
	v_mul_f32_e32 v3, 0xbfb8aa3b, v3
	v_exp_f32_e32 v197, v3
	v_add_f32_e32 v3, 1.0, v186
	v_rcp_f32_e32 v199, v3
	s_waitcnt vmcnt(3)
; __device__ __forceinline__ void unpack8(const u32x4 w, float (&v)[8]) { v[0] = bf_lo(w.x); v[1] = bf_hi(w.x); v[2] = bf_lo(w.y); v[3] = bf_hi(w.y); v[4] = bf_lo(w.z); v[5] = bf_hi(w.z); v[6] = bf_lo(w.w); v[7] = bf_hi(w.w); }
;     __device__ __forceinline__ void after(int te, f32x4 (&acc)[2][2][4][2], const Unit& u, int wr, int wc, int fr, int fq) const {
;     ...
;             for (int bj = 0; bj < 2; ++bj) { const int c = col0 + bj * HALF;
;                 const f32x4 s0 = *(const f32x4*)(gb + c), s1 = *(const f32x4*)(gb + c + 4), a0 = *(const f32x4*)(gb + D_MODEL + c), a1 = *(const f32x4*)(gb + D_MODEL + c + 4);
; #pragma unroll
;                 for (int ai = 0; ai < 2; ++ai) {
;                     u32x4 gs[4], ga[4];
; #pragma unroll
;                     for (int m = 0; m < 4; ++m) { const size_t r = (size_t)(row0 + ai * HALF + m * 16); gs[m] = *(const u32x4*)(proj + r * LDP + PGS + c); ga[m] = *(const u32x4*)(proj + r * LDP + PGA + c); }
; #pragma unroll
;                     for (int m = 0; m < 4; ++m) { float vs[8], va[8]; unpack8(gs[m], vs); unpack8(ga[m], va);
; #pragma unroll
;                         for (int e = 0; e < 4; ++e) {
;                             acc[ai][bj][m][0][e] *= (1.f + __expf(-(va[e] + a0[e]))) * __builtin_amdgcn_rcpf(1.f + __expf(-(vs[e] + s0[e])));
;                             acc[ai][bj][m][1][e] *= (1.f + __expf(-(va[4 + e] + a1[e]))) * __builtin_amdgcn_rcpf(1.f + __expf(-(vs[4 + e] + s1[e]))); } }
	v_lshlrev_b32_e32 v3, 16, v146
	v_mul_f32_e32 v189, 0xbfb8aa3b, v189
	v_add_f32_e32 v3, v158, v3
	v_exp_f32_e32 v189, v189
	v_mul_f32_e32 v3, 0xbfb8aa3b, v3
	v_exp_f32_e32 v3, v3
	v_pk_mul_f32 v[26:27], v[26:27], v[4:5]
	v_pk_add_f32 v[4:5], v[196:197], 1.0 op_sel_hi:[1,0]
	v_pk_add_f32 v[186:187], v[188:189], 1.0 op_sel_hi:[1,0]
	v_pk_mul_f32 v[4:5], v[4:5], v[198:199]
	v_pk_mul_f32 v[186:187], v[186:187], v[190:191]
	v_pk_mul_f32 v[24:25], v[24:25], v[4:5]
	v_and_b32_e32 v5, 0xffff0000, v146
	v_lshlrev_b32_e32 v146, 16, v148
	v_add_f32_e32 v3, 1.0, v3
	v_pk_mul_f32 v[22:23], v[22:23], v[186:187]
	v_lshlrev_b32_e32 v186, 16, v147
	v_and_b32_e32 v187, 0xffff0000, v147
	v_and_b32_e32 v147, 0xffff0000, v148
	s_waitcnt vmcnt(2)
	v_lshlrev_b32_e32 v4, 16, v142
	v_and_b32_e32 v148, 0xffff0000, v142
	v_rcp_f32_e32 v142, v3
	v_add_f32_e32 v3, v150, v146
	v_mul_f32_e32 v3, 0xbfb8aa3b, v3
	v_exp_f32_e32 v3, v3
	v_lshlrev_b32_e32 v188, 16, v149
	v_and_b32_e32 v189, 0xffff0000, v149
	v_lshlrev_b32_e32 v149, 16, v143
	v_add_f32_e32 v3, 1.0, v3
	v_rcp_f32_e32 v146, v3
	v_add_f32_e32 v3, v159, v5
	v_mul_f32_e32 v3, 0xbfb8aa3b, v3
	v_exp_f32_e32 v3, v3
	v_and_b32_e32 v190, 0xffff0000, v143
	v_lshlrev_b32_e32 v143, 16, v144
	v_add_f32_e32 v143, v154, v143
	v_mul_f32_e32 v143, 0xbfb8aa3b, v143
	v_add_f32_e32 v3, 1.0, v3
	v_and_b32_e32 v191, 0xffff0000, v144
	v_exp_f32_e32 v144, v143
	v_rcp_f32_e32 v143, v3
	v_add_f32_e32 v3, v151, v147
	v_mul_f32_e32 v3, 0xbfb8aa3b, v3
	v_exp_f32_e32 v3, v3
	v_add_f32_e32 v187, v161, v187
	v_lshlrev_b32_e32 v192, 16, v145
	v_mul_f32_e32 v187, 0xbfb8aa3b, v187
	v_add_f32_e32 v3, 1.0, v3
	v_rcp_f32_e32 v147, v3
	v_add_f32_e32 v3, v160, v186
	v_mul_f32_e32 v3, 0xbfb8aa3b, v3
	v_exp_f32_e32 v3, v3
	v_add_f32_e32 v5, v163, v148
	v_add_f32_e32 v148, v164, v149
	v_add_f32_e32 v149, v156, v192
	v_add_f32_e32 v3, 1.0, v3
	v_rcp_f32_e32 v186, v3
	v_add_f32_e32 v3, v152, v188
	v_mul_f32_e32 v3, 0xbfb8aa3b, v3
	v_exp_f32_e32 v3, v3
	v_exp_f32_e32 v187, v187
	v_mul_f32_e32 v149, 0xbfb8aa3b, v149
	v_add_f32_e32 v4, v162, v4
	v_exp_f32_e32 v188, v149
	v_add_f32_e32 v149, v165, v190
	v_mul_f32_e32 v4, 0xbfb8aa3b, v4
	v_mul_f32_e32 v5, 0xbfb8aa3b, v5
	v_mul_f32_e32 v148, 0xbfb8aa3b, v148
	v_add_f32_e32 v3, 1.0, v3
	v_mul_f32_e32 v149, 0xbfb8aa3b, v149
	v_exp_f32_e32 v4, v4
	v_exp_f32_e32 v5, v5
	v_exp_f32_e32 v148, v148
	v_exp_f32_e32 v149, v149
	v_rcp_f32_e32 v190, v3
	v_add_f32_e32 v3, 1.0, v187
	v_rcp_f32_e32 v187, v3
	v_pk_add_f32 v[148:149], v[148:149], 1.0 op_sel_hi:[1,0]
	v_pk_add_f32 v[4:5], v[4:5], 1.0 op_sel_hi:[1,0]
	v_and_b32_e32 v193, 0xffff0000, v145
	v_pk_mul_f32 v[4:5], v[4:5], v[142:143]
	v_pk_mul_f32 v[142:143], v[148:149], v[186:187]
	v_add_f32_e32 v3, v157, v193
	v_pk_mul_f32 v[20:21], v[20:21], v[142:143]
	v_add_f32_e32 v142, v153, v189
	v_mul_f32_e32 v142, 0xbfb8aa3b, v142
	v_exp_f32_e32 v142, v142
	v_mul_f32_e32 v3, 0xbfb8aa3b, v3
	v_exp_f32_e32 v189, v3
	v_add_f32_e32 v145, v155, v191
	v_add_f32_e32 v3, 1.0, v142
	v_rcp_f32_e32 v191, v3
	s_waitcnt vmcnt(1)
	v_lshlrev_b32_e32 v3, 16, v130
	v_mul_f32_e32 v145, 0xbfb8aa3b, v145
	v_add_f32_e32 v3, v158, v3
	v_exp_f32_e32 v145, v145
	v_mul_f32_e32 v3, 0xbfb8aa3b, v3
	v_exp_f32_e32 v3, v3
	v_pk_mul_f32 v[18:19], v[18:19], v[4:5]
	v_pk_add_f32 v[4:5], v[188:189], 1.0 op_sel_hi:[1,0]
	v_pk_add_f32 v[142:143], v[144:145], 1.0 op_sel_hi:[1,0]
	v_pk_mul_f32 v[4:5], v[4:5], v[190:191]
	v_pk_mul_f32 v[142:143], v[142:143], v[146:147]
	v_pk_mul_f32 v[16:17], v[16:17], v[4:5]
	v_and_b32_e32 v5, 0xffff0000, v130
	v_lshlrev_b32_e32 v130, 16, v132
	v_add_f32_e32 v3, 1.0, v3
	v_pk_mul_f32 v[14:15], v[14:15], v[142:143]
	v_lshlrev_b32_e32 v142, 16, v131
	v_and_b32_e32 v143, 0xffff0000, v131
	v_and_b32_e32 v131, 0xffff0000, v132
	s_waitcnt vmcnt(0)
	v_lshlrev_b32_e32 v4, 16, v126
	v_and_b32_e32 v132, 0xffff0000, v126
	v_rcp_f32_e32 v126, v3
	v_add_f32_e32 v3, v150, v130
	v_mul_f32_e32 v3, 0xbfb8aa3b, v3
	v_exp_f32_e32 v3, v3
	v_lshlrev_b32_e32 v144, 16, v133
	v_and_b32_e32 v145, 0xffff0000, v133
	v_lshlrev_b32_e32 v133, 16, v127
	v_add_f32_e32 v3, 1.0, v3
	v_rcp_f32_e32 v130, v3
	v_add_f32_e32 v3, v159, v5
	v_mul_f32_e32 v3, 0xbfb8aa3b, v3
	v_exp_f32_e32 v3, v3
	v_and_b32_e32 v146, 0xffff0000, v127
	v_lshlrev_b32_e32 v127, 16, v128
	v_add_f32_e32 v127, v154, v127
	v_mul_f32_e32 v127, 0xbfb8aa3b, v127
	v_add_f32_e32 v3, 1.0, v3
	v_and_b32_e32 v147, 0xffff0000, v128
	v_exp_f32_e32 v128, v127
	v_rcp_f32_e32 v127, v3
	v_add_f32_e32 v3, v151, v131
	v_mul_f32_e32 v3, 0xbfb8aa3b, v3
	v_exp_f32_e32 v3, v3
	v_add_f32_e32 v143, v161, v143
	v_lshlrev_b32_e32 v148, 16, v129
	v_mul_f32_e32 v143, 0xbfb8aa3b, v143
	v_add_f32_e32 v3, 1.0, v3
	v_rcp_f32_e32 v131, v3
	v_add_f32_e32 v3, v160, v142
	v_mul_f32_e32 v3, 0xbfb8aa3b, v3
	v_exp_f32_e32 v3, v3
	v_add_f32_e32 v5, v163, v132
	v_add_f32_e32 v132, v164, v133
	v_add_f32_e32 v133, v156, v148
	v_add_f32_e32 v3, 1.0, v3
	v_rcp_f32_e32 v142, v3
	v_add_f32_e32 v3, v152, v144
	v_mul_f32_e32 v3, 0xbfb8aa3b, v3
	v_exp_f32_e32 v3, v3
	v_exp_f32_e32 v143, v143
	v_mul_f32_e32 v133, 0xbfb8aa3b, v133
	v_add_f32_e32 v4, v162, v4
	v_exp_f32_e32 v144, v133
	v_add_f32_e32 v133, v165, v146
	v_mul_f32_e32 v4, 0xbfb8aa3b, v4
	v_mul_f32_e32 v5, 0xbfb8aa3b, v5
	v_mul_f32_e32 v132, 0xbfb8aa3b, v132
	v_add_f32_e32 v3, 1.0, v3
	v_mul_f32_e32 v133, 0xbfb8aa3b, v133
	v_exp_f32_e32 v4, v4
	v_exp_f32_e32 v5, v5
	v_exp_f32_e32 v132, v132
	v_exp_f32_e32 v133, v133
	v_rcp_f32_e32 v146, v3
	v_add_f32_e32 v3, 1.0, v143
	v_rcp_f32_e32 v143, v3
	v_pk_add_f32 v[132:133], v[132:133], 1.0 op_sel_hi:[1,0]
	v_pk_add_f32 v[4:5], v[4:5], 1.0 op_sel_hi:[1,0]
	v_and_b32_e32 v149, 0xffff0000, v129
	v_pk_mul_f32 v[4:5], v[4:5], v[126:127]
	v_pk_mul_f32 v[126:127], v[132:133], v[142:143]
	v_add_f32_e32 v129, v155, v147
	v_pk_mul_f32 v[12:13], v[12:13], v[126:127]
	v_add_f32_e32 v126, v153, v145
	v_mul_f32_e32 v126, 0xbfb8aa3b, v126
	v_exp_f32_e32 v126, v126
	v_add_f32_e32 v3, v157, v149
	v_mul_f32_e32 v129, 0xbfb8aa3b, v129
	v_mul_f32_e32 v3, 0xbfb8aa3b, v3
	v_exp_f32_e32 v129, v129
	v_exp_f32_e32 v145, v3
	v_add_f32_e32 v3, 1.0, v126
	v_rcp_f32_e32 v147, v3
	v_pk_mul_f32 v[10:11], v[10:11], v[4:5]
	v_pk_add_f32 v[4:5], v[144:145], 1.0 op_sel_hi:[1,0]
	v_pk_add_f32 v[126:127], v[128:129], 1.0 op_sel_hi:[1,0]
	v_pk_mul_f32 v[4:5], v[4:5], v[146:147]
	v_pk_mul_f32 v[126:127], v[126:127], v[130:131]
	v_pk_mul_f32 v[8:9], v[8:9], v[4:5]
	v_pk_mul_f32 v[6:7], v[6:7], v[126:127]

; #define PG8_STAGE(bufoff, gbase, voff) do { _Pragma("unroll") for (int _i = 0; _i < 2; ++_i) \
;         __builtin_amdgcn_global_load_lds((const unsigned*)((const char*)(gbase) + (voff)[_i]), (LAS unsigned*)(lds + (bufoff) + ldsw + _i * 8192), 16, 0, 0); } while (0)
; #define PG8_LDA(dst, b, h) do { _Pragma("unroll") for (int m = 0; m < 4; ++m) _Pragma("unroll") for (int k = 0; k < 2; ++k) dst[m][k] = *(const LAS bf16x8*)(lds + PG8_SA(b, h) + aoff + m * 2048 + k * 1024); } while (0)
; #define PG8_LDB(dst, b, h) do { _Pragma("unroll") for (int n = 0; n < 2; ++n) _Pragma("unroll") for (int k = 0; k < 2; ++k) dst[n][k] = *(const LAS bf16x8*)(lds + PG8_SB(b, h) + boff + n * 2048 + k * 1024); } while (0)
; #define PG8_MMA(ai, bj, At, Bt) do { __builtin_amdgcn_s_setprio(1); _Pragma("unroll") for (int m = 0; m < 4; ++m) _Pragma("unroll") for (int n = 0; n < 2; ++n) _Pragma("unroll") for (int k = 0; k < 2; ++k) \
;         acc[ai][bj][m][n] = __builtin_amdgcn_mfma_f32_16x16x32_bf16(Bt[n][k], At[m][k], acc[ai][bj][m][n], 0, 0, 0); __builtin_amdgcn_s_setprio(0); } while (0)
; #define PG8_WAIT_V(n) asm volatile("s_waitcnt vmcnt(" #n ")" ::: "memory")
; #define PG8_WAIT_L(n) asm volatile("s_waitcnt lgkmcnt(" #n ")" ::: "memory")
; #define PG8_BAR __builtin_amdgcn_s_barrier()
; template <class Epi, class Sched, bool ALIGN_EPI, class Hook = NoHook>
; __device__ __forceinline__ void gemm_phase(LAS unsigned char* lds, const Gemm g, const Sched& S, const Epi& E, const Hook& H = Hook()) {
;     ...
;             const bool last = (t == nt - 2);
;             const char* a1 = cA + (size_t)(t + 1) * kstep;
;             const char* a2 = last ? nA : cA + (size_t)(t + 2) * kstep; const char* b2 = last ? nB : cB + (size_t)(t + 2) * kstep;
;             const char* a3 = a2 + kstep; const char* b3 = b2 + kstep;
;             if (last && has_next) S.a_ready(nxt);
;             PG8_LDB(B0, 0, 0); PG8_LDB(B1, 0, 1); PG8_SCHED; PG8_LDA(At, 0, 0); PG8_STAGE(PG8_SA(1, 1), a1 + hA, voffA);
;             PG8_WAIT_V(8); PG8_WAIT_L(0); PG8_BAR; PG8_MMA(0, 0, At, B0); PG8_MMA(0, 1, At, B1); PG8_BAR; PG8_SCHED;
;             PG8_LDA(At, 0, 1); PG8_STAGE(PG8_SB(0, 0), b2, voffB); PG8_STAGE(PG8_SB(0, 1), b2 + hB, voffB); PG8_STAGE(PG8_SA(0, 0), a2, voffA);
;             PG8_WAIT_V(8); PG8_WAIT_L(0); PG8_BAR; PG8_MMA(1, 0, At, B0); PG8_MMA(1, 1, At, B1); PG8_BAR; PG8_SCHED;
.LBB0_850:
	s_add_u32 s20, s6, 0x87c00080
	s_addc_u32 s21, s7, -1
	s_cmp_lg_u32 s42, 60
	s_cselect_b32 s20, s20, 0
	s_cselect_b32 s21, s21, 0
	s_add_u32 s22, s2, s20
	s_addc_u32 s23, s3, s21
	s_add_u32 s20, s14, s20
	s_addc_u32 s21, s15, s21
	s_mov_b32 m0, s43
	ds_read_b128 v[146:149], v1
	ds_read_b128 v[150:153], v1 offset:1024
	ds_read_b128 v[154:157], v1 offset:2048
	ds_read_b128 v[158:161], v1 offset:3072
	ds_read_b128 v[162:165], v142
	ds_read_b128 v[166:169], v142 offset:1024
	ds_read_b128 v[170:173], v142 offset:2048
	ds_read_b128 v[174:177], v142 offset:3072
	v_lshl_add_u64 v[178:179], v[138:139], 0, s[6:7]
	global_load_lds_dwordx4 v[178:179], off
	ds_read_b128 v[186:189], v143
	ds_read_b128 v[190:193], v143 offset:1024
	ds_read_b128 v[194:197], v143 offset:2048
	ds_read_b128 v[198:201], v143 offset:3072
	ds_read_b128 v[202:205], v143 offset:4096
	ds_read_b128 v[206:209], v143 offset:5120
	ds_read_b128 v[210:213], v143 offset:6144
	ds_read_b128 v[214:217], v143 offset:7168
	v_lshl_add_u64 v[178:179], v[140:141], 0, s[6:7]
	s_mov_b32 m0, s44
	s_nop 0
	global_load_lds_dwordx4 v[178:179], off
	s_waitcnt vmcnt(8)
	s_waitcnt lgkmcnt(0)
	s_barrier
	s_setprio 1
	s_waitcnt lgkmcnt(0)
	v_mfma_f32_16x16x32_bf16 v[54:57], v[146:149], v[186:189], v[54:57]
	v_mfma_f32_16x16x32_bf16 v[34:37], v[154:157], v[186:189], v[34:37]
	v_mfma_f32_16x16x32_bf16 v[42:45], v[146:149], v[194:197], v[42:45]
	v_mfma_f32_16x16x32_bf16 v[30:33], v[154:157], v[194:197], v[30:33]
	v_mfma_f32_16x16x32_bf16 v[62:65], v[146:149], v[202:205], v[62:65]
	v_mfma_f32_16x16x32_bf16 v[50:53], v[154:157], v[202:205], v[50:53]
	v_mfma_f32_16x16x32_bf16 v[78:81], v[146:149], v[210:213], v[78:81]
	v_mfma_f32_16x16x32_bf16 v[70:73], v[154:157], v[210:213], v[70:73]
	v_mfma_f32_16x16x32_bf16 v[54:57], v[150:153], v[190:193], v[54:57]
	v_mfma_f32_16x16x32_bf16 v[34:37], v[158:161], v[190:193], v[34:37]
	v_mfma_f32_16x16x32_bf16 v[42:45], v[150:153], v[198:201], v[42:45]
	v_mfma_f32_16x16x32_bf16 v[30:33], v[158:161], v[198:201], v[30:33]
	v_mfma_f32_16x16x32_bf16 v[62:65], v[150:153], v[206:209], v[62:65]
	v_mfma_f32_16x16x32_bf16 v[50:53], v[158:161], v[206:209], v[50:53]
	v_mfma_f32_16x16x32_bf16 v[78:81], v[150:153], v[214:217], v[78:81]
	v_mfma_f32_16x16x32_bf16 v[70:73], v[158:161], v[214:217], v[70:73]
	s_setprio 0
	s_setprio 1
	v_mfma_f32_16x16x32_bf16 v[10:13], v[162:165], v[186:189], v[10:13]
	v_mfma_f32_16x16x32_bf16 v[2:5], v[170:173], v[186:189], v[2:5]
	v_mfma_f32_16x16x32_bf16 v[14:17], v[162:165], v[194:197], v[14:17]
	v_mfma_f32_16x16x32_bf16 v[6:9], v[170:173], v[194:197], v[6:9]
	v_mfma_f32_16x16x32_bf16 v[22:25], v[162:165], v[202:205], v[22:25]
	v_mfma_f32_16x16x32_bf16 v[18:21], v[170:173], v[202:205], v[18:21]
	v_mfma_f32_16x16x32_bf16 v[38:41], v[162:165], v[210:213], v[38:41]
	v_mfma_f32_16x16x32_bf16 v[26:29], v[170:173], v[210:213], v[26:29]
	v_mfma_f32_16x16x32_bf16 v[10:13], v[166:169], v[190:193], v[10:13]
	v_mfma_f32_16x16x32_bf16 v[2:5], v[174:177], v[190:193], v[2:5]
	v_mfma_f32_16x16x32_bf16 v[14:17], v[166:169], v[198:201], v[14:17]
	v_mfma_f32_16x16x32_bf16 v[6:9], v[174:177], v[198:201], v[6:9]
	v_mfma_f32_16x16x32_bf16 v[22:25], v[166:169], v[206:209], v[22:25]
	v_mfma_f32_16x16x32_bf16 v[18:21], v[174:177], v[206:209], v[18:21]
	v_mfma_f32_16x16x32_bf16 v[38:41], v[166:169], v[214:217], v[38:41]
	v_mfma_f32_16x16x32_bf16 v[26:29], v[174:177], v[214:217], v[26:29]
	s_setprio 0
	s_barrier
	s_mov_b32 m0, s45
	s_add_u32 s54, s20, 0x100000
	global_load_lds_dwordx4 v132, s[20:21]
	ds_read_b128 v[186:189], v143 offset:16384
	ds_read_b128 v[190:193], v143 offset:17408
	s_mov_b32 m0, s46
	s_addc_u32 s55, s21, 0
	global_load_lds_dwordx4 v136, s[20:21]
	ds_read_b128 v[194:197], v143 offset:18432
	ds_read_b128 v[198:201], v143 offset:19456
	s_mov_b32 m0, s47
	s_nop 0
	global_load_lds_dwordx4 v132, s[54:55]
	ds_read_b128 v[202:205], v143 offset:20480
	s_mov_b32 m0, s48
	s_nop 0
	global_load_lds_dwordx4 v136, s[54:55]
	ds_read_b128 v[206:209], v143 offset:21504
	s_add_u32 s58, s22, s4
	s_addc_u32 s59, s23, s5
	s_mov_b32 m0, s28
	s_nop 0
	global_load_lds_dwordx4 v130, s[22:23]
	ds_read_b128 v[210:213], v143 offset:22528
	s_mov_b32 m0, s29
	s_nop 0
	global_load_lds_dwordx4 v134, s[22:23]
	ds_read_b128 v[214:217], v143 offset:23552
	s_waitcnt vmcnt(8)
	s_waitcnt lgkmcnt(0)
	s_barrier
	s_setprio 1
	s_waitcnt lgkmcnt(0)
	v_mfma_f32_16x16x32_bf16 v[94:97], v[146:149], v[186:189], v[94:97]
	v_mfma_f32_16x16x32_bf16 v[86:89], v[154:157], v[186:189], v[86:89]
	v_mfma_f32_16x16x32_bf16 v[102:105], v[146:149], v[194:197], v[102:105]
	v_mfma_f32_16x16x32_bf16 v[98:101], v[154:157], v[194:197], v[98:101]
	v_mfma_f32_16x16x32_bf16 v[110:113], v[146:149], v[202:205], v[110:113]
	v_mfma_f32_16x16x32_bf16 v[106:109], v[154:157], v[202:205], v[106:109]
	v_mfma_f32_16x16x32_bf16 v[126:129], v[146:149], v[210:213], v[126:129]
	v_mfma_f32_16x16x32_bf16 v[122:125], v[154:157], v[210:213], v[122:125]
	v_mfma_f32_16x16x32_bf16 v[94:97], v[150:153], v[190:193], v[94:97]
	v_mfma_f32_16x16x32_bf16 v[86:89], v[158:161], v[190:193], v[86:89]
	v_mfma_f32_16x16x32_bf16 v[102:105], v[150:153], v[198:201], v[102:105]
	v_mfma_f32_16x16x32_bf16 v[98:101], v[158:161], v[198:201], v[98:101]
	v_mfma_f32_16x16x32_bf16 v[110:113], v[150:153], v[206:209], v[110:113]
	v_mfma_f32_16x16x32_bf16 v[106:109], v[158:161], v[206:209], v[106:109]
	v_mfma_f32_16x16x32_bf16 v[126:129], v[150:153], v[214:217], v[126:129]
	v_mfma_f32_16x16x32_bf16 v[122:125], v[158:161], v[214:217], v[122:125]
	s_setprio 0
	s_setprio 1
	v_mfma_f32_16x16x32_bf16 v[58:61], v[162:165], v[186:189], v[58:61]
	v_mfma_f32_16x16x32_bf16 v[46:49], v[170:173], v[186:189], v[46:49]
	v_mfma_f32_16x16x32_bf16 v[74:77], v[162:165], v[194:197], v[74:77]
	v_mfma_f32_16x16x32_bf16 v[66:69], v[170:173], v[194:197], v[66:69]
	v_mfma_f32_16x16x32_bf16 v[90:93], v[162:165], v[202:205], v[90:93]
	v_mfma_f32_16x16x32_bf16 v[82:85], v[170:173], v[202:205], v[82:85]
	v_mfma_f32_16x16x32_bf16 v[118:121], v[162:165], v[210:213], v[118:121]
	v_mfma_f32_16x16x32_bf16 v[114:117], v[170:173], v[210:213], v[114:117]
	v_mfma_f32_16x16x32_bf16 v[58:61], v[166:169], v[190:193], v[58:61]
	v_mfma_f32_16x16x32_bf16 v[46:49], v[174:177], v[190:193], v[46:49]
	v_mfma_f32_16x16x32_bf16 v[74:77], v[166:169], v[198:201], v[74:77]
	v_mfma_f32_16x16x32_bf16 v[66:69], v[174:177], v[198:201], v[66:69]
	v_mfma_f32_16x16x32_bf16 v[90:93], v[166:169], v[206:209], v[90:93]
	v_mfma_f32_16x16x32_bf16 v[82:85], v[174:177], v[206:209], v[82:85]
	v_mfma_f32_16x16x32_bf16 v[118:121], v[166:169], v[214:217], v[118:121]
	v_mfma_f32_16x16x32_bf16 v[114:117], v[174:177], v[214:217], v[114:117]
	s_setprio 0
	s_barrier
; #define PG8_STAGE(bufoff, gbase, voff) do { _Pragma("unroll") for (int _i = 0; _i < 2; ++_i) \
;         __builtin_amdgcn_global_load_lds((const unsigned*)((const char*)(gbase) + (voff)[_i]), (LAS unsigned*)(lds + (bufoff) + ldsw + _i * 8192), 16, 0, 0); } while (0)
; #define PG8_LDA(dst, b, h) do { _Pragma("unroll") for (int m = 0; m < 4; ++m) _Pragma("unroll") for (int k = 0; k < 2; ++k) dst[m][k] = *(const LAS bf16x8*)(lds + PG8_SA(b, h) + aoff + m * 2048 + k * 1024); } while (0)
; #define PG8_LDB(dst, b, h) do { _Pragma("unroll") for (int n = 0; n < 2; ++n) _Pragma("unroll") for (int k = 0; k < 2; ++k) dst[n][k] = *(const LAS bf16x8*)(lds + PG8_SB(b, h) + boff + n * 2048 + k * 1024); } while (0)
; #define PG8_MMA(ai, bj, At, Bt) do { __builtin_amdgcn_s_setprio(1); _Pragma("unroll") for (int m = 0; m < 4; ++m) _Pragma("unroll") for (int n = 0; n < 2; ++n) _Pragma("unroll") for (int k = 0; k < 2; ++k) \
;         acc[ai][bj][m][n] = __builtin_amdgcn_mfma_f32_16x16x32_bf16(Bt[n][k], At[m][k], acc[ai][bj][m][n], 0, 0, 0); __builtin_amdgcn_s_setprio(0); } while (0)
; #define PG8_WAIT_V(n) asm volatile("s_waitcnt vmcnt(" #n ")" ::: "memory")
; #define PG8_WAIT_L(n) asm volatile("s_waitcnt lgkmcnt(" #n ")" ::: "memory")
; #define PG8_BAR __builtin_amdgcn_s_barrier()
; #define PG8_SCHED __builtin_amdgcn_sched_barrier(0)
; template <class Epi, class Sched, bool ALIGN_EPI, class Hook = NoHook>
; __device__ __forceinline__ void gemm_phase(LAS unsigned char* lds, const Gemm g, const Sched& S, const Epi& E, const Hook& H = Hook()) {
;     ...
;             PG8_LDB(B0, 1, 0); PG8_LDB(B1, 1, 1); PG8_SCHED; PG8_LDA(At, 1, 0); PG8_STAGE(PG8_SA(0, 1), a2 + hA, voffA);
;             PG8_WAIT_V(8); PG8_WAIT_L(0); PG8_BAR; PG8_MMA(0, 0, At, B0); PG8_MMA(0, 1, At, B1); PG8_BAR; PG8_SCHED;
;             PG8_LDA(At, 1, 1); PG8_STAGE(PG8_SB(1, 0), b3, voffB); PG8_STAGE(PG8_SB(1, 1), b3 + hB, voffB); PG8_STAGE(PG8_SA(1, 0), a3, voffA);
;             PG8_WAIT_V(8); PG8_WAIT_L(0); PG8_BAR; PG8_MMA(1, 0, At, B0); PG8_MMA(1, 1, At, B1); PG8_BAR; PG8_SCHED;
;         }
;         if constexpr (Hook::ON) H.after(te, acc, cur, wr, wc, fr, fq);
;         }
;         if constexpr (ALIGN_EPI) { if (wr == 0) PG8_BAR; }
	s_add_u32 s22, s22, 0x100000
	s_addc_u32 s23, s23, 0
	s_mov_b32 m0, s38
	s_nop 0
	global_load_lds_dwordx4 v130, s[22:23]
	ds_read_b128 v[146:149], v144
	ds_read_b128 v[150:153], v144 offset:1024
	ds_read_b128 v[154:157], v144 offset:2048
	ds_read_b128 v[158:161], v144 offset:3072
	ds_read_b128 v[162:165], v145
	ds_read_b128 v[166:169], v145 offset:1024
	ds_read_b128 v[170:173], v145 offset:2048
	ds_read_b128 v[174:177], v145 offset:3072
	s_mov_b32 m0, s39
	s_nop 0
	global_load_lds_dwordx4 v134, s[22:23]
	ds_read_b128 v[186:189], v143 offset:32768
	ds_read_b128 v[190:193], v143 offset:33792
	ds_read_b128 v[194:197], v143 offset:34816
	ds_read_b128 v[198:201], v143 offset:35840
	ds_read_b128 v[202:205], v143 offset:36864
	ds_read_b128 v[206:209], v143 offset:37888
	ds_read_b128 v[210:213], v143 offset:38912
	ds_read_b128 v[214:217], v143 offset:39936
	s_waitcnt vmcnt(8)
	s_waitcnt lgkmcnt(0)
	s_barrier
	s_setprio 1
	s_waitcnt lgkmcnt(0)
	v_mfma_f32_16x16x32_bf16 v[54:57], v[146:149], v[186:189], v[54:57]
	v_mfma_f32_16x16x32_bf16 v[34:37], v[154:157], v[186:189], v[34:37]
	v_mfma_f32_16x16x32_bf16 v[42:45], v[146:149], v[194:197], v[42:45]
	v_mfma_f32_16x16x32_bf16 v[30:33], v[154:157], v[194:197], v[30:33]
	v_mfma_f32_16x16x32_bf16 v[62:65], v[146:149], v[202:205], v[62:65]
	v_mfma_f32_16x16x32_bf16 v[50:53], v[154:157], v[202:205], v[50:53]
	v_mfma_f32_16x16x32_bf16 v[78:81], v[146:149], v[210:213], v[78:81]
	v_mfma_f32_16x16x32_bf16 v[70:73], v[154:157], v[210:213], v[70:73]
	v_mfma_f32_16x16x32_bf16 v[54:57], v[150:153], v[190:193], v[54:57]
	v_mfma_f32_16x16x32_bf16 v[34:37], v[158:161], v[190:193], v[34:37]
	v_mfma_f32_16x16x32_bf16 v[42:45], v[150:153], v[198:201], v[42:45]
	v_mfma_f32_16x16x32_bf16 v[30:33], v[158:161], v[198:201], v[30:33]
	v_mfma_f32_16x16x32_bf16 v[62:65], v[150:153], v[206:209], v[62:65]
	v_mfma_f32_16x16x32_bf16 v[50:53], v[158:161], v[206:209], v[50:53]
	v_mfma_f32_16x16x32_bf16 v[78:81], v[150:153], v[214:217], v[78:81]
	v_mfma_f32_16x16x32_bf16 v[70:73], v[158:161], v[214:217], v[70:73]
	s_setprio 0
	s_setprio 1
	v_mfma_f32_16x16x32_bf16 v[10:13], v[162:165], v[186:189], v[10:13]
	v_mfma_f32_16x16x32_bf16 v[2:5], v[170:173], v[186:189], v[2:5]
	v_mfma_f32_16x16x32_bf16 v[14:17], v[162:165], v[194:197], v[14:17]
	v_mfma_f32_16x16x32_bf16 v[6:9], v[170:173], v[194:197], v[6:9]
	v_mfma_f32_16x16x32_bf16 v[22:25], v[162:165], v[202:205], v[22:25]
	v_mfma_f32_16x16x32_bf16 v[18:21], v[170:173], v[202:205], v[18:21]
	v_mfma_f32_16x16x32_bf16 v[38:41], v[162:165], v[210:213], v[38:41]
	v_mfma_f32_16x16x32_bf16 v[26:29], v[170:173], v[210:213], v[26:29]
	v_mfma_f32_16x16x32_bf16 v[10:13], v[166:169], v[190:193], v[10:13]
	v_mfma_f32_16x16x32_bf16 v[2:5], v[174:177], v[190:193], v[2:5]
	v_mfma_f32_16x16x32_bf16 v[14:17], v[166:169], v[198:201], v[14:17]
	v_mfma_f32_16x16x32_bf16 v[6:9], v[174:177], v[198:201], v[6:9]
	v_mfma_f32_16x16x32_bf16 v[22:25], v[166:169], v[206:209], v[22:25]
	v_mfma_f32_16x16x32_bf16 v[18:21], v[174:177], v[206:209], v[18:21]
	v_mfma_f32_16x16x32_bf16 v[38:41], v[166:169], v[214:217], v[38:41]
	v_mfma_f32_16x16x32_bf16 v[26:29], v[174:177], v[214:217], v[26:29]
	s_setprio 0
	s_barrier
	s_mov_b32 m0, s49
	s_add_u32 s56, s20, s4
	s_addc_u32 s57, s21, s5
	s_add_u32 s20, s20, 0x100080
	global_load_lds_dwordx4 v132, s[56:57]
	ds_read_b128 v[186:189], v143 offset:49152
	ds_read_b128 v[190:193], v143 offset:50176
	s_mov_b32 m0, s50
	s_addc_u32 s21, s21, 0
	global_load_lds_dwordx4 v136, s[56:57]
	ds_read_b128 v[194:197], v143 offset:51200
	ds_read_b128 v[198:201], v143 offset:52224
	s_mov_b32 m0, s51
	s_nop 0
	global_load_lds_dwordx4 v132, s[20:21]
	ds_read_b128 v[202:205], v143 offset:53248
	s_mov_b32 m0, s52
	s_nop 0
	global_load_lds_dwordx4 v136, s[20:21]
	ds_read_b128 v[206:209], v143 offset:54272
	s_mov_b32 m0, s40
	s_nop 0
	global_load_lds_dwordx4 v130, s[58:59]
	ds_read_b128 v[210:213], v143 offset:55296
	s_mov_b32 m0, s41
	s_nop 0
	global_load_lds_dwordx4 v134, s[58:59]
	ds_read_b128 v[214:217], v143 offset:56320
	s_waitcnt vmcnt(8)
	s_waitcnt lgkmcnt(0)
	s_barrier
	s_setprio 1
	s_waitcnt lgkmcnt(0)
	v_mfma_f32_16x16x32_bf16 v[94:97], v[146:149], v[186:189], v[94:97]
	v_mfma_f32_16x16x32_bf16 v[86:89], v[154:157], v[186:189], v[86:89]
	v_mfma_f32_16x16x32_bf16 v[102:105], v[146:149], v[194:197], v[102:105]
	v_mfma_f32_16x16x32_bf16 v[98:101], v[154:157], v[194:197], v[98:101]
	v_mfma_f32_16x16x32_bf16 v[110:113], v[146:149], v[202:205], v[110:113]
	v_mfma_f32_16x16x32_bf16 v[106:109], v[154:157], v[202:205], v[106:109]
	v_mfma_f32_16x16x32_bf16 v[126:129], v[146:149], v[210:213], v[126:129]
	v_mfma_f32_16x16x32_bf16 v[122:125], v[154:157], v[210:213], v[122:125]
	v_mfma_f32_16x16x32_bf16 v[94:97], v[150:153], v[190:193], v[94:97]
	v_mfma_f32_16x16x32_bf16 v[86:89], v[158:161], v[190:193], v[86:89]
	v_mfma_f32_16x16x32_bf16 v[102:105], v[150:153], v[198:201], v[102:105]
	v_mfma_f32_16x16x32_bf16 v[98:101], v[158:161], v[198:201], v[98:101]
	v_mfma_f32_16x16x32_bf16 v[110:113], v[150:153], v[206:209], v[110:113]
	v_mfma_f32_16x16x32_bf16 v[106:109], v[158:161], v[206:209], v[106:109]
	v_mfma_f32_16x16x32_bf16 v[126:129], v[150:153], v[214:217], v[126:129]
	v_mfma_f32_16x16x32_bf16 v[122:125], v[158:161], v[214:217], v[122:125]
	s_setprio 0
	s_setprio 1
	v_mfma_f32_16x16x32_bf16 v[58:61], v[162:165], v[186:189], v[58:61]
	v_mfma_f32_16x16x32_bf16 v[46:49], v[170:173], v[186:189], v[46:49]
	v_mfma_f32_16x16x32_bf16 v[74:77], v[162:165], v[194:197], v[74:77]
	v_mfma_f32_16x16x32_bf16 v[66:69], v[170:173], v[194:197], v[66:69]
	v_mfma_f32_16x16x32_bf16 v[90:93], v[162:165], v[202:205], v[90:93]
	v_mfma_f32_16x16x32_bf16 v[82:85], v[170:173], v[202:205], v[82:85]
	v_mfma_f32_16x16x32_bf16 v[118:121], v[162:165], v[210:213], v[118:121]
	v_mfma_f32_16x16x32_bf16 v[114:117], v[170:173], v[210:213], v[114:117]
	v_mfma_f32_16x16x32_bf16 v[58:61], v[166:169], v[190:193], v[58:61]
	v_mfma_f32_16x16x32_bf16 v[46:49], v[174:177], v[190:193], v[46:49]
	v_mfma_f32_16x16x32_bf16 v[74:77], v[166:169], v[198:201], v[74:77]
	v_mfma_f32_16x16x32_bf16 v[66:69], v[174:177], v[198:201], v[66:69]
	v_mfma_f32_16x16x32_bf16 v[90:93], v[166:169], v[206:209], v[90:93]
	v_mfma_f32_16x16x32_bf16 v[82:85], v[174:177], v[206:209], v[82:85]
	v_mfma_f32_16x16x32_bf16 v[118:121], v[166:169], v[214:217], v[118:121]
	v_mfma_f32_16x16x32_bf16 v[114:117], v[174:177], v[214:217], v[114:117]
	s_setprio 0
	s_barrier
	s_add_i32 s42, s42, 2
	s_add_u32 s6, s6, 0x100
	s_addc_u32 s7, s7, 0
	s_cmp_gt_u32 s42, 61
	s_cbranch_scc0 .LBB0_850
	s_cmpk_lt_u32 s26, 0x100
	s_cbranch_scc0 .LBB0_853
	s_barrier

; #define PG8_STAGE(bufoff, gbase, voff) do { _Pragma("unroll") for (int _i = 0; _i < 2; ++_i) \
;         __builtin_amdgcn_global_load_lds((const unsigned*)((const char*)(gbase) + (voff)[_i]), (LAS unsigned*)(lds + (bufoff) + ldsw + _i * 8192), 16, 0, 0); } while (0)
; #define PG8_LDA(dst, b, h) do { _Pragma("unroll") for (int m = 0; m < 4; ++m) _Pragma("unroll") for (int k = 0; k < 2; ++k) dst[m][k] = *(const LAS bf16x8*)(lds + PG8_SA(b, h) + aoff + m * 2048 + k * 1024); } while (0)
; #define PG8_LDB(dst, b, h) do { _Pragma("unroll") for (int n = 0; n < 2; ++n) _Pragma("unroll") for (int k = 0; k < 2; ++k) dst[n][k] = *(const LAS bf16x8*)(lds + PG8_SB(b, h) + boff + n * 2048 + k * 1024); } while (0)
; #define PG8_MMA(ai, bj, At, Bt) do { __builtin_amdgcn_s_setprio(1); _Pragma("unroll") for (int m = 0; m < 4; ++m) _Pragma("unroll") for (int n = 0; n < 2; ++n) _Pragma("unroll") for (int k = 0; k < 2; ++k) \
;         acc[ai][bj][m][n] = __builtin_amdgcn_mfma_f32_16x16x32_bf16(Bt[n][k], At[m][k], acc[ai][bj][m][n], 0, 0, 0); __builtin_amdgcn_s_setprio(0); } while (0)
; #define PG8_WAIT_V(n) asm volatile("s_waitcnt vmcnt(" #n ")" ::: "memory")
; #define PG8_WAIT_L(n) asm volatile("s_waitcnt lgkmcnt(" #n ")" ::: "memory")
; #define PG8_BAR __builtin_amdgcn_s_barrier()
; template <class Epi, class Sched, bool ALIGN_EPI, class Hook = NoHook>
; __device__ __forceinline__ void gemm_phase(LAS unsigned char* lds, const Gemm g, const Sched& S, const Epi& E, const Hook& H = Hook()) {
;     ...
;             const bool last = (t == nt - 2);
;             const char* a1 = cA + (size_t)(t + 1) * kstep;
;             const char* a2 = last ? nA : cA + (size_t)(t + 2) * kstep; const char* b2 = last ? nB : cB + (size_t)(t + 2) * kstep;
;             const char* a3 = a2 + kstep; const char* b3 = b2 + kstep;
;             if (last && has_next) S.a_ready(nxt);
;             PG8_LDB(B0, 0, 0); PG8_LDB(B1, 0, 1); PG8_SCHED; PG8_LDA(At, 0, 0); PG8_STAGE(PG8_SA(1, 1), a1 + hA, voffA);
;             PG8_WAIT_V(8); PG8_WAIT_L(0); PG8_BAR; PG8_MMA(0, 0, At, B0); PG8_MMA(0, 1, At, B1); PG8_BAR; PG8_SCHED;
;             PG8_LDA(At, 0, 1); PG8_STAGE(PG8_SB(0, 0), b2, voffB); PG8_STAGE(PG8_SB(0, 1), b2 + hB, voffB); PG8_STAGE(PG8_SA(0, 0), a2, voffA);
;             PG8_WAIT_V(8); PG8_WAIT_L(0); PG8_BAR; PG8_MMA(1, 0, At, B0); PG8_MMA(1, 1, At, B1); PG8_BAR; PG8_SCHED;
.LBB0_896:
	s_add_u32 s10, s6, 0x87c00080
	s_addc_u32 s11, s7, -1
	s_cmp_lg_u32 s18, 60
	s_cselect_b32 s10, s10, 0
	s_cselect_b32 s11, s11, 0
	s_add_u32 s16, s2, s10
	s_addc_u32 s17, s3, s11
	s_add_u32 s10, s14, s10
	s_addc_u32 s11, s15, s11
	s_mov_b32 m0, s19
	ds_read_b128 v[146:149], v140
	ds_read_b128 v[150:153], v140 offset:1024
	ds_read_b128 v[154:157], v140 offset:2048
	ds_read_b128 v[158:161], v140 offset:3072
	ds_read_b128 v[162:165], v141
	ds_read_b128 v[166:169], v141 offset:1024
	ds_read_b128 v[170:173], v141 offset:2048
	ds_read_b128 v[174:177], v141 offset:3072
	v_lshl_add_u64 v[178:179], v[136:137], 0, s[6:7]
	global_load_lds_dwordx4 v[178:179], off
	ds_read_b128 v[186:189], v142
	ds_read_b128 v[190:193], v142 offset:1024
	ds_read_b128 v[194:197], v142 offset:2048
	ds_read_b128 v[198:201], v142 offset:3072
	ds_read_b128 v[202:205], v142 offset:4096
	ds_read_b128 v[206:209], v142 offset:5120
	ds_read_b128 v[210:213], v142 offset:6144
	ds_read_b128 v[214:217], v142 offset:7168
	v_lshl_add_u64 v[178:179], v[138:139], 0, s[6:7]
	s_mov_b32 m0, s31
	s_nop 0
	global_load_lds_dwordx4 v[178:179], off
	s_waitcnt vmcnt(8)
	s_waitcnt lgkmcnt(0)
	s_barrier
	s_setprio 1
	s_waitcnt lgkmcnt(0)
	v_mfma_f32_16x16x32_bf16 v[54:57], v[146:149], v[186:189], v[54:57]
	v_mfma_f32_16x16x32_bf16 v[34:37], v[154:157], v[186:189], v[34:37]
	v_mfma_f32_16x16x32_bf16 v[42:45], v[146:149], v[194:197], v[42:45]
	v_mfma_f32_16x16x32_bf16 v[30:33], v[154:157], v[194:197], v[30:33]
	v_mfma_f32_16x16x32_bf16 v[62:65], v[146:149], v[202:205], v[62:65]
	v_mfma_f32_16x16x32_bf16 v[50:53], v[154:157], v[202:205], v[50:53]
	v_mfma_f32_16x16x32_bf16 v[78:81], v[146:149], v[210:213], v[78:81]
	v_mfma_f32_16x16x32_bf16 v[70:73], v[154:157], v[210:213], v[70:73]
	v_mfma_f32_16x16x32_bf16 v[54:57], v[150:153], v[190:193], v[54:57]
	v_mfma_f32_16x16x32_bf16 v[34:37], v[158:161], v[190:193], v[34:37]
	v_mfma_f32_16x16x32_bf16 v[42:45], v[150:153], v[198:201], v[42:45]
	v_mfma_f32_16x16x32_bf16 v[30:33], v[158:161], v[198:201], v[30:33]
	v_mfma_f32_16x16x32_bf16 v[62:65], v[150:153], v[206:209], v[62:65]
	v_mfma_f32_16x16x32_bf16 v[50:53], v[158:161], v[206:209], v[50:53]
	v_mfma_f32_16x16x32_bf16 v[78:81], v[150:153], v[214:217], v[78:81]
	v_mfma_f32_16x16x32_bf16 v[70:73], v[158:161], v[214:217], v[70:73]
	s_setprio 0
	s_setprio 1
	v_mfma_f32_16x16x32_bf16 v[10:13], v[162:165], v[186:189], v[10:13]
	v_mfma_f32_16x16x32_bf16 v[2:5], v[170:173], v[186:189], v[2:5]
	v_mfma_f32_16x16x32_bf16 v[14:17], v[162:165], v[194:197], v[14:17]
	v_mfma_f32_16x16x32_bf16 v[6:9], v[170:173], v[194:197], v[6:9]
	v_mfma_f32_16x16x32_bf16 v[22:25], v[162:165], v[202:205], v[22:25]
	v_mfma_f32_16x16x32_bf16 v[18:21], v[170:173], v[202:205], v[18:21]
	v_mfma_f32_16x16x32_bf16 v[38:41], v[162:165], v[210:213], v[38:41]
	v_mfma_f32_16x16x32_bf16 v[26:29], v[170:173], v[210:213], v[26:29]
	v_mfma_f32_16x16x32_bf16 v[10:13], v[166:169], v[190:193], v[10:13]
	v_mfma_f32_16x16x32_bf16 v[2:5], v[174:177], v[190:193], v[2:5]
	v_mfma_f32_16x16x32_bf16 v[14:17], v[166:169], v[198:201], v[14:17]
	v_mfma_f32_16x16x32_bf16 v[6:9], v[174:177], v[198:201], v[6:9]
	v_mfma_f32_16x16x32_bf16 v[22:25], v[166:169], v[206:209], v[22:25]
	v_mfma_f32_16x16x32_bf16 v[18:21], v[174:177], v[206:209], v[18:21]
	v_mfma_f32_16x16x32_bf16 v[38:41], v[166:169], v[214:217], v[38:41]
	v_mfma_f32_16x16x32_bf16 v[26:29], v[174:177], v[214:217], v[26:29]
	s_setprio 0
	s_barrier
	s_mov_b32 m0, s33
	s_add_u32 s46, s10, 0x100000
	global_load_lds_dwordx4 v180, s[10:11]
	ds_read_b128 v[186:189], v142 offset:16384
	ds_read_b128 v[190:193], v142 offset:17408
	s_mov_b32 m0, s34
	s_addc_u32 s47, s11, 0
	global_load_lds_dwordx4 v134, s[10:11]
	ds_read_b128 v[194:197], v142 offset:18432
	ds_read_b128 v[198:201], v142 offset:19456
	s_mov_b32 m0, s35
	s_nop 0
	global_load_lds_dwordx4 v180, s[46:47]
	ds_read_b128 v[202:205], v142 offset:20480
	s_mov_b32 m0, s42
	s_nop 0
	global_load_lds_dwordx4 v134, s[46:47]
	ds_read_b128 v[206:209], v142 offset:21504
	s_add_u32 s50, s16, s4
	s_addc_u32 s51, s17, s5
	s_mov_b32 m0, s27
	s_nop 0
	global_load_lds_dwordx4 v130, s[16:17]
	ds_read_b128 v[210:213], v142 offset:22528
	s_mov_b32 m0, s28
	s_nop 0
	global_load_lds_dwordx4 v132, s[16:17]
	ds_read_b128 v[214:217], v142 offset:23552
	s_waitcnt vmcnt(8)
	s_waitcnt lgkmcnt(0)
	s_barrier
	s_setprio 1
	s_waitcnt lgkmcnt(0)
	v_mfma_f32_16x16x32_bf16 v[94:97], v[146:149], v[186:189], v[94:97]
	v_mfma_f32_16x16x32_bf16 v[86:89], v[154:157], v[186:189], v[86:89]
	v_mfma_f32_16x16x32_bf16 v[102:105], v[146:149], v[194:197], v[102:105]
	v_mfma_f32_16x16x32_bf16 v[98:101], v[154:157], v[194:197], v[98:101]
	v_mfma_f32_16x16x32_bf16 v[110:113], v[146:149], v[202:205], v[110:113]
	v_mfma_f32_16x16x32_bf16 v[106:109], v[154:157], v[202:205], v[106:109]
	v_mfma_f32_16x16x32_bf16 v[126:129], v[146:149], v[210:213], v[126:129]
	v_mfma_f32_16x16x32_bf16 v[122:125], v[154:157], v[210:213], v[122:125]
	v_mfma_f32_16x16x32_bf16 v[94:97], v[150:153], v[190:193], v[94:97]
	v_mfma_f32_16x16x32_bf16 v[86:89], v[158:161], v[190:193], v[86:89]
	v_mfma_f32_16x16x32_bf16 v[102:105], v[150:153], v[198:201], v[102:105]
	v_mfma_f32_16x16x32_bf16 v[98:101], v[158:161], v[198:201], v[98:101]
	v_mfma_f32_16x16x32_bf16 v[110:113], v[150:153], v[206:209], v[110:113]
	v_mfma_f32_16x16x32_bf16 v[106:109], v[158:161], v[206:209], v[106:109]
	v_mfma_f32_16x16x32_bf16 v[126:129], v[150:153], v[214:217], v[126:129]
	v_mfma_f32_16x16x32_bf16 v[122:125], v[158:161], v[214:217], v[122:125]
	s_setprio 0
	s_setprio 1
	v_mfma_f32_16x16x32_bf16 v[58:61], v[162:165], v[186:189], v[58:61]
	v_mfma_f32_16x16x32_bf16 v[46:49], v[170:173], v[186:189], v[46:49]
	v_mfma_f32_16x16x32_bf16 v[74:77], v[162:165], v[194:197], v[74:77]
	v_mfma_f32_16x16x32_bf16 v[66:69], v[170:173], v[194:197], v[66:69]
	v_mfma_f32_16x16x32_bf16 v[90:93], v[162:165], v[202:205], v[90:93]
	v_mfma_f32_16x16x32_bf16 v[82:85], v[170:173], v[202:205], v[82:85]
	v_mfma_f32_16x16x32_bf16 v[118:121], v[162:165], v[210:213], v[118:121]
	v_mfma_f32_16x16x32_bf16 v[114:117], v[170:173], v[210:213], v[114:117]
	v_mfma_f32_16x16x32_bf16 v[58:61], v[166:169], v[190:193], v[58:61]
	v_mfma_f32_16x16x32_bf16 v[46:49], v[174:177], v[190:193], v[46:49]
	v_mfma_f32_16x16x32_bf16 v[74:77], v[166:169], v[198:201], v[74:77]
	v_mfma_f32_16x16x32_bf16 v[66:69], v[174:177], v[198:201], v[66:69]
	v_mfma_f32_16x16x32_bf16 v[90:93], v[166:169], v[206:209], v[90:93]
	v_mfma_f32_16x16x32_bf16 v[82:85], v[174:177], v[206:209], v[82:85]
	v_mfma_f32_16x16x32_bf16 v[118:121], v[166:169], v[214:217], v[118:121]
	v_mfma_f32_16x16x32_bf16 v[114:117], v[174:177], v[214:217], v[114:117]
	s_setprio 0
	s_barrier
; #define PG8_STAGE(bufoff, gbase, voff) do { _Pragma("unroll") for (int _i = 0; _i < 2; ++_i) \
;         __builtin_amdgcn_global_load_lds((const unsigned*)((const char*)(gbase) + (voff)[_i]), (LAS unsigned*)(lds + (bufoff) + ldsw + _i * 8192), 16, 0, 0); } while (0)
; #define PG8_LDA(dst, b, h) do { _Pragma("unroll") for (int m = 0; m < 4; ++m) _Pragma("unroll") for (int k = 0; k < 2; ++k) dst[m][k] = *(const LAS bf16x8*)(lds + PG8_SA(b, h) + aoff + m * 2048 + k * 1024); } while (0)
; #define PG8_LDB(dst, b, h) do { _Pragma("unroll") for (int n = 0; n < 2; ++n) _Pragma("unroll") for (int k = 0; k < 2; ++k) dst[n][k] = *(const LAS bf16x8*)(lds + PG8_SB(b, h) + boff + n * 2048 + k * 1024); } while (0)
; #define PG8_MMA(ai, bj, At, Bt) do { __builtin_amdgcn_s_setprio(1); _Pragma("unroll") for (int m = 0; m < 4; ++m) _Pragma("unroll") for (int n = 0; n < 2; ++n) _Pragma("unroll") for (int k = 0; k < 2; ++k) \
;         acc[ai][bj][m][n] = __builtin_amdgcn_mfma_f32_16x16x32_bf16(Bt[n][k], At[m][k], acc[ai][bj][m][n], 0, 0, 0); __builtin_amdgcn_s_setprio(0); } while (0)
; #define PG8_WAIT_V(n) asm volatile("s_waitcnt vmcnt(" #n ")" ::: "memory")
; #define PG8_WAIT_L(n) asm volatile("s_waitcnt lgkmcnt(" #n ")" ::: "memory")
; #define PG8_BAR __builtin_amdgcn_s_barrier()
; #define PG8_SCHED __builtin_amdgcn_sched_barrier(0)
; template <class Epi, class Sched, bool ALIGN_EPI, class Hook = NoHook>
; __device__ __forceinline__ void gemm_phase(LAS unsigned char* lds, const Gemm g, const Sched& S, const Epi& E, const Hook& H = Hook()) {
;     ...
;             PG8_LDB(B0, 1, 0); PG8_LDB(B1, 1, 1); PG8_SCHED; PG8_LDA(At, 1, 0); PG8_STAGE(PG8_SA(0, 1), a2 + hA, voffA);
;             PG8_WAIT_V(8); PG8_WAIT_L(0); PG8_BAR; PG8_MMA(0, 0, At, B0); PG8_MMA(0, 1, At, B1); PG8_BAR; PG8_SCHED;
;             PG8_LDA(At, 1, 1); PG8_STAGE(PG8_SB(1, 0), b3, voffB); PG8_STAGE(PG8_SB(1, 1), b3 + hB, voffB); PG8_STAGE(PG8_SA(1, 0), a3, voffA);
;             PG8_WAIT_V(8); PG8_WAIT_L(0); PG8_BAR; PG8_MMA(1, 0, At, B0); PG8_MMA(1, 1, At, B1); PG8_BAR; PG8_SCHED;
;         }
;         if constexpr (Hook::ON) H.after(te, acc, cur, wr, wc, fr, fq);
;         }
;         if constexpr (ALIGN_EPI) { if (wr == 0) PG8_BAR; }
	s_add_u32 s16, s16, 0x100000
	s_addc_u32 s17, s17, 0
	s_mov_b32 m0, s29
	s_nop 0
	global_load_lds_dwordx4 v130, s[16:17]
	ds_read_b128 v[146:149], v143
	ds_read_b128 v[150:153], v143 offset:1024
	ds_read_b128 v[154:157], v143 offset:2048
	ds_read_b128 v[158:161], v143 offset:3072
	ds_read_b128 v[162:165], v144
	ds_read_b128 v[166:169], v144 offset:1024
	ds_read_b128 v[170:173], v144 offset:2048
	ds_read_b128 v[174:177], v144 offset:3072
	s_mov_b32 m0, s39
	s_nop 0
	global_load_lds_dwordx4 v132, s[16:17]
	ds_read_b128 v[186:189], v142 offset:32768
	ds_read_b128 v[190:193], v142 offset:33792
	ds_read_b128 v[194:197], v142 offset:34816
	ds_read_b128 v[198:201], v142 offset:35840
	ds_read_b128 v[202:205], v142 offset:36864
	ds_read_b128 v[206:209], v142 offset:37888
	ds_read_b128 v[210:213], v142 offset:38912
	ds_read_b128 v[214:217], v142 offset:39936
	s_waitcnt vmcnt(8)
	s_waitcnt lgkmcnt(0)
	s_barrier
	s_setprio 1
	s_waitcnt lgkmcnt(0)
	v_mfma_f32_16x16x32_bf16 v[54:57], v[146:149], v[186:189], v[54:57]
	v_mfma_f32_16x16x32_bf16 v[34:37], v[154:157], v[186:189], v[34:37]
	v_mfma_f32_16x16x32_bf16 v[42:45], v[146:149], v[194:197], v[42:45]
	v_mfma_f32_16x16x32_bf16 v[30:33], v[154:157], v[194:197], v[30:33]
	v_mfma_f32_16x16x32_bf16 v[62:65], v[146:149], v[202:205], v[62:65]
	v_mfma_f32_16x16x32_bf16 v[50:53], v[154:157], v[202:205], v[50:53]
	v_mfma_f32_16x16x32_bf16 v[78:81], v[146:149], v[210:213], v[78:81]
	v_mfma_f32_16x16x32_bf16 v[70:73], v[154:157], v[210:213], v[70:73]
	v_mfma_f32_16x16x32_bf16 v[54:57], v[150:153], v[190:193], v[54:57]
	v_mfma_f32_16x16x32_bf16 v[34:37], v[158:161], v[190:193], v[34:37]
	v_mfma_f32_16x16x32_bf16 v[42:45], v[150:153], v[198:201], v[42:45]
	v_mfma_f32_16x16x32_bf16 v[30:33], v[158:161], v[198:201], v[30:33]
	v_mfma_f32_16x16x32_bf16 v[62:65], v[150:153], v[206:209], v[62:65]
	v_mfma_f32_16x16x32_bf16 v[50:53], v[158:161], v[206:209], v[50:53]
	v_mfma_f32_16x16x32_bf16 v[78:81], v[150:153], v[214:217], v[78:81]
	v_mfma_f32_16x16x32_bf16 v[70:73], v[158:161], v[214:217], v[70:73]
	s_setprio 0
	s_setprio 1
	v_mfma_f32_16x16x32_bf16 v[10:13], v[162:165], v[186:189], v[10:13]
	v_mfma_f32_16x16x32_bf16 v[2:5], v[170:173], v[186:189], v[2:5]
	v_mfma_f32_16x16x32_bf16 v[14:17], v[162:165], v[194:197], v[14:17]
	v_mfma_f32_16x16x32_bf16 v[6:9], v[170:173], v[194:197], v[6:9]
	v_mfma_f32_16x16x32_bf16 v[22:25], v[162:165], v[202:205], v[22:25]
	v_mfma_f32_16x16x32_bf16 v[18:21], v[170:173], v[202:205], v[18:21]
	v_mfma_f32_16x16x32_bf16 v[38:41], v[162:165], v[210:213], v[38:41]
	v_mfma_f32_16x16x32_bf16 v[26:29], v[170:173], v[210:213], v[26:29]
	v_mfma_f32_16x16x32_bf16 v[10:13], v[166:169], v[190:193], v[10:13]
	v_mfma_f32_16x16x32_bf16 v[2:5], v[174:177], v[190:193], v[2:5]
	v_mfma_f32_16x16x32_bf16 v[14:17], v[166:169], v[198:201], v[14:17]
	v_mfma_f32_16x16x32_bf16 v[6:9], v[174:177], v[198:201], v[6:9]
	v_mfma_f32_16x16x32_bf16 v[22:25], v[166:169], v[206:209], v[22:25]
	v_mfma_f32_16x16x32_bf16 v[18:21], v[174:177], v[206:209], v[18:21]
	v_mfma_f32_16x16x32_bf16 v[38:41], v[166:169], v[214:217], v[38:41]
	v_mfma_f32_16x16x32_bf16 v[26:29], v[174:177], v[214:217], v[26:29]
	s_setprio 0
	s_barrier
	s_mov_b32 m0, s36
	s_add_u32 s48, s10, s4
	s_addc_u32 s49, s11, s5
	s_add_u32 s10, s10, 0x100080
	global_load_lds_dwordx4 v180, s[48:49]
	ds_read_b128 v[186:189], v142 offset:49152
	ds_read_b128 v[190:193], v142 offset:50176
	s_mov_b32 m0, s43
	s_addc_u32 s11, s11, 0
	global_load_lds_dwordx4 v134, s[48:49]
	ds_read_b128 v[194:197], v142 offset:51200
	ds_read_b128 v[198:201], v142 offset:52224
	s_mov_b32 m0, s37
	s_nop 0
	global_load_lds_dwordx4 v180, s[10:11]
	ds_read_b128 v[202:205], v142 offset:53248
	s_mov_b32 m0, s44
	s_nop 0
	global_load_lds_dwordx4 v134, s[10:11]
	ds_read_b128 v[206:209], v142 offset:54272
	s_mov_b32 m0, s40
	s_nop 0
	global_load_lds_dwordx4 v130, s[50:51]
	ds_read_b128 v[210:213], v142 offset:55296
	s_mov_b32 m0, s41
	s_nop 0
	global_load_lds_dwordx4 v132, s[50:51]
	ds_read_b128 v[214:217], v142 offset:56320
	s_waitcnt vmcnt(8)
	s_waitcnt lgkmcnt(0)
	s_barrier
	s_setprio 1
	s_waitcnt lgkmcnt(0)
	v_mfma_f32_16x16x32_bf16 v[94:97], v[146:149], v[186:189], v[94:97]
	v_mfma_f32_16x16x32_bf16 v[86:89], v[154:157], v[186:189], v[86:89]
	v_mfma_f32_16x16x32_bf16 v[102:105], v[146:149], v[194:197], v[102:105]
	v_mfma_f32_16x16x32_bf16 v[98:101], v[154:157], v[194:197], v[98:101]
	v_mfma_f32_16x16x32_bf16 v[110:113], v[146:149], v[202:205], v[110:113]
	v_mfma_f32_16x16x32_bf16 v[106:109], v[154:157], v[202:205], v[106:109]
	v_mfma_f32_16x16x32_bf16 v[126:129], v[146:149], v[210:213], v[126:129]
	v_mfma_f32_16x16x32_bf16 v[122:125], v[154:157], v[210:213], v[122:125]
	v_mfma_f32_16x16x32_bf16 v[94:97], v[150:153], v[190:193], v[94:97]
	v_mfma_f32_16x16x32_bf16 v[86:89], v[158:161], v[190:193], v[86:89]
	v_mfma_f32_16x16x32_bf16 v[102:105], v[150:153], v[198:201], v[102:105]
	v_mfma_f32_16x16x32_bf16 v[98:101], v[158:161], v[198:201], v[98:101]
	v_mfma_f32_16x16x32_bf16 v[110:113], v[150:153], v[206:209], v[110:113]
	v_mfma_f32_16x16x32_bf16 v[106:109], v[158:161], v[206:209], v[106:109]
	v_mfma_f32_16x16x32_bf16 v[126:129], v[150:153], v[214:217], v[126:129]
	v_mfma_f32_16x16x32_bf16 v[122:125], v[158:161], v[214:217], v[122:125]
	s_setprio 0
	s_setprio 1
	v_mfma_f32_16x16x32_bf16 v[58:61], v[162:165], v[186:189], v[58:61]
	v_mfma_f32_16x16x32_bf16 v[46:49], v[170:173], v[186:189], v[46:49]
	v_mfma_f32_16x16x32_bf16 v[74:77], v[162:165], v[194:197], v[74:77]
	v_mfma_f32_16x16x32_bf16 v[66:69], v[170:173], v[194:197], v[66:69]
	v_mfma_f32_16x16x32_bf16 v[90:93], v[162:165], v[202:205], v[90:93]
	v_mfma_f32_16x16x32_bf16 v[82:85], v[170:173], v[202:205], v[82:85]
	v_mfma_f32_16x16x32_bf16 v[118:121], v[162:165], v[210:213], v[118:121]
	v_mfma_f32_16x16x32_bf16 v[114:117], v[170:173], v[210:213], v[114:117]
	v_mfma_f32_16x16x32_bf16 v[58:61], v[166:169], v[190:193], v[58:61]
	v_mfma_f32_16x16x32_bf16 v[46:49], v[174:177], v[190:193], v[46:49]
	v_mfma_f32_16x16x32_bf16 v[74:77], v[166:169], v[198:201], v[74:77]
	v_mfma_f32_16x16x32_bf16 v[66:69], v[174:177], v[198:201], v[66:69]
	v_mfma_f32_16x16x32_bf16 v[90:93], v[166:169], v[206:209], v[90:93]
	v_mfma_f32_16x16x32_bf16 v[82:85], v[174:177], v[206:209], v[82:85]
	v_mfma_f32_16x16x32_bf16 v[118:121], v[166:169], v[214:217], v[118:121]
	v_mfma_f32_16x16x32_bf16 v[114:117], v[174:177], v[214:217], v[114:117]
	s_setprio 0
	s_barrier
	s_add_i32 s18, s18, 2
	s_add_u32 s6, s6, 0x100
	s_addc_u32 s7, s7, 0
	s_cmp_gt_u32 s18, 61
	s_cbranch_scc0 .LBB0_896
	s_cmpk_lt_u32 s22, 0x100
	s_cbranch_scc0 .LBB0_899
	s_barrier

; #define PG8_STAGE(bufoff, gbase, voff) do { _Pragma("unroll") for (int _i = 0; _i < 2; ++_i) \
;         __builtin_amdgcn_global_load_lds((const unsigned*)((const char*)(gbase) + (voff)[_i]), (LAS unsigned*)(lds + (bufoff) + ldsw + _i * 8192), 16, 0, 0); } while (0)
; #define PG8_LDA(dst, b, h) do { _Pragma("unroll") for (int m = 0; m < 4; ++m) _Pragma("unroll") for (int k = 0; k < 2; ++k) dst[m][k] = *(const LAS bf16x8*)(lds + PG8_SA(b, h) + aoff + m * 2048 + k * 1024); } while (0)
; #define PG8_LDB(dst, b, h) do { _Pragma("unroll") for (int n = 0; n < 2; ++n) _Pragma("unroll") for (int k = 0; k < 2; ++k) dst[n][k] = *(const LAS bf16x8*)(lds + PG8_SB(b, h) + boff + n * 2048 + k * 1024); } while (0)
; #define PG8_MMA(ai, bj, At, Bt) do { __builtin_amdgcn_s_setprio(1); _Pragma("unroll") for (int m = 0; m < 4; ++m) _Pragma("unroll") for (int n = 0; n < 2; ++n) _Pragma("unroll") for (int k = 0; k < 2; ++k) \
;         acc[ai][bj][m][n] = __builtin_amdgcn_mfma_f32_16x16x32_bf16(Bt[n][k], At[m][k], acc[ai][bj][m][n], 0, 0, 0); __builtin_amdgcn_s_setprio(0); } while (0)
; #define PG8_WAIT_V(n) asm volatile("s_waitcnt vmcnt(" #n ")" ::: "memory")
; #define PG8_WAIT_L(n) asm volatile("s_waitcnt lgkmcnt(" #n ")" ::: "memory")
; #define PG8_BAR __builtin_amdgcn_s_barrier()
; template <class Epi, class Sched, bool ALIGN_EPI, class Hook = NoHook>
; __device__ __forceinline__ void gemm_phase(LAS unsigned char* lds, const Gemm g, const Sched& S, const Epi& E, const Hook& H = Hook()) {
;     ...
;             const bool last = (t == nt - 2);
;             const char* a1 = cA + (size_t)(t + 1) * kstep;
;             const char* a2 = last ? nA : cA + (size_t)(t + 2) * kstep; const char* b2 = last ? nB : cB + (size_t)(t + 2) * kstep;
;             const char* a3 = a2 + kstep; const char* b3 = b2 + kstep;
;             if (last && has_next) S.a_ready(nxt);
;             PG8_LDB(B0, 0, 0); PG8_LDB(B1, 0, 1); PG8_SCHED; PG8_LDA(At, 0, 0); PG8_STAGE(PG8_SA(1, 1), a1 + hA, voffA);
;             PG8_WAIT_V(8); PG8_WAIT_L(0); PG8_BAR; PG8_MMA(0, 0, At, B0); PG8_MMA(0, 1, At, B1); PG8_BAR; PG8_SCHED;
;             PG8_LDA(At, 0, 1); PG8_STAGE(PG8_SB(0, 0), b2, voffB); PG8_STAGE(PG8_SB(0, 1), b2 + hB, voffB); PG8_STAGE(PG8_SA(0, 0), a2, voffA);
;             PG8_WAIT_V(8); PG8_WAIT_L(0); PG8_BAR; PG8_MMA(1, 0, At, B0); PG8_MMA(1, 1, At, B1); PG8_BAR; PG8_SCHED;
.LBB0_1001:
	s_add_u32 s42, s6, 0x100
	s_addc_u32 s43, s7, 0
	s_cmp_eq_u32 s70, 60
	s_cselect_b32 s47, s35, s43
	s_cselect_b32 s46, s66, s42
	s_cselect_b32 s45, s31, s69
	s_cselect_b32 s44, s67, s68
	s_add_i32 m0, s51, 0xc000
	s_nop 0
	global_load_lds_dwordx4 v236, s[6:7]
	ds_read_b128 v[106:109], v246
	ds_read_b128 v[110:113], v246 offset:1024
	ds_read_b128 v[114:117], v246 offset:2048
	ds_read_b128 v[118:121], v246 offset:3072
	ds_read_b128 v[122:125], v247
	ds_read_b128 v[126:129], v247 offset:1024
	ds_read_b128 v[130:133], v247 offset:2048
	ds_read_b128 v[134:137], v247 offset:3072
	s_add_i32 m0, s51, 0xe000
	s_nop 0
	global_load_lds_dwordx4 v238, s[6:7]
	ds_read_b128 v[138:141], v248
	ds_read_b128 v[142:145], v248 offset:1024
	ds_read_b128 v[146:149], v248 offset:2048
	ds_read_b128 v[150:153], v248 offset:3072
	ds_read_b128 v[154:157], v248 offset:4096
	ds_read_b128 v[158:161], v248 offset:5120
	ds_read_b128 v[162:165], v248 offset:6144
	ds_read_b128 v[170:173], v248 offset:7168
	s_waitcnt vmcnt(8)
	s_waitcnt lgkmcnt(0)
	s_barrier
	s_setprio 1
	s_waitcnt lgkmcnt(0)
	v_mfma_f32_16x16x32_bf16 v[190:193], v[106:109], v[138:141], v[190:193]
	v_mfma_f32_16x16x32_bf16 v[178:181], v[114:117], v[138:141], v[178:181]
	v_mfma_f32_16x16x32_bf16 v[182:185], v[106:109], v[146:149], v[182:185]
	v_mfma_f32_16x16x32_bf16 v[98:101], v[114:117], v[146:149], v[98:101]
	v_mfma_f32_16x16x32_bf16 v[102:105], v[106:109], v[154:157], v[102:105]
	v_mfma_f32_16x16x32_bf16 v[86:89], v[114:117], v[154:157], v[86:89]
	v_mfma_f32_16x16x32_bf16 v[78:81], v[106:109], v[162:165], v[78:81]
	v_mfma_f32_16x16x32_bf16 v[70:73], v[114:117], v[162:165], v[70:73]
	v_mfma_f32_16x16x32_bf16 v[190:193], v[110:113], v[142:145], v[190:193]
	v_mfma_f32_16x16x32_bf16 v[178:181], v[118:121], v[142:145], v[178:181]
	v_mfma_f32_16x16x32_bf16 v[182:185], v[110:113], v[150:153], v[182:185]
	v_mfma_f32_16x16x32_bf16 v[98:101], v[118:121], v[150:153], v[98:101]
	v_mfma_f32_16x16x32_bf16 v[102:105], v[110:113], v[158:161], v[102:105]
	v_mfma_f32_16x16x32_bf16 v[86:89], v[118:121], v[158:161], v[86:89]
	v_mfma_f32_16x16x32_bf16 v[78:81], v[110:113], v[170:173], v[78:81]
	v_mfma_f32_16x16x32_bf16 v[70:73], v[118:121], v[170:173], v[70:73]
	s_setprio 0
	s_setprio 1
	v_mfma_f32_16x16x32_bf16 v[186:189], v[122:125], v[138:141], v[186:189]
	v_mfma_f32_16x16x32_bf16 v[138:141], v[130:133], v[138:141], v[174:177]
	v_mfma_f32_16x16x32_bf16 v[94:97], v[130:133], v[146:149], v[94:97]
	v_mfma_f32_16x16x32_bf16 v[90:93], v[122:125], v[154:157], v[90:93]
	v_mfma_f32_16x16x32_bf16 v[82:85], v[130:133], v[154:157], v[82:85]
	v_mfma_f32_16x16x32_bf16 v[74:77], v[122:125], v[162:165], v[74:77]
	v_mfma_f32_16x16x32_bf16 v[66:69], v[130:133], v[162:165], v[66:69]
	v_mfma_f32_16x16x32_bf16 v[186:189], v[126:129], v[142:145], v[186:189]
	v_mfma_f32_16x16x32_bf16 v[138:141], v[134:137], v[142:145], v[138:141]
	v_mfma_f32_16x16x32_bf16 v[142:145], v[122:125], v[146:149], v[166:169]
	v_mfma_f32_16x16x32_bf16 v[94:97], v[134:137], v[150:153], v[94:97]
	v_mfma_f32_16x16x32_bf16 v[90:93], v[126:129], v[158:161], v[90:93]
	v_mfma_f32_16x16x32_bf16 v[82:85], v[134:137], v[158:161], v[82:85]
	v_mfma_f32_16x16x32_bf16 v[74:77], v[126:129], v[170:173], v[74:77]
	v_mfma_f32_16x16x32_bf16 v[66:69], v[134:137], v[170:173], v[66:69]
	v_mfma_f32_16x16x32_bf16 v[142:145], v[126:129], v[150:153], v[142:145]
	s_setprio 0
	s_barrier
	s_add_i32 s6, s63, s29
	s_mov_b32 m0, s6
	s_nop 0
	global_load_lds_dwordx4 v232, s[44:45]
	ds_read_b128 v[146:149], v248 offset:16384
	ds_read_b128 v[150:153], v248 offset:17408
	s_add_i32 m0, s6, 0x2000
	s_add_u32 s6, s44, 0x100000
	s_addc_u32 s7, s45, 0
	s_add_i32 s71, s64, s29
	global_load_lds_dwordx4 v228, s[44:45]
	ds_read_b128 v[154:157], v248 offset:18432
	ds_read_b128 v[158:161], v248 offset:19456
	s_mov_b32 m0, s71
	s_nop 0
	global_load_lds_dwordx4 v232, s[6:7]
	ds_read_b128 v[162:165], v248 offset:20480
	s_add_i32 m0, s71, 0x2000
	s_nop 0
	global_load_lds_dwordx4 v228, s[6:7]
	ds_read_b128 v[166:169], v248 offset:21504
	s_mov_b32 m0, s51
	s_nop 0
	global_load_lds_dwordx4 v234, s[46:47]
	ds_read_b128 v[170:173], v248 offset:22528
	s_mov_b32 m0, s52
	s_nop 0
	global_load_lds_dwordx4 v230, s[46:47]
	ds_read_b128 v[174:177], v248 offset:23552
	s_waitcnt vmcnt(8)
	s_waitcnt lgkmcnt(0)
	s_barrier
	s_setprio 1
	s_waitcnt lgkmcnt(0)
	v_mfma_f32_16x16x32_bf16 v[62:65], v[106:109], v[146:149], v[62:65]
	v_mfma_f32_16x16x32_bf16 v[54:57], v[114:117], v[146:149], v[54:57]
	v_mfma_f32_16x16x32_bf16 v[46:49], v[106:109], v[154:157], v[46:49]
	v_mfma_f32_16x16x32_bf16 v[22:25], v[114:117], v[154:157], v[22:25]
	v_mfma_f32_16x16x32_bf16 v[42:45], v[106:109], v[162:165], v[42:45]
	v_mfma_f32_16x16x32_bf16 v[10:13], v[114:117], v[162:165], v[10:13]
	v_mfma_f32_16x16x32_bf16 v[38:41], v[106:109], v[170:173], v[38:41]
	v_mfma_f32_16x16x32_bf16 v[14:17], v[114:117], v[170:173], v[14:17]
	v_mfma_f32_16x16x32_bf16 v[62:65], v[110:113], v[150:153], v[62:65]
	v_mfma_f32_16x16x32_bf16 v[54:57], v[118:121], v[150:153], v[54:57]
	v_mfma_f32_16x16x32_bf16 v[46:49], v[110:113], v[158:161], v[46:49]
	v_mfma_f32_16x16x32_bf16 v[22:25], v[118:121], v[158:161], v[22:25]
	v_mfma_f32_16x16x32_bf16 v[42:45], v[110:113], v[166:169], v[42:45]
	v_mfma_f32_16x16x32_bf16 v[10:13], v[118:121], v[166:169], v[10:13]
	v_mfma_f32_16x16x32_bf16 v[38:41], v[110:113], v[174:177], v[38:41]
	v_mfma_f32_16x16x32_bf16 v[14:17], v[118:121], v[174:177], v[14:17]
	s_setprio 0
	s_setprio 1
	v_mfma_f32_16x16x32_bf16 v[58:61], v[122:125], v[146:149], v[58:61]
	v_mfma_f32_16x16x32_bf16 v[50:53], v[130:133], v[146:149], v[50:53]
	v_mfma_f32_16x16x32_bf16 v[34:37], v[122:125], v[154:157], v[34:37]
	v_mfma_f32_16x16x32_bf16 v[18:21], v[130:133], v[154:157], v[18:21]
	v_mfma_f32_16x16x32_bf16 v[30:33], v[122:125], v[162:165], v[30:33]
	v_mfma_f32_16x16x32_bf16 v[2:5], v[130:133], v[162:165], v[2:5]
	v_mfma_f32_16x16x32_bf16 v[26:29], v[122:125], v[170:173], v[26:29]
	v_mfma_f32_16x16x32_bf16 v[6:9], v[130:133], v[170:173], v[6:9]
	v_mfma_f32_16x16x32_bf16 v[58:61], v[126:129], v[150:153], v[58:61]
	v_mfma_f32_16x16x32_bf16 v[50:53], v[134:137], v[150:153], v[50:53]
	v_mfma_f32_16x16x32_bf16 v[34:37], v[126:129], v[158:161], v[34:37]
	v_mfma_f32_16x16x32_bf16 v[18:21], v[134:137], v[158:161], v[18:21]
	v_mfma_f32_16x16x32_bf16 v[30:33], v[126:129], v[166:169], v[30:33]
	v_mfma_f32_16x16x32_bf16 v[2:5], v[134:137], v[166:169], v[2:5]
	v_mfma_f32_16x16x32_bf16 v[26:29], v[126:129], v[174:177], v[26:29]
	v_mfma_f32_16x16x32_bf16 v[6:9], v[134:137], v[174:177], v[6:9]
	s_setprio 0
	s_barrier
; #define PG8_STAGE(bufoff, gbase, voff) do { _Pragma("unroll") for (int _i = 0; _i < 2; ++_i) \
;         __builtin_amdgcn_global_load_lds((const unsigned*)((const char*)(gbase) + (voff)[_i]), (LAS unsigned*)(lds + (bufoff) + ldsw + _i * 8192), 16, 0, 0); } while (0)
; #define PG8_LDA(dst, b, h) do { _Pragma("unroll") for (int m = 0; m < 4; ++m) _Pragma("unroll") for (int k = 0; k < 2; ++k) dst[m][k] = *(const LAS bf16x8*)(lds + PG8_SA(b, h) + aoff + m * 2048 + k * 1024); } while (0)
; #define PG8_LDB(dst, b, h) do { _Pragma("unroll") for (int n = 0; n < 2; ++n) _Pragma("unroll") for (int k = 0; k < 2; ++k) dst[n][k] = *(const LAS bf16x8*)(lds + PG8_SB(b, h) + boff + n * 2048 + k * 1024); } while (0)
; #define PG8_MMA(ai, bj, At, Bt) do { __builtin_amdgcn_s_setprio(1); _Pragma("unroll") for (int m = 0; m < 4; ++m) _Pragma("unroll") for (int n = 0; n < 2; ++n) _Pragma("unroll") for (int k = 0; k < 2; ++k) \
;         acc[ai][bj][m][n] = __builtin_amdgcn_mfma_f32_16x16x32_bf16(Bt[n][k], At[m][k], acc[ai][bj][m][n], 0, 0, 0); __builtin_amdgcn_s_setprio(0); } while (0)
; #define PG8_WAIT_V(n) asm volatile("s_waitcnt vmcnt(" #n ")" ::: "memory")
; #define PG8_WAIT_L(n) asm volatile("s_waitcnt lgkmcnt(" #n ")" ::: "memory")
; #define PG8_BAR __builtin_amdgcn_s_barrier()
; #define PG8_SCHED __builtin_amdgcn_sched_barrier(0)
; template <class Epi, class Sched, bool ALIGN_EPI, class Hook = NoHook>
; __device__ __forceinline__ void gemm_phase(LAS unsigned char* lds, const Gemm g, const Sched& S, const Epi& E, const Hook& H = Hook()) {
;     ...
;             PG8_LDB(B0, 1, 0); PG8_LDB(B1, 1, 1); PG8_SCHED; PG8_LDA(At, 1, 0); PG8_STAGE(PG8_SA(0, 1), a2 + hA, voffA);
;             PG8_WAIT_V(8); PG8_WAIT_L(0); PG8_BAR; PG8_MMA(0, 0, At, B0); PG8_MMA(0, 1, At, B1); PG8_BAR; PG8_SCHED;
;             PG8_LDA(At, 1, 1); PG8_STAGE(PG8_SB(1, 0), b3, voffB); PG8_STAGE(PG8_SB(1, 1), b3 + hB, voffB); PG8_STAGE(PG8_SA(1, 0), a3, voffA);
;             PG8_WAIT_V(8); PG8_WAIT_L(0); PG8_BAR; PG8_MMA(1, 0, At, B0); PG8_MMA(1, 1, At, B1); PG8_BAR; PG8_SCHED;
;         }
;         if constexpr (Hook::ON) H.after(te, acc, cur, wr, wc, fr, fq);
;         }
;         if constexpr (ALIGN_EPI) { if (wr == 0) PG8_BAR; }
	s_add_i32 s71, 0, 0x18000
	s_add_i32 s72, 0, 0x1c000
	v_add_u32_e32 v118, s71, v245
	v_add_u32_e32 v134, s72, v245
	s_add_u32 s6, s46, 0x8000
	s_addc_u32 s7, s47, 0
	s_mov_b32 m0, s53
	s_nop 0
	global_load_lds_dwordx4 v234, s[6:7]
	ds_read_b128 v[106:109], v118
	ds_read_b128 v[110:113], v118 offset:1024
	ds_read_b128 v[114:117], v118 offset:2048
	ds_read_b128 v[118:121], v118 offset:3072
	ds_read_b128 v[122:125], v134
	ds_read_b128 v[126:129], v134 offset:1024
	ds_read_b128 v[130:133], v134 offset:2048
	ds_read_b128 v[134:137], v134 offset:3072
	s_mov_b32 m0, s54
	s_nop 0
	global_load_lds_dwordx4 v230, s[6:7]
	ds_read_b128 v[146:149], v248 offset:32768
	ds_read_b128 v[150:153], v248 offset:33792
	ds_read_b128 v[154:157], v248 offset:34816
	ds_read_b128 v[158:161], v248 offset:35840
	ds_read_b128 v[162:165], v248 offset:36864
	ds_read_b128 v[170:173], v248 offset:37888
	ds_read_b128 v[194:197], v248 offset:38912
	ds_read_b128 v[198:201], v248 offset:39936
	s_waitcnt vmcnt(8)
	s_waitcnt lgkmcnt(0)
	s_barrier
	s_setprio 1
	s_waitcnt lgkmcnt(0)
	v_mfma_f32_16x16x32_bf16 v[166:169], v[106:109], v[146:149], v[190:193]
	v_mfma_f32_16x16x32_bf16 v[190:193], v[110:113], v[150:153], v[166:169]
	v_mfma_f32_16x16x32_bf16 v[166:169], v[114:117], v[146:149], v[178:181]
	v_mfma_f32_16x16x32_bf16 v[178:181], v[118:121], v[150:153], v[166:169]
	v_mfma_f32_16x16x32_bf16 v[166:169], v[106:109], v[154:157], v[182:185]
	v_mfma_f32_16x16x32_bf16 v[98:101], v[114:117], v[154:157], v[98:101]
	v_mfma_f32_16x16x32_bf16 v[102:105], v[106:109], v[162:165], v[102:105]
	v_mfma_f32_16x16x32_bf16 v[86:89], v[114:117], v[162:165], v[86:89]
	v_mfma_f32_16x16x32_bf16 v[78:81], v[106:109], v[194:197], v[78:81]
	v_mfma_f32_16x16x32_bf16 v[70:73], v[114:117], v[194:197], v[70:73]
	v_mfma_f32_16x16x32_bf16 v[182:185], v[110:113], v[158:161], v[166:169]
	v_mfma_f32_16x16x32_bf16 v[98:101], v[118:121], v[158:161], v[98:101]
	v_mfma_f32_16x16x32_bf16 v[102:105], v[110:113], v[170:173], v[102:105]
	v_mfma_f32_16x16x32_bf16 v[86:89], v[118:121], v[170:173], v[86:89]
	v_mfma_f32_16x16x32_bf16 v[78:81], v[110:113], v[198:201], v[78:81]
	v_mfma_f32_16x16x32_bf16 v[70:73], v[118:121], v[198:201], v[70:73]
	s_setprio 0
	s_setprio 1
	v_mfma_f32_16x16x32_bf16 v[138:141], v[130:133], v[146:149], v[138:141]
	v_mfma_f32_16x16x32_bf16 v[166:169], v[122:125], v[146:149], v[186:189]
	v_mfma_f32_16x16x32_bf16 v[174:177], v[134:137], v[150:153], v[138:141]
	v_mfma_f32_16x16x32_bf16 v[138:141], v[122:125], v[154:157], v[142:145]
	v_mfma_f32_16x16x32_bf16 v[94:97], v[130:133], v[154:157], v[94:97]
	v_mfma_f32_16x16x32_bf16 v[90:93], v[122:125], v[162:165], v[90:93]
	v_mfma_f32_16x16x32_bf16 v[82:85], v[130:133], v[162:165], v[82:85]
	v_mfma_f32_16x16x32_bf16 v[74:77], v[122:125], v[194:197], v[74:77]
	v_mfma_f32_16x16x32_bf16 v[66:69], v[130:133], v[194:197], v[66:69]
	v_mfma_f32_16x16x32_bf16 v[186:189], v[126:129], v[150:153], v[166:169]
	v_mfma_f32_16x16x32_bf16 v[166:169], v[126:129], v[158:161], v[138:141]
	v_mfma_f32_16x16x32_bf16 v[94:97], v[134:137], v[158:161], v[94:97]
	v_mfma_f32_16x16x32_bf16 v[90:93], v[126:129], v[170:173], v[90:93]
	v_mfma_f32_16x16x32_bf16 v[82:85], v[134:137], v[170:173], v[82:85]
	v_mfma_f32_16x16x32_bf16 v[74:77], v[126:129], v[198:201], v[74:77]
	v_mfma_f32_16x16x32_bf16 v[66:69], v[134:137], v[198:201], v[66:69]
	s_setprio 0
	s_barrier
	s_add_i32 s6, s71, s29
	s_add_u32 s74, s44, s14
	s_addc_u32 s75, s45, s15
	s_mov_b32 m0, s6
	s_nop 0
	global_load_lds_dwordx4 v232, s[74:75]
	ds_read_b128 v[138:141], v248 offset:49152
	ds_read_b128 v[142:145], v248 offset:50176
	s_add_i32 m0, s6, 0x2000
	s_add_u32 s6, s44, 0x100080
	s_addc_u32 s7, s45, 0
	s_add_i32 s44, s72, s29
	global_load_lds_dwordx4 v228, s[74:75]
	ds_read_b128 v[146:149], v248 offset:51200
	ds_read_b128 v[150:153], v248 offset:52224
	s_mov_b32 m0, s44
	s_nop 0
	global_load_lds_dwordx4 v232, s[6:7]
	ds_read_b128 v[154:157], v248 offset:53248
	s_add_i32 m0, s44, 0x2000
	s_nop 0
	global_load_lds_dwordx4 v228, s[6:7]
	ds_read_b128 v[158:161], v248 offset:54272
	s_add_u32 s78, s46, s14
	s_addc_u32 s79, s47, s15
	s_mov_b32 m0, s57
	s_nop 0
	global_load_lds_dwordx4 v234, s[78:79]
	ds_read_b128 v[162:165], v248 offset:55296
	s_mov_b32 m0, s58
	s_nop 0
	global_load_lds_dwordx4 v230, s[78:79]
	ds_read_b128 v[170:173], v248 offset:56320
	s_waitcnt vmcnt(8)
	s_waitcnt lgkmcnt(0)
	s_barrier
	s_setprio 1
	s_waitcnt lgkmcnt(0)
	v_mfma_f32_16x16x32_bf16 v[62:65], v[106:109], v[138:141], v[62:65]
	v_mfma_f32_16x16x32_bf16 v[54:57], v[114:117], v[138:141], v[54:57]
	v_mfma_f32_16x16x32_bf16 v[46:49], v[106:109], v[146:149], v[46:49]
	v_mfma_f32_16x16x32_bf16 v[22:25], v[114:117], v[146:149], v[22:25]
	v_mfma_f32_16x16x32_bf16 v[42:45], v[106:109], v[154:157], v[42:45]
	v_mfma_f32_16x16x32_bf16 v[10:13], v[114:117], v[154:157], v[10:13]
	v_mfma_f32_16x16x32_bf16 v[38:41], v[106:109], v[162:165], v[38:41]
	v_mfma_f32_16x16x32_bf16 v[14:17], v[114:117], v[162:165], v[14:17]
	v_mfma_f32_16x16x32_bf16 v[62:65], v[110:113], v[142:145], v[62:65]
	v_mfma_f32_16x16x32_bf16 v[54:57], v[118:121], v[142:145], v[54:57]
	v_mfma_f32_16x16x32_bf16 v[46:49], v[110:113], v[150:153], v[46:49]
	v_mfma_f32_16x16x32_bf16 v[22:25], v[118:121], v[150:153], v[22:25]
	v_mfma_f32_16x16x32_bf16 v[42:45], v[110:113], v[158:161], v[42:45]
	v_mfma_f32_16x16x32_bf16 v[10:13], v[118:121], v[158:161], v[10:13]
	v_mfma_f32_16x16x32_bf16 v[38:41], v[110:113], v[170:173], v[38:41]
	v_mfma_f32_16x16x32_bf16 v[14:17], v[118:121], v[170:173], v[14:17]
	s_setprio 0
	s_setprio 1
	v_mfma_f32_16x16x32_bf16 v[58:61], v[122:125], v[138:141], v[58:61]
	v_mfma_f32_16x16x32_bf16 v[50:53], v[130:133], v[138:141], v[50:53]
	v_mfma_f32_16x16x32_bf16 v[34:37], v[122:125], v[146:149], v[34:37]
	v_mfma_f32_16x16x32_bf16 v[18:21], v[130:133], v[146:149], v[18:21]
	v_mfma_f32_16x16x32_bf16 v[30:33], v[122:125], v[154:157], v[30:33]
	v_mfma_f32_16x16x32_bf16 v[2:5], v[130:133], v[154:157], v[2:5]
	v_mfma_f32_16x16x32_bf16 v[26:29], v[122:125], v[162:165], v[26:29]
	v_mfma_f32_16x16x32_bf16 v[6:9], v[130:133], v[162:165], v[6:9]
	v_mfma_f32_16x16x32_bf16 v[58:61], v[126:129], v[142:145], v[58:61]
	v_mfma_f32_16x16x32_bf16 v[50:53], v[134:137], v[142:145], v[50:53]
	v_mfma_f32_16x16x32_bf16 v[34:37], v[126:129], v[150:153], v[34:37]
	v_mfma_f32_16x16x32_bf16 v[18:21], v[134:137], v[150:153], v[18:21]
	v_mfma_f32_16x16x32_bf16 v[30:33], v[126:129], v[158:161], v[30:33]
	v_mfma_f32_16x16x32_bf16 v[2:5], v[134:137], v[158:161], v[2:5]
	v_mfma_f32_16x16x32_bf16 v[26:29], v[126:129], v[170:173], v[26:29]
	v_mfma_f32_16x16x32_bf16 v[6:9], v[134:137], v[170:173], v[6:9]
	s_setprio 0
	s_barrier
	s_add_i32 s70, s70, 2
	s_add_u32 s68, s68, 0x100
	s_addc_u32 s69, s69, 0
	s_cmp_gt_u32 s70, 61
	s_mov_b64 s[6:7], s[42:43]
	s_cbranch_scc0 .LBB0_1001
	s_and_b64 vcc, exec, s[2:3]
	s_cbranch_vccz .LBB0_1004
	s_barrier

; #define PG8_STAGE(bufoff, gbase, voff) do { _Pragma("unroll") for (int _i = 0; _i < 2; ++_i) \
;         __builtin_amdgcn_global_load_lds((const unsigned*)((const char*)(gbase) + (voff)[_i]), (LAS unsigned*)(lds + (bufoff) + ldsw + _i * 8192), 16, 0, 0); } while (0)
; #define PG8_LDA(dst, b, h) do { _Pragma("unroll") for (int m = 0; m < 4; ++m) _Pragma("unroll") for (int k = 0; k < 2; ++k) dst[m][k] = *(const LAS bf16x8*)(lds + PG8_SA(b, h) + aoff + m * 2048 + k * 1024); } while (0)
; #define PG8_LDB(dst, b, h) do { _Pragma("unroll") for (int n = 0; n < 2; ++n) _Pragma("unroll") for (int k = 0; k < 2; ++k) dst[n][k] = *(const LAS bf16x8*)(lds + PG8_SB(b, h) + boff + n * 2048 + k * 1024); } while (0)
; #define PG8_MMA(ai, bj, At, Bt) do { __builtin_amdgcn_s_setprio(1); _Pragma("unroll") for (int m = 0; m < 4; ++m) _Pragma("unroll") for (int n = 0; n < 2; ++n) _Pragma("unroll") for (int k = 0; k < 2; ++k) \
;         acc[ai][bj][m][n] = __builtin_amdgcn_mfma_f32_16x16x32_bf16(Bt[n][k], At[m][k], acc[ai][bj][m][n], 0, 0, 0); __builtin_amdgcn_s_setprio(0); } while (0)
; #define PG8_WAIT_V(n) asm volatile("s_waitcnt vmcnt(" #n ")" ::: "memory")
; #define PG8_WAIT_L(n) asm volatile("s_waitcnt lgkmcnt(" #n ")" ::: "memory")
; #define PG8_BAR __builtin_amdgcn_s_barrier()
; template <class Epi, class Sched, bool ALIGN_EPI, class Hook = NoHook>
; __device__ __forceinline__ void gemm_phase(LAS unsigned char* lds, const Gemm g, const Sched& S, const Epi& E, const Hook& H = Hook()) {
;     ...
;             const bool last = (t == nt - 2);
;             const char* a1 = cA + (size_t)(t + 1) * kstep;
;             const char* a2 = last ? nA : cA + (size_t)(t + 2) * kstep; const char* b2 = last ? nB : cB + (size_t)(t + 2) * kstep;
;             const char* a3 = a2 + kstep; const char* b3 = b2 + kstep;
;             if (last && has_next) S.a_ready(nxt);
;             PG8_LDB(B0, 0, 0); PG8_LDB(B1, 0, 1); PG8_SCHED; PG8_LDA(At, 0, 0); PG8_STAGE(PG8_SA(1, 1), a1 + hA, voffA);
;             PG8_WAIT_V(8); PG8_WAIT_L(0); PG8_BAR; PG8_MMA(0, 0, At, B0); PG8_MMA(0, 1, At, B1); PG8_BAR; PG8_SCHED;
;             PG8_LDA(At, 0, 1); PG8_STAGE(PG8_SB(0, 0), b2, voffB); PG8_STAGE(PG8_SB(0, 1), b2 + hB, voffB); PG8_STAGE(PG8_SA(0, 0), a2, voffA);
;             PG8_WAIT_V(8); PG8_WAIT_L(0); PG8_BAR; PG8_MMA(1, 0, At, B0); PG8_MMA(1, 1, At, B1); PG8_BAR; PG8_SCHED;
.LBB0_1360:
	s_add_u32 s14, s4, 0xbb050080
	s_addc_u32 s15, s5, -1
	s_cmpk_lg_i32 s41, 0xa8
	s_cselect_b32 s14, s14, 0
	s_cselect_b32 s15, s15, 0
	s_add_u32 s20, s0, s14
	s_addc_u32 s21, s1, s15
	s_add_u32 s14, s12, s14
	s_addc_u32 s15, s13, s15
	s_mov_b32 m0, s42
	ds_read_b128 v[146:149], v1
	ds_read_b128 v[150:153], v1 offset:1024
	ds_read_b128 v[154:157], v1 offset:2048
	ds_read_b128 v[158:161], v1 offset:3072
	ds_read_b128 v[164:167], v142
	ds_read_b128 v[170:173], v142 offset:1024
	ds_read_b128 v[174:177], v142 offset:2048
	ds_read_b128 v[178:181], v142 offset:3072
	v_lshl_add_u64 v[214:215], v[138:139], 0, s[4:5]
	global_load_lds_dwordx4 v[214:215], off
	ds_read_b128 v[182:185], v143
	ds_read_b128 v[186:189], v143 offset:1024
	ds_read_b128 v[190:193], v143 offset:2048
	ds_read_b128 v[194:197], v143 offset:3072
	ds_read_b128 v[198:201], v143 offset:4096
	ds_read_b128 v[202:205], v143 offset:5120
	ds_read_b128 v[206:209], v143 offset:6144
	ds_read_b128 v[210:213], v143 offset:7168
	v_lshl_add_u64 v[214:215], v[140:141], 0, s[4:5]
	s_mov_b32 m0, s43
	s_nop 0
	global_load_lds_dwordx4 v[214:215], off
	s_waitcnt vmcnt(8)
	s_waitcnt lgkmcnt(0)
	s_barrier
	s_setprio 1
	s_waitcnt lgkmcnt(0)
	v_mfma_f32_16x16x32_bf16 v[82:85], v[146:149], v[182:185], v[82:85]
	v_mfma_f32_16x16x32_bf16 v[54:57], v[154:157], v[182:185], v[54:57]
	v_mfma_f32_16x16x32_bf16 v[58:61], v[146:149], v[190:193], v[58:61]
	v_mfma_f32_16x16x32_bf16 v[42:45], v[154:157], v[190:193], v[42:45]
	v_mfma_f32_16x16x32_bf16 v[70:73], v[146:149], v[198:201], v[70:73]
	v_mfma_f32_16x16x32_bf16 v[50:53], v[154:157], v[198:201], v[50:53]
	v_mfma_f32_16x16x32_bf16 v[86:89], v[146:149], v[206:209], v[86:89]
	v_mfma_f32_16x16x32_bf16 v[74:77], v[154:157], v[206:209], v[74:77]
	v_mfma_f32_16x16x32_bf16 v[82:85], v[150:153], v[186:189], v[82:85]
	v_mfma_f32_16x16x32_bf16 v[54:57], v[158:161], v[186:189], v[54:57]
	v_mfma_f32_16x16x32_bf16 v[58:61], v[150:153], v[194:197], v[58:61]
	v_mfma_f32_16x16x32_bf16 v[42:45], v[158:161], v[194:197], v[42:45]
	v_mfma_f32_16x16x32_bf16 v[70:73], v[150:153], v[202:205], v[70:73]
	v_mfma_f32_16x16x32_bf16 v[50:53], v[158:161], v[202:205], v[50:53]
	v_mfma_f32_16x16x32_bf16 v[86:89], v[150:153], v[210:213], v[86:89]
	v_mfma_f32_16x16x32_bf16 v[74:77], v[158:161], v[210:213], v[74:77]
	s_setprio 0
	s_setprio 1
	v_mfma_f32_16x16x32_bf16 v[14:17], v[164:167], v[182:185], v[14:17]
	v_mfma_f32_16x16x32_bf16 v[2:5], v[174:177], v[182:185], v[2:5]
	v_mfma_f32_16x16x32_bf16 v[18:21], v[164:167], v[190:193], v[18:21]
	v_mfma_f32_16x16x32_bf16 v[6:9], v[174:177], v[190:193], v[6:9]
	v_mfma_f32_16x16x32_bf16 v[22:25], v[164:167], v[198:201], v[22:25]
	v_mfma_f32_16x16x32_bf16 v[10:13], v[174:177], v[198:201], v[10:13]
	v_mfma_f32_16x16x32_bf16 v[30:33], v[164:167], v[206:209], v[30:33]
	v_mfma_f32_16x16x32_bf16 v[26:29], v[174:177], v[206:209], v[26:29]
	v_mfma_f32_16x16x32_bf16 v[14:17], v[170:173], v[186:189], v[14:17]
	v_mfma_f32_16x16x32_bf16 v[2:5], v[178:181], v[186:189], v[2:5]
	v_mfma_f32_16x16x32_bf16 v[18:21], v[170:173], v[194:197], v[18:21]
	v_mfma_f32_16x16x32_bf16 v[6:9], v[178:181], v[194:197], v[6:9]
	v_mfma_f32_16x16x32_bf16 v[22:25], v[170:173], v[202:205], v[22:25]
	v_mfma_f32_16x16x32_bf16 v[10:13], v[178:181], v[202:205], v[10:13]
	v_mfma_f32_16x16x32_bf16 v[30:33], v[170:173], v[210:213], v[30:33]
	v_mfma_f32_16x16x32_bf16 v[26:29], v[178:181], v[210:213], v[26:29]
	s_setprio 0
	s_barrier
	s_mov_b32 m0, s44
	s_add_u32 s52, s14, 0x2b0000
	global_load_lds_dwordx4 v132, s[14:15]
	ds_read_b128 v[182:185], v143 offset:16384
	ds_read_b128 v[186:189], v143 offset:17408
	s_mov_b32 m0, s45
	s_addc_u32 s53, s15, 0
	global_load_lds_dwordx4 v136, s[14:15]
	ds_read_b128 v[190:193], v143 offset:18432
	ds_read_b128 v[194:197], v143 offset:19456
	s_mov_b32 m0, s46
	s_nop 0
	global_load_lds_dwordx4 v132, s[52:53]
	ds_read_b128 v[198:201], v143 offset:20480
	s_mov_b32 m0, s47
	s_nop 0
	global_load_lds_dwordx4 v136, s[52:53]
	ds_read_b128 v[202:205], v143 offset:21504
	s_add_u32 s56, s20, s2
	s_addc_u32 s57, s21, s3
	s_mov_b32 m0, s25
	s_nop 0
	global_load_lds_dwordx4 v130, s[20:21]
	ds_read_b128 v[206:209], v143 offset:22528
	s_mov_b32 m0, s27
	s_nop 0
	global_load_lds_dwordx4 v134, s[20:21]
	ds_read_b128 v[210:213], v143 offset:23552
	s_waitcnt vmcnt(8)
	s_waitcnt lgkmcnt(0)
	s_barrier
	s_setprio 1
	s_waitcnt lgkmcnt(0)
	v_mfma_f32_16x16x32_bf16 v[94:97], v[146:149], v[182:185], v[94:97]
	v_mfma_f32_16x16x32_bf16 v[90:93], v[154:157], v[182:185], v[90:93]
	v_mfma_f32_16x16x32_bf16 v[106:109], v[146:149], v[190:193], v[106:109]
	v_mfma_f32_16x16x32_bf16 v[98:101], v[154:157], v[190:193], v[98:101]
	v_mfma_f32_16x16x32_bf16 v[110:113], v[146:149], v[198:201], v[110:113]
	v_mfma_f32_16x16x32_bf16 v[102:105], v[154:157], v[198:201], v[102:105]
	v_mfma_f32_16x16x32_bf16 v[126:129], v[146:149], v[206:209], v[126:129]
	v_mfma_f32_16x16x32_bf16 v[122:125], v[154:157], v[206:209], v[122:125]
	v_mfma_f32_16x16x32_bf16 v[94:97], v[150:153], v[186:189], v[94:97]
	v_mfma_f32_16x16x32_bf16 v[90:93], v[158:161], v[186:189], v[90:93]
	v_mfma_f32_16x16x32_bf16 v[106:109], v[150:153], v[194:197], v[106:109]
	v_mfma_f32_16x16x32_bf16 v[98:101], v[158:161], v[194:197], v[98:101]
	v_mfma_f32_16x16x32_bf16 v[110:113], v[150:153], v[202:205], v[110:113]
	v_mfma_f32_16x16x32_bf16 v[102:105], v[158:161], v[202:205], v[102:105]
	v_mfma_f32_16x16x32_bf16 v[126:129], v[150:153], v[210:213], v[126:129]
	v_mfma_f32_16x16x32_bf16 v[122:125], v[158:161], v[210:213], v[122:125]
	s_setprio 0
	s_setprio 1
	v_mfma_f32_16x16x32_bf16 v[38:41], v[164:167], v[182:185], v[38:41]
	v_mfma_f32_16x16x32_bf16 v[34:37], v[174:177], v[182:185], v[34:37]
	v_mfma_f32_16x16x32_bf16 v[66:69], v[164:167], v[190:193], v[66:69]
	v_mfma_f32_16x16x32_bf16 v[46:49], v[174:177], v[190:193], v[46:49]
	v_mfma_f32_16x16x32_bf16 v[78:81], v[164:167], v[198:201], v[78:81]
	v_mfma_f32_16x16x32_bf16 v[62:65], v[174:177], v[198:201], v[62:65]
	v_mfma_f32_16x16x32_bf16 v[118:121], v[164:167], v[206:209], v[118:121]
	v_mfma_f32_16x16x32_bf16 v[114:117], v[174:177], v[206:209], v[114:117]
	v_mfma_f32_16x16x32_bf16 v[38:41], v[170:173], v[186:189], v[38:41]
	v_mfma_f32_16x16x32_bf16 v[34:37], v[178:181], v[186:189], v[34:37]
	v_mfma_f32_16x16x32_bf16 v[66:69], v[170:173], v[194:197], v[66:69]
	v_mfma_f32_16x16x32_bf16 v[46:49], v[178:181], v[194:197], v[46:49]
	v_mfma_f32_16x16x32_bf16 v[78:81], v[170:173], v[202:205], v[78:81]
	v_mfma_f32_16x16x32_bf16 v[62:65], v[178:181], v[202:205], v[62:65]
	v_mfma_f32_16x16x32_bf16 v[118:121], v[170:173], v[210:213], v[118:121]
	v_mfma_f32_16x16x32_bf16 v[114:117], v[178:181], v[210:213], v[114:117]
	s_setprio 0
	s_barrier
; #define PG8_STAGE(bufoff, gbase, voff) do { _Pragma("unroll") for (int _i = 0; _i < 2; ++_i) \
;         __builtin_amdgcn_global_load_lds((const unsigned*)((const char*)(gbase) + (voff)[_i]), (LAS unsigned*)(lds + (bufoff) + ldsw + _i * 8192), 16, 0, 0); } while (0)
; #define PG8_LDA(dst, b, h) do { _Pragma("unroll") for (int m = 0; m < 4; ++m) _Pragma("unroll") for (int k = 0; k < 2; ++k) dst[m][k] = *(const LAS bf16x8*)(lds + PG8_SA(b, h) + aoff + m * 2048 + k * 1024); } while (0)
; #define PG8_LDB(dst, b, h) do { _Pragma("unroll") for (int n = 0; n < 2; ++n) _Pragma("unroll") for (int k = 0; k < 2; ++k) dst[n][k] = *(const LAS bf16x8*)(lds + PG8_SB(b, h) + boff + n * 2048 + k * 1024); } while (0)
; #define PG8_MMA(ai, bj, At, Bt) do { __builtin_amdgcn_s_setprio(1); _Pragma("unroll") for (int m = 0; m < 4; ++m) _Pragma("unroll") for (int n = 0; n < 2; ++n) _Pragma("unroll") for (int k = 0; k < 2; ++k) \
;         acc[ai][bj][m][n] = __builtin_amdgcn_mfma_f32_16x16x32_bf16(Bt[n][k], At[m][k], acc[ai][bj][m][n], 0, 0, 0); __builtin_amdgcn_s_setprio(0); } while (0)
; #define PG8_WAIT_V(n) asm volatile("s_waitcnt vmcnt(" #n ")" ::: "memory")
; #define PG8_WAIT_L(n) asm volatile("s_waitcnt lgkmcnt(" #n ")" ::: "memory")
; #define PG8_BAR __builtin_amdgcn_s_barrier()
; #define PG8_SCHED __builtin_amdgcn_sched_barrier(0)
; template <class Epi, class Sched, bool ALIGN_EPI, class Hook = NoHook>
; __device__ __forceinline__ void gemm_phase(LAS unsigned char* lds, const Gemm g, const Sched& S, const Epi& E, const Hook& H = Hook()) {
;     ...
;             PG8_LDB(B0, 1, 0); PG8_LDB(B1, 1, 1); PG8_SCHED; PG8_LDA(At, 1, 0); PG8_STAGE(PG8_SA(0, 1), a2 + hA, voffA);
;             PG8_WAIT_V(8); PG8_WAIT_L(0); PG8_BAR; PG8_MMA(0, 0, At, B0); PG8_MMA(0, 1, At, B1); PG8_BAR; PG8_SCHED;
;             PG8_LDA(At, 1, 1); PG8_STAGE(PG8_SB(1, 0), b3, voffB); PG8_STAGE(PG8_SB(1, 1), b3 + hB, voffB); PG8_STAGE(PG8_SA(1, 0), a3, voffA);
;             PG8_WAIT_V(8); PG8_WAIT_L(0); PG8_BAR; PG8_MMA(1, 0, At, B0); PG8_MMA(1, 1, At, B1); PG8_BAR; PG8_SCHED;
;         }
;         if constexpr (Hook::ON) H.after(te, acc, cur, wr, wc, fr, fq);
;         }
;         if constexpr (ALIGN_EPI) { if (wr == 0) PG8_BAR; }
	s_add_u32 s20, s20, 0x2b0000
	s_addc_u32 s21, s21, 0
	s_mov_b32 m0, s28
	s_nop 0
	global_load_lds_dwordx4 v130, s[20:21]
	ds_read_b128 v[146:149], v144
	ds_read_b128 v[150:153], v144 offset:1024
	ds_read_b128 v[154:157], v144 offset:2048
	ds_read_b128 v[158:161], v144 offset:3072
	ds_read_b128 v[164:167], v145
	ds_read_b128 v[170:173], v145 offset:1024
	ds_read_b128 v[174:177], v145 offset:2048
	ds_read_b128 v[178:181], v145 offset:3072
	s_mov_b32 m0, s38
	s_nop 0
	global_load_lds_dwordx4 v134, s[20:21]
	ds_read_b128 v[182:185], v143 offset:32768
	ds_read_b128 v[186:189], v143 offset:33792
	ds_read_b128 v[190:193], v143 offset:34816
	ds_read_b128 v[194:197], v143 offset:35840
	ds_read_b128 v[198:201], v143 offset:36864
	ds_read_b128 v[202:205], v143 offset:37888
	ds_read_b128 v[206:209], v143 offset:38912
	ds_read_b128 v[210:213], v143 offset:39936
	s_waitcnt vmcnt(8)
	s_waitcnt lgkmcnt(0)
	s_barrier
	s_setprio 1
	s_waitcnt lgkmcnt(0)
	v_mfma_f32_16x16x32_bf16 v[82:85], v[146:149], v[182:185], v[82:85]
	v_mfma_f32_16x16x32_bf16 v[54:57], v[154:157], v[182:185], v[54:57]
	v_mfma_f32_16x16x32_bf16 v[58:61], v[146:149], v[190:193], v[58:61]
	v_mfma_f32_16x16x32_bf16 v[42:45], v[154:157], v[190:193], v[42:45]
	v_mfma_f32_16x16x32_bf16 v[70:73], v[146:149], v[198:201], v[70:73]
	v_mfma_f32_16x16x32_bf16 v[50:53], v[154:157], v[198:201], v[50:53]
	v_mfma_f32_16x16x32_bf16 v[86:89], v[146:149], v[206:209], v[86:89]
	v_mfma_f32_16x16x32_bf16 v[74:77], v[154:157], v[206:209], v[74:77]
	v_mfma_f32_16x16x32_bf16 v[82:85], v[150:153], v[186:189], v[82:85]
	v_mfma_f32_16x16x32_bf16 v[54:57], v[158:161], v[186:189], v[54:57]
	v_mfma_f32_16x16x32_bf16 v[58:61], v[150:153], v[194:197], v[58:61]
	v_mfma_f32_16x16x32_bf16 v[42:45], v[158:161], v[194:197], v[42:45]
	v_mfma_f32_16x16x32_bf16 v[70:73], v[150:153], v[202:205], v[70:73]
	v_mfma_f32_16x16x32_bf16 v[50:53], v[158:161], v[202:205], v[50:53]
	v_mfma_f32_16x16x32_bf16 v[86:89], v[150:153], v[210:213], v[86:89]
	v_mfma_f32_16x16x32_bf16 v[74:77], v[158:161], v[210:213], v[74:77]
	s_setprio 0
	s_setprio 1
	v_mfma_f32_16x16x32_bf16 v[14:17], v[164:167], v[182:185], v[14:17]
	v_mfma_f32_16x16x32_bf16 v[2:5], v[174:177], v[182:185], v[2:5]
	v_mfma_f32_16x16x32_bf16 v[18:21], v[164:167], v[190:193], v[18:21]
	v_mfma_f32_16x16x32_bf16 v[6:9], v[174:177], v[190:193], v[6:9]
	v_mfma_f32_16x16x32_bf16 v[22:25], v[164:167], v[198:201], v[22:25]
	v_mfma_f32_16x16x32_bf16 v[10:13], v[174:177], v[198:201], v[10:13]
	v_mfma_f32_16x16x32_bf16 v[30:33], v[164:167], v[206:209], v[30:33]
	v_mfma_f32_16x16x32_bf16 v[26:29], v[174:177], v[206:209], v[26:29]
	v_mfma_f32_16x16x32_bf16 v[14:17], v[170:173], v[186:189], v[14:17]
	v_mfma_f32_16x16x32_bf16 v[2:5], v[178:181], v[186:189], v[2:5]
	v_mfma_f32_16x16x32_bf16 v[18:21], v[170:173], v[194:197], v[18:21]
	v_mfma_f32_16x16x32_bf16 v[6:9], v[178:181], v[194:197], v[6:9]
	v_mfma_f32_16x16x32_bf16 v[22:25], v[170:173], v[202:205], v[22:25]
	v_mfma_f32_16x16x32_bf16 v[10:13], v[178:181], v[202:205], v[10:13]
	v_mfma_f32_16x16x32_bf16 v[30:33], v[170:173], v[210:213], v[30:33]
	v_mfma_f32_16x16x32_bf16 v[26:29], v[178:181], v[210:213], v[26:29]
	s_setprio 0
	s_barrier
	s_mov_b32 m0, s48
	s_add_u32 s54, s14, s2
	s_addc_u32 s55, s15, s3
	s_add_u32 s14, s14, 0x2b0080
	global_load_lds_dwordx4 v132, s[54:55]
	ds_read_b128 v[182:185], v143 offset:49152
	ds_read_b128 v[186:189], v143 offset:50176
	s_mov_b32 m0, s49
	s_addc_u32 s15, s15, 0
	global_load_lds_dwordx4 v136, s[54:55]
	ds_read_b128 v[190:193], v143 offset:51200
	ds_read_b128 v[194:197], v143 offset:52224
	s_mov_b32 m0, s50
	s_nop 0
	global_load_lds_dwordx4 v132, s[14:15]
	ds_read_b128 v[198:201], v143 offset:53248
	s_mov_b32 m0, s51
	s_nop 0
	global_load_lds_dwordx4 v136, s[14:15]
	ds_read_b128 v[202:205], v143 offset:54272
	s_mov_b32 m0, s39
	s_nop 0
	global_load_lds_dwordx4 v130, s[56:57]
	ds_read_b128 v[206:209], v143 offset:55296
	s_mov_b32 m0, s40
	s_nop 0
	global_load_lds_dwordx4 v134, s[56:57]
	ds_read_b128 v[210:213], v143 offset:56320
	s_waitcnt vmcnt(8)
	s_waitcnt lgkmcnt(0)
	s_barrier
	s_setprio 1
	s_waitcnt lgkmcnt(0)
	v_mfma_f32_16x16x32_bf16 v[94:97], v[146:149], v[182:185], v[94:97]
	v_mfma_f32_16x16x32_bf16 v[90:93], v[154:157], v[182:185], v[90:93]
	v_mfma_f32_16x16x32_bf16 v[106:109], v[146:149], v[190:193], v[106:109]
	v_mfma_f32_16x16x32_bf16 v[98:101], v[154:157], v[190:193], v[98:101]
	v_mfma_f32_16x16x32_bf16 v[110:113], v[146:149], v[198:201], v[110:113]
	v_mfma_f32_16x16x32_bf16 v[102:105], v[154:157], v[198:201], v[102:105]
	v_mfma_f32_16x16x32_bf16 v[126:129], v[146:149], v[206:209], v[126:129]
	v_mfma_f32_16x16x32_bf16 v[122:125], v[154:157], v[206:209], v[122:125]
	v_mfma_f32_16x16x32_bf16 v[94:97], v[150:153], v[186:189], v[94:97]
	v_mfma_f32_16x16x32_bf16 v[90:93], v[158:161], v[186:189], v[90:93]
	v_mfma_f32_16x16x32_bf16 v[106:109], v[150:153], v[194:197], v[106:109]
	v_mfma_f32_16x16x32_bf16 v[98:101], v[158:161], v[194:197], v[98:101]
	v_mfma_f32_16x16x32_bf16 v[110:113], v[150:153], v[202:205], v[110:113]
	v_mfma_f32_16x16x32_bf16 v[102:105], v[158:161], v[202:205], v[102:105]
	v_mfma_f32_16x16x32_bf16 v[126:129], v[150:153], v[210:213], v[126:129]
	v_mfma_f32_16x16x32_bf16 v[122:125], v[158:161], v[210:213], v[122:125]
	s_setprio 0
	s_setprio 1
	v_mfma_f32_16x16x32_bf16 v[38:41], v[164:167], v[182:185], v[38:41]
	v_mfma_f32_16x16x32_bf16 v[34:37], v[174:177], v[182:185], v[34:37]
	v_mfma_f32_16x16x32_bf16 v[66:69], v[164:167], v[190:193], v[66:69]
	v_mfma_f32_16x16x32_bf16 v[46:49], v[174:177], v[190:193], v[46:49]
	v_mfma_f32_16x16x32_bf16 v[78:81], v[164:167], v[198:201], v[78:81]
	v_mfma_f32_16x16x32_bf16 v[62:65], v[174:177], v[198:201], v[62:65]
	v_mfma_f32_16x16x32_bf16 v[118:121], v[164:167], v[206:209], v[118:121]
	v_mfma_f32_16x16x32_bf16 v[114:117], v[174:177], v[206:209], v[114:117]
	v_mfma_f32_16x16x32_bf16 v[38:41], v[170:173], v[186:189], v[38:41]
	v_mfma_f32_16x16x32_bf16 v[34:37], v[178:181], v[186:189], v[34:37]
	v_mfma_f32_16x16x32_bf16 v[66:69], v[170:173], v[194:197], v[66:69]
	v_mfma_f32_16x16x32_bf16 v[46:49], v[178:181], v[194:197], v[46:49]
	v_mfma_f32_16x16x32_bf16 v[78:81], v[170:173], v[202:205], v[78:81]
	v_mfma_f32_16x16x32_bf16 v[62:65], v[178:181], v[202:205], v[62:65]
	v_mfma_f32_16x16x32_bf16 v[118:121], v[170:173], v[210:213], v[118:121]
	v_mfma_f32_16x16x32_bf16 v[114:117], v[178:181], v[210:213], v[114:117]
	s_setprio 0
	s_barrier
	s_add_i32 s41, s41, 2
	s_add_u32 s4, s4, 0x100
	s_addc_u32 s5, s5, 0
	s_cmpk_gt_u32 s41, 0xa9
	s_cbranch_scc0 .LBB0_1360
	s_cmpk_lt_u32 s26, 0x100
	s_cbranch_scc0 .LBB0_1363
	s_barrier

; #define PG8_STAGE(bufoff, gbase, voff) do { _Pragma("unroll") for (int _i = 0; _i < 2; ++_i) \
;         __builtin_amdgcn_global_load_lds((const unsigned*)((const char*)(gbase) + (voff)[_i]), (LAS unsigned*)(lds + (bufoff) + ldsw + _i * 8192), 16, 0, 0); } while (0)
; #define PG8_LDA(dst, b, h) do { _Pragma("unroll") for (int m = 0; m < 4; ++m) _Pragma("unroll") for (int k = 0; k < 2; ++k) dst[m][k] = *(const LAS bf16x8*)(lds + PG8_SA(b, h) + aoff + m * 2048 + k * 1024); } while (0)
; #define PG8_LDB(dst, b, h) do { _Pragma("unroll") for (int n = 0; n < 2; ++n) _Pragma("unroll") for (int k = 0; k < 2; ++k) dst[n][k] = *(const LAS bf16x8*)(lds + PG8_SB(b, h) + boff + n * 2048 + k * 1024); } while (0)
; #define PG8_MMA(ai, bj, At, Bt) do { __builtin_amdgcn_s_setprio(1); _Pragma("unroll") for (int m = 0; m < 4; ++m) _Pragma("unroll") for (int n = 0; n < 2; ++n) _Pragma("unroll") for (int k = 0; k < 2; ++k) \
;         acc[ai][bj][m][n] = __builtin_amdgcn_mfma_f32_16x16x32_bf16(Bt[n][k], At[m][k], acc[ai][bj][m][n], 0, 0, 0); __builtin_amdgcn_s_setprio(0); } while (0)
; #define PG8_WAIT_V(n) asm volatile("s_waitcnt vmcnt(" #n ")" ::: "memory")
; #define PG8_WAIT_L(n) asm volatile("s_waitcnt lgkmcnt(" #n ")" ::: "memory")
; #define PG8_BAR __builtin_amdgcn_s_barrier()
; template <class Epi, class Sched, bool ALIGN_EPI, class Hook = NoHook>
; __device__ __forceinline__ void gemm_phase(LAS unsigned char* lds, const Gemm g, const Sched& S, const Epi& E, const Hook& H = Hook()) {
;     ...
;             const bool last = (t == nt - 2);
;             const char* a1 = cA + (size_t)(t + 1) * kstep;
;             const char* a2 = last ? nA : cA + (size_t)(t + 2) * kstep; const char* b2 = last ? nB : cB + (size_t)(t + 2) * kstep;
;             const char* a3 = a2 + kstep; const char* b3 = b2 + kstep;
;             if (last && has_next) S.a_ready(nxt);
;             PG8_LDB(B0, 0, 0); PG8_LDB(B1, 0, 1); PG8_SCHED; PG8_LDA(At, 0, 0); PG8_STAGE(PG8_SA(1, 1), a1 + hA, voffA);
;             PG8_WAIT_V(8); PG8_WAIT_L(0); PG8_BAR; PG8_MMA(0, 0, At, B0); PG8_MMA(0, 1, At, B1); PG8_BAR; PG8_SCHED;
;             PG8_LDA(At, 0, 1); PG8_STAGE(PG8_SB(0, 0), b2, voffB); PG8_STAGE(PG8_SB(0, 1), b2 + hB, voffB); PG8_STAGE(PG8_SA(0, 0), a2, voffA);
;             PG8_WAIT_V(8); PG8_WAIT_L(0); PG8_BAR; PG8_MMA(1, 0, At, B0); PG8_MMA(1, 1, At, B1); PG8_BAR; PG8_SCHED;
.LBB0_1406:
	s_add_u32 s10, s4, 0xbb050080
	s_addc_u32 s11, s5, -1
	s_cmpk_lg_i32 s18, 0xa8
	s_cselect_b32 s10, s10, 0
	s_cselect_b32 s11, s11, 0
	s_add_u32 s16, s0, s10
	s_addc_u32 s17, s1, s11
	s_add_u32 s10, s12, s10
	s_addc_u32 s11, s13, s11
	s_mov_b32 m0, s19
	ds_read_b128 v[146:149], v140
	ds_read_b128 v[150:153], v140 offset:1024
	ds_read_b128 v[154:157], v140 offset:2048
	ds_read_b128 v[158:161], v140 offset:3072
	ds_read_b128 v[170:173], v141
	ds_read_b128 v[174:177], v141 offset:1024
	ds_read_b128 v[178:181], v141 offset:2048
	ds_read_b128 v[182:185], v141 offset:3072
	v_lshl_add_u64 v[218:219], v[136:137], 0, s[4:5]
	global_load_lds_dwordx4 v[218:219], off
	ds_read_b128 v[186:189], v142
	ds_read_b128 v[190:193], v142 offset:1024
	ds_read_b128 v[194:197], v142 offset:2048
	ds_read_b128 v[198:201], v142 offset:3072
	ds_read_b128 v[202:205], v142 offset:4096
	ds_read_b128 v[206:209], v142 offset:5120
	ds_read_b128 v[210:213], v142 offset:6144
	ds_read_b128 v[214:217], v142 offset:7168
	v_lshl_add_u64 v[218:219], v[138:139], 0, s[4:5]
	s_mov_b32 m0, s31
	s_nop 0
	global_load_lds_dwordx4 v[218:219], off
	s_waitcnt vmcnt(8)
	s_waitcnt lgkmcnt(0)
	s_barrier
	s_setprio 1
	s_waitcnt lgkmcnt(0)
	v_mfma_f32_16x16x32_bf16 v[82:85], v[146:149], v[186:189], v[82:85]
	v_mfma_f32_16x16x32_bf16 v[54:57], v[154:157], v[186:189], v[54:57]
	v_mfma_f32_16x16x32_bf16 v[58:61], v[146:149], v[194:197], v[58:61]
	v_mfma_f32_16x16x32_bf16 v[42:45], v[154:157], v[194:197], v[42:45]
	v_mfma_f32_16x16x32_bf16 v[70:73], v[146:149], v[202:205], v[70:73]
	v_mfma_f32_16x16x32_bf16 v[50:53], v[154:157], v[202:205], v[50:53]
	v_mfma_f32_16x16x32_bf16 v[86:89], v[146:149], v[210:213], v[86:89]
	v_mfma_f32_16x16x32_bf16 v[74:77], v[154:157], v[210:213], v[74:77]
	v_mfma_f32_16x16x32_bf16 v[82:85], v[150:153], v[190:193], v[82:85]
	v_mfma_f32_16x16x32_bf16 v[54:57], v[158:161], v[190:193], v[54:57]
	v_mfma_f32_16x16x32_bf16 v[58:61], v[150:153], v[198:201], v[58:61]
	v_mfma_f32_16x16x32_bf16 v[42:45], v[158:161], v[198:201], v[42:45]
	v_mfma_f32_16x16x32_bf16 v[70:73], v[150:153], v[206:209], v[70:73]
	v_mfma_f32_16x16x32_bf16 v[50:53], v[158:161], v[206:209], v[50:53]
	v_mfma_f32_16x16x32_bf16 v[86:89], v[150:153], v[214:217], v[86:89]
	v_mfma_f32_16x16x32_bf16 v[74:77], v[158:161], v[214:217], v[74:77]
	s_setprio 0
	s_setprio 1
	v_mfma_f32_16x16x32_bf16 v[14:17], v[170:173], v[186:189], v[14:17]
	v_mfma_f32_16x16x32_bf16 v[2:5], v[178:181], v[186:189], v[2:5]
	v_mfma_f32_16x16x32_bf16 v[18:21], v[170:173], v[194:197], v[18:21]
	v_mfma_f32_16x16x32_bf16 v[6:9], v[178:181], v[194:197], v[6:9]
	v_mfma_f32_16x16x32_bf16 v[22:25], v[170:173], v[202:205], v[22:25]
	v_mfma_f32_16x16x32_bf16 v[10:13], v[178:181], v[202:205], v[10:13]
	v_mfma_f32_16x16x32_bf16 v[30:33], v[170:173], v[210:213], v[30:33]
	v_mfma_f32_16x16x32_bf16 v[26:29], v[178:181], v[210:213], v[26:29]
	v_mfma_f32_16x16x32_bf16 v[14:17], v[174:177], v[190:193], v[14:17]
	v_mfma_f32_16x16x32_bf16 v[2:5], v[182:185], v[190:193], v[2:5]
	v_mfma_f32_16x16x32_bf16 v[18:21], v[174:177], v[198:201], v[18:21]
	v_mfma_f32_16x16x32_bf16 v[6:9], v[182:185], v[198:201], v[6:9]
	v_mfma_f32_16x16x32_bf16 v[22:25], v[174:177], v[206:209], v[22:25]
	v_mfma_f32_16x16x32_bf16 v[10:13], v[182:185], v[206:209], v[10:13]
	v_mfma_f32_16x16x32_bf16 v[30:33], v[174:177], v[214:217], v[30:33]
	v_mfma_f32_16x16x32_bf16 v[26:29], v[182:185], v[214:217], v[26:29]
	s_setprio 0
	s_barrier
	s_mov_b32 m0, s33
	s_add_u32 s46, s10, 0x2b0000
	global_load_lds_dwordx4 v162, s[10:11]
	ds_read_b128 v[186:189], v142 offset:16384
	ds_read_b128 v[190:193], v142 offset:17408
	s_mov_b32 m0, s34
	s_addc_u32 s47, s11, 0
	global_load_lds_dwordx4 v134, s[10:11]
	ds_read_b128 v[194:197], v142 offset:18432
	ds_read_b128 v[198:201], v142 offset:19456
	s_mov_b32 m0, s35
	s_nop 0
	global_load_lds_dwordx4 v162, s[46:47]
	ds_read_b128 v[202:205], v142 offset:20480
	s_mov_b32 m0, s43
	s_nop 0
	global_load_lds_dwordx4 v134, s[46:47]
	ds_read_b128 v[206:209], v142 offset:21504
	s_add_u32 s54, s16, s2
	s_addc_u32 s55, s17, s3
	s_mov_b32 m0, s27
	s_nop 0
	global_load_lds_dwordx4 v130, s[16:17]
	ds_read_b128 v[210:213], v142 offset:22528
	s_mov_b32 m0, s28
	s_nop 0
	global_load_lds_dwordx4 v132, s[16:17]
	ds_read_b128 v[214:217], v142 offset:23552
	s_waitcnt vmcnt(8)
	s_waitcnt lgkmcnt(0)
	s_barrier
	s_setprio 1
	s_waitcnt lgkmcnt(0)
	v_mfma_f32_16x16x32_bf16 v[94:97], v[146:149], v[186:189], v[94:97]
	v_mfma_f32_16x16x32_bf16 v[90:93], v[154:157], v[186:189], v[90:93]
	v_mfma_f32_16x16x32_bf16 v[118:121], v[146:149], v[194:197], v[118:121]
	v_mfma_f32_16x16x32_bf16 v[98:101], v[154:157], v[194:197], v[98:101]
	v_mfma_f32_16x16x32_bf16 v[126:129], v[146:149], v[202:205], v[126:129]
	v_mfma_f32_16x16x32_bf16 v[110:113], v[154:157], v[202:205], v[110:113]
	v_mfma_f32_16x16x32_bf16 v[122:125], v[146:149], v[210:213], v[122:125]
	v_mfma_f32_16x16x32_bf16 v[114:117], v[154:157], v[210:213], v[114:117]
	v_mfma_f32_16x16x32_bf16 v[94:97], v[150:153], v[190:193], v[94:97]
	v_mfma_f32_16x16x32_bf16 v[90:93], v[158:161], v[190:193], v[90:93]
	v_mfma_f32_16x16x32_bf16 v[118:121], v[150:153], v[198:201], v[118:121]
	v_mfma_f32_16x16x32_bf16 v[98:101], v[158:161], v[198:201], v[98:101]
	v_mfma_f32_16x16x32_bf16 v[126:129], v[150:153], v[206:209], v[126:129]
	v_mfma_f32_16x16x32_bf16 v[110:113], v[158:161], v[206:209], v[110:113]
	v_mfma_f32_16x16x32_bf16 v[122:125], v[150:153], v[214:217], v[122:125]
	v_mfma_f32_16x16x32_bf16 v[114:117], v[158:161], v[214:217], v[114:117]
	s_setprio 0
	s_setprio 1
	v_mfma_f32_16x16x32_bf16 v[38:41], v[170:173], v[186:189], v[38:41]
	v_mfma_f32_16x16x32_bf16 v[34:37], v[178:181], v[186:189], v[34:37]
	v_mfma_f32_16x16x32_bf16 v[66:69], v[170:173], v[194:197], v[66:69]
	v_mfma_f32_16x16x32_bf16 v[46:49], v[178:181], v[194:197], v[46:49]
	v_mfma_f32_16x16x32_bf16 v[78:81], v[170:173], v[202:205], v[78:81]
	v_mfma_f32_16x16x32_bf16 v[62:65], v[178:181], v[202:205], v[62:65]
	v_mfma_f32_16x16x32_bf16 v[106:109], v[170:173], v[210:213], v[106:109]
	v_mfma_f32_16x16x32_bf16 v[102:105], v[178:181], v[210:213], v[102:105]
	v_mfma_f32_16x16x32_bf16 v[38:41], v[174:177], v[190:193], v[38:41]
	v_mfma_f32_16x16x32_bf16 v[34:37], v[182:185], v[190:193], v[34:37]
	v_mfma_f32_16x16x32_bf16 v[66:69], v[174:177], v[198:201], v[66:69]
	v_mfma_f32_16x16x32_bf16 v[46:49], v[182:185], v[198:201], v[46:49]
	v_mfma_f32_16x16x32_bf16 v[78:81], v[174:177], v[206:209], v[78:81]
	v_mfma_f32_16x16x32_bf16 v[62:65], v[182:185], v[206:209], v[62:65]
	v_mfma_f32_16x16x32_bf16 v[106:109], v[174:177], v[214:217], v[106:109]
	v_mfma_f32_16x16x32_bf16 v[102:105], v[182:185], v[214:217], v[102:105]
	s_setprio 0
	s_barrier
; #define PG8_STAGE(bufoff, gbase, voff) do { _Pragma("unroll") for (int _i = 0; _i < 2; ++_i) \
;         __builtin_amdgcn_global_load_lds((const unsigned*)((const char*)(gbase) + (voff)[_i]), (LAS unsigned*)(lds + (bufoff) + ldsw + _i * 8192), 16, 0, 0); } while (0)
; #define PG8_LDA(dst, b, h) do { _Pragma("unroll") for (int m = 0; m < 4; ++m) _Pragma("unroll") for (int k = 0; k < 2; ++k) dst[m][k] = *(const LAS bf16x8*)(lds + PG8_SA(b, h) + aoff + m * 2048 + k * 1024); } while (0)
; #define PG8_LDB(dst, b, h) do { _Pragma("unroll") for (int n = 0; n < 2; ++n) _Pragma("unroll") for (int k = 0; k < 2; ++k) dst[n][k] = *(const LAS bf16x8*)(lds + PG8_SB(b, h) + boff + n * 2048 + k * 1024); } while (0)
; #define PG8_MMA(ai, bj, At, Bt) do { __builtin_amdgcn_s_setprio(1); _Pragma("unroll") for (int m = 0; m < 4; ++m) _Pragma("unroll") for (int n = 0; n < 2; ++n) _Pragma("unroll") for (int k = 0; k < 2; ++k) \
;         acc[ai][bj][m][n] = __builtin_amdgcn_mfma_f32_16x16x32_bf16(Bt[n][k], At[m][k], acc[ai][bj][m][n], 0, 0, 0); __builtin_amdgcn_s_setprio(0); } while (0)
; #define PG8_WAIT_V(n) asm volatile("s_waitcnt vmcnt(" #n ")" ::: "memory")
; #define PG8_WAIT_L(n) asm volatile("s_waitcnt lgkmcnt(" #n ")" ::: "memory")
; #define PG8_BAR __builtin_amdgcn_s_barrier()
; #define PG8_SCHED __builtin_amdgcn_sched_barrier(0)
; template <class Epi, class Sched, bool ALIGN_EPI, class Hook = NoHook>
; __device__ __forceinline__ void gemm_phase(LAS unsigned char* lds, const Gemm g, const Sched& S, const Epi& E, const Hook& H = Hook()) {
;     ...
;             PG8_LDB(B0, 1, 0); PG8_LDB(B1, 1, 1); PG8_SCHED; PG8_LDA(At, 1, 0); PG8_STAGE(PG8_SA(0, 1), a2 + hA, voffA);
;             PG8_WAIT_V(8); PG8_WAIT_L(0); PG8_BAR; PG8_MMA(0, 0, At, B0); PG8_MMA(0, 1, At, B1); PG8_BAR; PG8_SCHED;
;             PG8_LDA(At, 1, 1); PG8_STAGE(PG8_SB(1, 0), b3, voffB); PG8_STAGE(PG8_SB(1, 1), b3 + hB, voffB); PG8_STAGE(PG8_SA(1, 0), a3, voffA);
;             PG8_WAIT_V(8); PG8_WAIT_L(0); PG8_BAR; PG8_MMA(1, 0, At, B0); PG8_MMA(1, 1, At, B1); PG8_BAR; PG8_SCHED;
;         }
;         if constexpr (Hook::ON) H.after(te, acc, cur, wr, wc, fr, fq);
;         }
;         if constexpr (ALIGN_EPI) { if (wr == 0) PG8_BAR; }
	s_add_u32 s16, s16, 0x2b0000
	s_addc_u32 s17, s17, 0
	s_mov_b32 m0, s29
	s_nop 0
	global_load_lds_dwordx4 v130, s[16:17]
	ds_read_b128 v[146:149], v143
	ds_read_b128 v[150:153], v143 offset:1024
	ds_read_b128 v[154:157], v143 offset:2048
	ds_read_b128 v[158:161], v143 offset:3072
	ds_read_b128 v[170:173], v144
	ds_read_b128 v[174:177], v144 offset:1024
	ds_read_b128 v[178:181], v144 offset:2048
	ds_read_b128 v[182:185], v144 offset:3072
	s_mov_b32 m0, s39
	s_nop 0
	global_load_lds_dwordx4 v132, s[16:17]
	ds_read_b128 v[186:189], v142 offset:32768
	ds_read_b128 v[190:193], v142 offset:33792
	ds_read_b128 v[194:197], v142 offset:34816
	ds_read_b128 v[198:201], v142 offset:35840
	ds_read_b128 v[202:205], v142 offset:36864
	ds_read_b128 v[206:209], v142 offset:37888
	ds_read_b128 v[210:213], v142 offset:38912
	ds_read_b128 v[214:217], v142 offset:39936
	s_waitcnt vmcnt(8)
	s_waitcnt lgkmcnt(0)
	s_barrier
	s_setprio 1
	s_waitcnt lgkmcnt(0)
	v_mfma_f32_16x16x32_bf16 v[82:85], v[146:149], v[186:189], v[82:85]
	v_mfma_f32_16x16x32_bf16 v[54:57], v[154:157], v[186:189], v[54:57]
	v_mfma_f32_16x16x32_bf16 v[58:61], v[146:149], v[194:197], v[58:61]
	v_mfma_f32_16x16x32_bf16 v[42:45], v[154:157], v[194:197], v[42:45]
	v_mfma_f32_16x16x32_bf16 v[70:73], v[146:149], v[202:205], v[70:73]
	v_mfma_f32_16x16x32_bf16 v[50:53], v[154:157], v[202:205], v[50:53]
	v_mfma_f32_16x16x32_bf16 v[86:89], v[146:149], v[210:213], v[86:89]
	v_mfma_f32_16x16x32_bf16 v[74:77], v[154:157], v[210:213], v[74:77]
	v_mfma_f32_16x16x32_bf16 v[82:85], v[150:153], v[190:193], v[82:85]
	v_mfma_f32_16x16x32_bf16 v[54:57], v[158:161], v[190:193], v[54:57]
	v_mfma_f32_16x16x32_bf16 v[58:61], v[150:153], v[198:201], v[58:61]
	v_mfma_f32_16x16x32_bf16 v[42:45], v[158:161], v[198:201], v[42:45]
	v_mfma_f32_16x16x32_bf16 v[70:73], v[150:153], v[206:209], v[70:73]
	v_mfma_f32_16x16x32_bf16 v[50:53], v[158:161], v[206:209], v[50:53]
	v_mfma_f32_16x16x32_bf16 v[86:89], v[150:153], v[214:217], v[86:89]
	v_mfma_f32_16x16x32_bf16 v[74:77], v[158:161], v[214:217], v[74:77]
	s_setprio 0
	s_setprio 1
	v_mfma_f32_16x16x32_bf16 v[14:17], v[170:173], v[186:189], v[14:17]
	v_mfma_f32_16x16x32_bf16 v[2:5], v[178:181], v[186:189], v[2:5]
	v_mfma_f32_16x16x32_bf16 v[18:21], v[170:173], v[194:197], v[18:21]
	v_mfma_f32_16x16x32_bf16 v[6:9], v[178:181], v[194:197], v[6:9]
	v_mfma_f32_16x16x32_bf16 v[22:25], v[170:173], v[202:205], v[22:25]
	v_mfma_f32_16x16x32_bf16 v[10:13], v[178:181], v[202:205], v[10:13]
	v_mfma_f32_16x16x32_bf16 v[30:33], v[170:173], v[210:213], v[30:33]
	v_mfma_f32_16x16x32_bf16 v[26:29], v[178:181], v[210:213], v[26:29]
	v_mfma_f32_16x16x32_bf16 v[14:17], v[174:177], v[190:193], v[14:17]
	v_mfma_f32_16x16x32_bf16 v[2:5], v[182:185], v[190:193], v[2:5]
	v_mfma_f32_16x16x32_bf16 v[18:21], v[174:177], v[198:201], v[18:21]
	v_mfma_f32_16x16x32_bf16 v[6:9], v[182:185], v[198:201], v[6:9]
	v_mfma_f32_16x16x32_bf16 v[22:25], v[174:177], v[206:209], v[22:25]
	v_mfma_f32_16x16x32_bf16 v[10:13], v[182:185], v[206:209], v[10:13]
	v_mfma_f32_16x16x32_bf16 v[30:33], v[174:177], v[214:217], v[30:33]
	v_mfma_f32_16x16x32_bf16 v[26:29], v[182:185], v[214:217], v[26:29]
	s_setprio 0
	s_barrier
	s_mov_b32 m0, s36
	s_add_u32 s52, s10, s2
	s_addc_u32 s53, s11, s3
	s_add_u32 s10, s10, 0x2b0080
	global_load_lds_dwordx4 v162, s[52:53]
	ds_read_b128 v[186:189], v142 offset:49152
	ds_read_b128 v[190:193], v142 offset:50176
	s_mov_b32 m0, s44
	s_addc_u32 s11, s11, 0
	global_load_lds_dwordx4 v134, s[52:53]
	ds_read_b128 v[194:197], v142 offset:51200
	ds_read_b128 v[198:201], v142 offset:52224
	s_mov_b32 m0, s37
	s_nop 0
	global_load_lds_dwordx4 v162, s[10:11]
	ds_read_b128 v[202:205], v142 offset:53248
	s_mov_b32 m0, s45
	s_nop 0
	global_load_lds_dwordx4 v134, s[10:11]
	ds_read_b128 v[206:209], v142 offset:54272
	s_mov_b32 m0, s41
	s_nop 0
	global_load_lds_dwordx4 v130, s[54:55]
	ds_read_b128 v[210:213], v142 offset:55296
	s_mov_b32 m0, s42
	s_nop 0
	global_load_lds_dwordx4 v132, s[54:55]
	ds_read_b128 v[214:217], v142 offset:56320
	s_waitcnt vmcnt(8)
	s_waitcnt lgkmcnt(0)
	s_barrier
	s_setprio 1
	s_waitcnt lgkmcnt(0)
	v_mfma_f32_16x16x32_bf16 v[94:97], v[146:149], v[186:189], v[94:97]
	v_mfma_f32_16x16x32_bf16 v[90:93], v[154:157], v[186:189], v[90:93]
	v_mfma_f32_16x16x32_bf16 v[118:121], v[146:149], v[194:197], v[118:121]
	v_mfma_f32_16x16x32_bf16 v[98:101], v[154:157], v[194:197], v[98:101]
	v_mfma_f32_16x16x32_bf16 v[126:129], v[146:149], v[202:205], v[126:129]
	v_mfma_f32_16x16x32_bf16 v[110:113], v[154:157], v[202:205], v[110:113]
	v_mfma_f32_16x16x32_bf16 v[122:125], v[146:149], v[210:213], v[122:125]
	v_mfma_f32_16x16x32_bf16 v[114:117], v[154:157], v[210:213], v[114:117]
	v_mfma_f32_16x16x32_bf16 v[94:97], v[150:153], v[190:193], v[94:97]
	v_mfma_f32_16x16x32_bf16 v[90:93], v[158:161], v[190:193], v[90:93]
	v_mfma_f32_16x16x32_bf16 v[118:121], v[150:153], v[198:201], v[118:121]
	v_mfma_f32_16x16x32_bf16 v[98:101], v[158:161], v[198:201], v[98:101]
	v_mfma_f32_16x16x32_bf16 v[126:129], v[150:153], v[206:209], v[126:129]
	v_mfma_f32_16x16x32_bf16 v[110:113], v[158:161], v[206:209], v[110:113]
	v_mfma_f32_16x16x32_bf16 v[122:125], v[150:153], v[214:217], v[122:125]
	v_mfma_f32_16x16x32_bf16 v[114:117], v[158:161], v[214:217], v[114:117]
	s_setprio 0
	s_setprio 1
	v_mfma_f32_16x16x32_bf16 v[38:41], v[170:173], v[186:189], v[38:41]
	v_mfma_f32_16x16x32_bf16 v[34:37], v[178:181], v[186:189], v[34:37]
	v_mfma_f32_16x16x32_bf16 v[66:69], v[170:173], v[194:197], v[66:69]
	v_mfma_f32_16x16x32_bf16 v[46:49], v[178:181], v[194:197], v[46:49]
	v_mfma_f32_16x16x32_bf16 v[78:81], v[170:173], v[202:205], v[78:81]
	v_mfma_f32_16x16x32_bf16 v[62:65], v[178:181], v[202:205], v[62:65]
	v_mfma_f32_16x16x32_bf16 v[106:109], v[170:173], v[210:213], v[106:109]
	v_mfma_f32_16x16x32_bf16 v[102:105], v[178:181], v[210:213], v[102:105]
	v_mfma_f32_16x16x32_bf16 v[38:41], v[174:177], v[190:193], v[38:41]
	v_mfma_f32_16x16x32_bf16 v[34:37], v[182:185], v[190:193], v[34:37]
	v_mfma_f32_16x16x32_bf16 v[66:69], v[174:177], v[198:201], v[66:69]
	v_mfma_f32_16x16x32_bf16 v[46:49], v[182:185], v[198:201], v[46:49]
	v_mfma_f32_16x16x32_bf16 v[78:81], v[174:177], v[206:209], v[78:81]
	v_mfma_f32_16x16x32_bf16 v[62:65], v[182:185], v[206:209], v[62:65]
	v_mfma_f32_16x16x32_bf16 v[106:109], v[174:177], v[214:217], v[106:109]
	v_mfma_f32_16x16x32_bf16 v[102:105], v[182:185], v[214:217], v[102:105]
	s_setprio 0
	s_barrier
	s_add_i32 s18, s18, 2
	s_add_u32 s4, s4, 0x100
	s_addc_u32 s5, s5, 0
	s_cmpk_gt_u32 s18, 0xa9
	s_cbranch_scc0 .LBB0_1406
	s_cmpk_lt_u32 s22, 0x100
	s_cbranch_scc0 .LBB0_1409
	s_barrier
